# same but barrier before last 3 MFMAs at 21 of 28 sites, next-segment LDS reads interleaved among the 3 tail MFMAs
# baseline (speedup 1.0000x reference)
; #define PG8_STAGE(bufoff, gbase, voff) do { _Pragma("unroll") for (int _i = 0; _i < 2; ++_i) \
;         __builtin_amdgcn_global_load_lds((const unsigned*)((const char*)(gbase) + (voff)[_i]), (LAS unsigned*)(lds + (bufoff) + ldsw + _i * 8192), 16, 0, 0); } while (0)
; #define PG8_LDA(dst, b, h) do { _Pragma("unroll") for (int m = 0; m < 4; ++m) _Pragma("unroll") for (int k = 0; k < 2; ++k) dst[m][k] = *(const LAS bf16x8*)(lds + PG8_SA(b, h) + aoff + m * 2048 + k * 1024); } while (0)
; #define PG8_LDB(dst, b, h) do { _Pragma("unroll") for (int n = 0; n < 2; ++n) _Pragma("unroll") for (int k = 0; k < 2; ++k) dst[n][k] = *(const LAS bf16x8*)(lds + PG8_SB(b, h) + boff + n * 2048 + k * 1024); } while (0)
; #define PG8_MMA(ai, bj, At, Bt) do { __builtin_amdgcn_s_setprio(1); _Pragma("unroll") for (int m = 0; m < 4; ++m) _Pragma("unroll") for (int n = 0; n < 2; ++n) _Pragma("unroll") for (int k = 0; k < 2; ++k) \
;         acc[ai][bj][m][n] = __builtin_amdgcn_mfma_f32_16x16x32_bf16(Bt[n][k], At[m][k], acc[ai][bj][m][n], 0, 0, 0); __builtin_amdgcn_s_setprio(0); } while (0)
; #define PG8_WAIT_V(n) asm volatile("s_waitcnt vmcnt(" #n ")" ::: "memory")
; #define PG8_WAIT_L(n) asm volatile("s_waitcnt lgkmcnt(" #n ")" ::: "memory")
; #define PG8_BAR __builtin_amdgcn_s_barrier()
; #define PG8_SCHED __builtin_amdgcn_sched_barrier(0)
; template <class Epi>
; __device__ __forceinline__ void gemm_phase(LAS unsigned char* lds, const Gemm g, const TileOrder& S, const Epi& E) {
;     ...
;             const bool last = (t == nt - 2);
;             const char* a1 = cA + (size_t)(t + 1) * kstepA;
;             const char* a2 = last ? nA : cA + (size_t)(t + 2) * kstepA; const char* b2 = last ? nB : cB + (size_t)(t + 2) * kstep;
;             const char* a3 = a2 + kstepA; const char* b3 = b2 + kstep;
;             PG8_LDB(B0, 0, 0); PG8_LDB(B1, 0, 1); PG8_SCHED; PG8_LDA(At, 0, 0); PG8_STAGE(PG8_SA(1, 1), a1 + hstepA, voffA);
;             PG8_WAIT_V(8); PG8_WAIT_L(0); PG8_BAR; PG8_MMA(0, 0, At, B0); PG8_MMA(0, 1, At, B1); PG8_BAR; PG8_SCHED;
;             PG8_LDA(At, 0, 1); PG8_STAGE(PG8_SB(0, 0), b2, voffB); PG8_STAGE(PG8_SB(0, 1), b2 + hstepB, voffB); PG8_STAGE(PG8_SA(0, 0), a2, voffA);
.LBB0_51:
	s_mov_b32 s6, 0x10000
	v_add_u32_e32 v0, s6, v186
	s_mov_b32 s12, 0x14000
	ds_read_b128 v[130:133], v0
	ds_read_b128 v[134:137], v0 offset:1024
	ds_read_b128 v[138:141], v0 offset:2048
	ds_read_b128 v[142:145], v0 offset:3072
	v_add_u32_e32 v0, s12, v186
	ds_read_b128 v[154:157], v0
	ds_read_b128 v[158:161], v0 offset:1024
	ds_read_b128 v[162:165], v0 offset:2048
	ds_read_b128 v[166:169], v0 offset:3072
	ds_read_b128 v[170:173], v187
	ds_read_b128 v[174:177], v187 offset:1024
	ds_read_b128 v[178:181], v187 offset:2048
	ds_read_b128 v[188:191], v187 offset:3072
	ds_read_b128 v[192:195], v187 offset:4096
	ds_read_b128 v[196:199], v187 offset:5120
	ds_read_b128 v[200:203], v187 offset:6144
	ds_read_b128 v[204:207], v187 offset:7168
	s_add_u32 s2, s28, 0xfff80080
	s_addc_u32 s3, s29, -1
	s_cmp_eq_u32 s72, 28
	s_cselect_b32 s31, s49, s3
	s_cselect_b32 s30, s68, s2
	s_cselect_b32 s3, s47, s71
	s_cselect_b32 s2, s69, s70
	s_waitcnt lgkmcnt(0)
	s_add_i32 m0, s56, 0xc000
	s_nop 0
	global_load_lds_dwordx4 v150, s[28:29]
	s_add_i32 m0, s56, 0xe000
	s_nop 0
	global_load_lds_dwordx4 v152, s[28:29]
	s_waitcnt vmcnt(8)
	s_waitcnt lgkmcnt(0)
	s_barrier
	s_setprio 1
	s_waitcnt lgkmcnt(0)
	v_mfma_f32_16x16x32_bf16 v[126:129], v[130:133], v[170:173], v[126:129]
	v_mfma_f32_16x16x32_bf16 v[118:121], v[138:141], v[170:173], v[118:121]
	v_mfma_f32_16x16x32_bf16 v[110:113], v[130:133], v[178:181], v[110:113]
	v_mfma_f32_16x16x32_bf16 v[102:105], v[138:141], v[178:181], v[102:105]
	v_mfma_f32_16x16x32_bf16 v[94:97], v[130:133], v[192:195], v[94:97]
	v_mfma_f32_16x16x32_bf16 v[86:89], v[138:141], v[192:195], v[86:89]
	v_mfma_f32_16x16x32_bf16 v[78:81], v[130:133], v[200:203], v[78:81]
	v_mfma_f32_16x16x32_bf16 v[70:73], v[138:141], v[200:203], v[70:73]
	v_mfma_f32_16x16x32_bf16 v[126:129], v[134:137], v[174:177], v[126:129]
	v_mfma_f32_16x16x32_bf16 v[118:121], v[142:145], v[174:177], v[118:121]
	v_mfma_f32_16x16x32_bf16 v[110:113], v[134:137], v[188:191], v[110:113]
	v_mfma_f32_16x16x32_bf16 v[102:105], v[142:145], v[188:191], v[102:105]
	v_mfma_f32_16x16x32_bf16 v[94:97], v[134:137], v[196:199], v[94:97]
	v_mfma_f32_16x16x32_bf16 v[86:89], v[142:145], v[196:199], v[86:89]
	v_mfma_f32_16x16x32_bf16 v[78:81], v[134:137], v[204:207], v[78:81]
	v_mfma_f32_16x16x32_bf16 v[70:73], v[142:145], v[204:207], v[70:73]
	s_setprio 0
	s_setprio 1
	v_mfma_f32_16x16x32_bf16 v[122:125], v[154:157], v[170:173], v[122:125]
	v_mfma_f32_16x16x32_bf16 v[114:117], v[162:165], v[170:173], v[114:117]
	v_mfma_f32_16x16x32_bf16 v[106:109], v[154:157], v[178:181], v[106:109]
	v_mfma_f32_16x16x32_bf16 v[98:101], v[162:165], v[178:181], v[98:101]
	v_mfma_f32_16x16x32_bf16 v[90:93], v[154:157], v[192:195], v[90:93]
	v_mfma_f32_16x16x32_bf16 v[82:85], v[162:165], v[192:195], v[82:85]
	v_mfma_f32_16x16x32_bf16 v[74:77], v[154:157], v[200:203], v[74:77]
	v_mfma_f32_16x16x32_bf16 v[66:69], v[162:165], v[200:203], v[66:69]
	v_mfma_f32_16x16x32_bf16 v[122:125], v[158:161], v[174:177], v[122:125]
	v_mfma_f32_16x16x32_bf16 v[114:117], v[166:169], v[174:177], v[114:117]
	v_mfma_f32_16x16x32_bf16 v[106:109], v[158:161], v[188:191], v[106:109]
	v_mfma_f32_16x16x32_bf16 v[98:101], v[166:169], v[188:191], v[98:101]
	v_mfma_f32_16x16x32_bf16 v[90:93], v[158:161], v[196:199], v[90:93]
	s_setprio 2
	s_barrier
	v_mfma_f32_16x16x32_bf16 v[82:85], v[166:169], v[196:199], v[82:85]
	ds_read_b128 v[170:173], v187 offset:16384
	v_mfma_f32_16x16x32_bf16 v[74:77], v[158:161], v[204:207], v[74:77]
	ds_read_b128 v[174:177], v187 offset:17408
	ds_read_b128 v[178:181], v187 offset:18432
	v_mfma_f32_16x16x32_bf16 v[66:69], v[166:169], v[204:207], v[66:69]
	s_setprio 0
	s_add_i32 s6, s6, s55
	v_lshl_add_u64 v[182:183], s[2:3], 0, v[148:149]
	s_mov_b32 m0, s6
	ds_read_b128 v[188:191], v187 offset:19456
	ds_read_b128 v[192:195], v187 offset:20480
	ds_read_b128 v[196:199], v187 offset:21504
	ds_read_b128 v[200:203], v187 offset:22528
	ds_read_b128 v[204:207], v187 offset:23552
	global_load_lds_dwordx4 v[182:183], off
	s_add_i32 m0, s6, 0x2000
	s_add_u32 s14, s2, 0x80000
	v_lshl_add_u64 v[208:209], s[2:3], 0, v[146:147]
	s_addc_u32 s15, s3, 0
	s_add_i32 s6, s12, s55
	global_load_lds_dwordx4 v[208:209], off
	s_mov_b32 m0, s6
	v_lshl_add_u64 v[212:213], s[30:31], 0, v[146:147]
	global_load_lds_dwordx4 v148, s[14:15]
	s_add_i32 m0, s6, 0x2000
	s_nop 0
	global_load_lds_dwordx4 v146, s[14:15]
	v_lshl_add_u64 v[210:211], s[30:31], 0, v[148:149]
	s_mov_b32 m0, s56
	s_nop 0
	global_load_lds_dwordx4 v[210:211], off
	s_mov_b32 m0, s57
	s_nop 0
	global_load_lds_dwordx4 v[212:213], off
	s_waitcnt vmcnt(8)
	s_waitcnt lgkmcnt(0)
	s_barrier
; #define PG8_STAGE(bufoff, gbase, voff) do { _Pragma("unroll") for (int _i = 0; _i < 2; ++_i) \
;         __builtin_amdgcn_global_load_lds((const unsigned*)((const char*)(gbase) + (voff)[_i]), (LAS unsigned*)(lds + (bufoff) + ldsw + _i * 8192), 16, 0, 0); } while (0)
; #define PG8_LDA(dst, b, h) do { _Pragma("unroll") for (int m = 0; m < 4; ++m) _Pragma("unroll") for (int k = 0; k < 2; ++k) dst[m][k] = *(const LAS bf16x8*)(lds + PG8_SA(b, h) + aoff + m * 2048 + k * 1024); } while (0)
; #define PG8_LDB(dst, b, h) do { _Pragma("unroll") for (int n = 0; n < 2; ++n) _Pragma("unroll") for (int k = 0; k < 2; ++k) dst[n][k] = *(const LAS bf16x8*)(lds + PG8_SB(b, h) + boff + n * 2048 + k * 1024); } while (0)
; #define PG8_MMA(ai, bj, At, Bt) do { __builtin_amdgcn_s_setprio(1); _Pragma("unroll") for (int m = 0; m < 4; ++m) _Pragma("unroll") for (int n = 0; n < 2; ++n) _Pragma("unroll") for (int k = 0; k < 2; ++k) \
;         acc[ai][bj][m][n] = __builtin_amdgcn_mfma_f32_16x16x32_bf16(Bt[n][k], At[m][k], acc[ai][bj][m][n], 0, 0, 0); __builtin_amdgcn_s_setprio(0); } while (0)
; #define PG8_WAIT_V(n) asm volatile("s_waitcnt vmcnt(" #n ")" ::: "memory")
; #define PG8_WAIT_L(n) asm volatile("s_waitcnt lgkmcnt(" #n ")" ::: "memory")
; #define PG8_BAR __builtin_amdgcn_s_barrier()
; #define PG8_SCHED __builtin_amdgcn_sched_barrier(0)
; template <class Epi>
; __device__ __forceinline__ void gemm_phase(LAS unsigned char* lds, const Gemm g, const TileOrder& S, const Epi& E) {
;     ...
;             PG8_WAIT_V(8); PG8_WAIT_L(0); PG8_BAR; PG8_MMA(1, 0, At, B0); PG8_MMA(1, 1, At, B1); PG8_BAR; PG8_SCHED;
;             PG8_LDB(B0, 1, 0); PG8_LDB(B1, 1, 1); PG8_SCHED; PG8_LDA(At, 1, 0); PG8_STAGE(PG8_SA(0, 1), a2 + hstepA, voffA);
;             PG8_WAIT_V(8); PG8_WAIT_L(0); PG8_BAR; PG8_MMA(0, 0, At, B0); PG8_MMA(0, 1, At, B1); PG8_BAR; PG8_SCHED;
	s_setprio 1
	s_waitcnt lgkmcnt(0)
	v_mfma_f32_16x16x32_bf16 v[62:65], v[130:133], v[170:173], v[62:65]
	v_mfma_f32_16x16x32_bf16 v[54:57], v[138:141], v[170:173], v[54:57]
	v_mfma_f32_16x16x32_bf16 v[46:49], v[130:133], v[178:181], v[46:49]
	v_mfma_f32_16x16x32_bf16 v[38:41], v[138:141], v[178:181], v[38:41]
	v_mfma_f32_16x16x32_bf16 v[30:33], v[130:133], v[192:195], v[30:33]
	v_mfma_f32_16x16x32_bf16 v[22:25], v[138:141], v[192:195], v[22:25]
	v_mfma_f32_16x16x32_bf16 v[14:17], v[130:133], v[200:203], v[14:17]
	v_mfma_f32_16x16x32_bf16 v[6:9], v[138:141], v[200:203], v[6:9]
	v_mfma_f32_16x16x32_bf16 v[62:65], v[134:137], v[174:177], v[62:65]
	v_mfma_f32_16x16x32_bf16 v[54:57], v[142:145], v[174:177], v[54:57]
	v_mfma_f32_16x16x32_bf16 v[46:49], v[134:137], v[188:191], v[46:49]
	v_mfma_f32_16x16x32_bf16 v[38:41], v[142:145], v[188:191], v[38:41]
	v_mfma_f32_16x16x32_bf16 v[30:33], v[134:137], v[196:199], v[30:33]
	v_mfma_f32_16x16x32_bf16 v[22:25], v[142:145], v[196:199], v[22:25]
	v_mfma_f32_16x16x32_bf16 v[14:17], v[134:137], v[204:207], v[14:17]
	v_mfma_f32_16x16x32_bf16 v[6:9], v[142:145], v[204:207], v[6:9]
	s_setprio 0
	s_setprio 1
	v_mfma_f32_16x16x32_bf16 v[58:61], v[154:157], v[170:173], v[58:61]
	v_mfma_f32_16x16x32_bf16 v[50:53], v[162:165], v[170:173], v[50:53]
	v_mfma_f32_16x16x32_bf16 v[42:45], v[154:157], v[178:181], v[42:45]
	v_mfma_f32_16x16x32_bf16 v[34:37], v[162:165], v[178:181], v[34:37]
	v_mfma_f32_16x16x32_bf16 v[26:29], v[154:157], v[192:195], v[26:29]
	v_mfma_f32_16x16x32_bf16 v[18:21], v[162:165], v[192:195], v[18:21]
	v_mfma_f32_16x16x32_bf16 v[10:13], v[154:157], v[200:203], v[10:13]
	v_mfma_f32_16x16x32_bf16 v[2:5], v[162:165], v[200:203], v[2:5]
	v_mfma_f32_16x16x32_bf16 v[58:61], v[158:161], v[174:177], v[58:61]
	v_mfma_f32_16x16x32_bf16 v[50:53], v[166:169], v[174:177], v[50:53]
	v_mfma_f32_16x16x32_bf16 v[42:45], v[158:161], v[188:191], v[42:45]
	v_mfma_f32_16x16x32_bf16 v[34:37], v[166:169], v[188:191], v[34:37]
	v_mfma_f32_16x16x32_bf16 v[26:29], v[158:161], v[196:199], v[26:29]
	s_setprio 2
	s_barrier
	v_mfma_f32_16x16x32_bf16 v[18:21], v[166:169], v[196:199], v[18:21]
	s_mov_b32 s6, 0x18000
	v_add_u32_e32 v0, s6, v186
	s_mov_b32 s12, 0x1c000
	ds_read_b128 v[130:133], v0
	v_mfma_f32_16x16x32_bf16 v[10:13], v[158:161], v[204:207], v[10:13]
	ds_read_b128 v[134:137], v0 offset:1024
	ds_read_b128 v[138:141], v0 offset:2048
	v_mfma_f32_16x16x32_bf16 v[2:5], v[166:169], v[204:207], v[2:5]
	s_setprio 0
	ds_read_b128 v[142:145], v0 offset:3072
	v_add_u32_e32 v0, s12, v186
	ds_read_b128 v[154:157], v0
	ds_read_b128 v[158:161], v0 offset:1024
	ds_read_b128 v[162:165], v0 offset:2048
	ds_read_b128 v[166:169], v0 offset:3072
	s_add_u32 s14, s30, 0x80000
	s_addc_u32 s15, s31, 0
	s_mov_b32 m0, s58
	ds_read_b128 v[170:173], v187 offset:32768
	ds_read_b128 v[174:177], v187 offset:33792
	ds_read_b128 v[178:181], v187 offset:34816
	ds_read_b128 v[188:191], v187 offset:35840
	ds_read_b128 v[192:195], v187 offset:36864
	ds_read_b128 v[196:199], v187 offset:37888
	ds_read_b128 v[200:203], v187 offset:38912
	ds_read_b128 v[204:207], v187 offset:39936
	global_load_lds_dwordx4 v148, s[14:15]
	s_mov_b32 m0, s59
	s_nop 0
	global_load_lds_dwordx4 v146, s[14:15]
	s_waitcnt vmcnt(8)
	s_waitcnt lgkmcnt(0)
	s_barrier
	s_setprio 1
	s_waitcnt lgkmcnt(0)
	v_mfma_f32_16x16x32_bf16 v[126:129], v[130:133], v[170:173], v[126:129]
	v_mfma_f32_16x16x32_bf16 v[118:121], v[138:141], v[170:173], v[118:121]
	v_mfma_f32_16x16x32_bf16 v[110:113], v[130:133], v[178:181], v[110:113]
	v_mfma_f32_16x16x32_bf16 v[102:105], v[138:141], v[178:181], v[102:105]
	v_mfma_f32_16x16x32_bf16 v[94:97], v[130:133], v[192:195], v[94:97]
	v_mfma_f32_16x16x32_bf16 v[86:89], v[138:141], v[192:195], v[86:89]
	v_mfma_f32_16x16x32_bf16 v[78:81], v[130:133], v[200:203], v[78:81]
	v_mfma_f32_16x16x32_bf16 v[70:73], v[138:141], v[200:203], v[70:73]
	v_mfma_f32_16x16x32_bf16 v[126:129], v[134:137], v[174:177], v[126:129]
	v_mfma_f32_16x16x32_bf16 v[118:121], v[142:145], v[174:177], v[118:121]
	v_mfma_f32_16x16x32_bf16 v[110:113], v[134:137], v[188:191], v[110:113]
	v_mfma_f32_16x16x32_bf16 v[102:105], v[142:145], v[188:191], v[102:105]
	v_mfma_f32_16x16x32_bf16 v[94:97], v[134:137], v[196:199], v[94:97]
	v_mfma_f32_16x16x32_bf16 v[86:89], v[142:145], v[196:199], v[86:89]
	v_mfma_f32_16x16x32_bf16 v[78:81], v[134:137], v[204:207], v[78:81]
	v_mfma_f32_16x16x32_bf16 v[70:73], v[142:145], v[204:207], v[70:73]
	s_setprio 0
	s_setprio 1
	v_mfma_f32_16x16x32_bf16 v[122:125], v[154:157], v[170:173], v[122:125]
	v_mfma_f32_16x16x32_bf16 v[114:117], v[162:165], v[170:173], v[114:117]
	v_mfma_f32_16x16x32_bf16 v[106:109], v[154:157], v[178:181], v[106:109]
	v_mfma_f32_16x16x32_bf16 v[98:101], v[162:165], v[178:181], v[98:101]
	v_mfma_f32_16x16x32_bf16 v[90:93], v[154:157], v[192:195], v[90:93]
	v_mfma_f32_16x16x32_bf16 v[82:85], v[162:165], v[192:195], v[82:85]
	v_mfma_f32_16x16x32_bf16 v[74:77], v[154:157], v[200:203], v[74:77]
	v_mfma_f32_16x16x32_bf16 v[66:69], v[162:165], v[200:203], v[66:69]
	v_mfma_f32_16x16x32_bf16 v[122:125], v[158:161], v[174:177], v[122:125]
	v_mfma_f32_16x16x32_bf16 v[114:117], v[166:169], v[174:177], v[114:117]
	v_mfma_f32_16x16x32_bf16 v[106:109], v[158:161], v[188:191], v[106:109]
	v_mfma_f32_16x16x32_bf16 v[98:101], v[166:169], v[188:191], v[98:101]
	v_mfma_f32_16x16x32_bf16 v[90:93], v[158:161], v[196:199], v[90:93]
	s_setprio 2
	s_barrier
; #define PG8_STAGE(bufoff, gbase, voff) do { _Pragma("unroll") for (int _i = 0; _i < 2; ++_i) \
;         __builtin_amdgcn_global_load_lds((const unsigned*)((const char*)(gbase) + (voff)[_i]), (LAS unsigned*)(lds + (bufoff) + ldsw + _i * 8192), 16, 0, 0); } while (0)
; #define PG8_LDA(dst, b, h) do { _Pragma("unroll") for (int m = 0; m < 4; ++m) _Pragma("unroll") for (int k = 0; k < 2; ++k) dst[m][k] = *(const LAS bf16x8*)(lds + PG8_SA(b, h) + aoff + m * 2048 + k * 1024); } while (0)
; #define PG8_MMA(ai, bj, At, Bt) do { __builtin_amdgcn_s_setprio(1); _Pragma("unroll") for (int m = 0; m < 4; ++m) _Pragma("unroll") for (int n = 0; n < 2; ++n) _Pragma("unroll") for (int k = 0; k < 2; ++k) \
;         acc[ai][bj][m][n] = __builtin_amdgcn_mfma_f32_16x16x32_bf16(Bt[n][k], At[m][k], acc[ai][bj][m][n], 0, 0, 0); __builtin_amdgcn_s_setprio(0); } while (0)
; #define PG8_WAIT_V(n) asm volatile("s_waitcnt vmcnt(" #n ")" ::: "memory")
; #define PG8_WAIT_L(n) asm volatile("s_waitcnt lgkmcnt(" #n ")" ::: "memory")
; #define PG8_BAR __builtin_amdgcn_s_barrier()
; #define PG8_SCHED __builtin_amdgcn_sched_barrier(0)
; template <class Epi>
; __device__ __forceinline__ void gemm_phase(LAS unsigned char* lds, const Gemm g, const TileOrder& S, const Epi& E) {
;     ...
;             PG8_WAIT_V(8); PG8_WAIT_L(0); PG8_BAR; PG8_MMA(0, 0, At, B0); PG8_MMA(0, 1, At, B1); PG8_BAR; PG8_SCHED;
;             PG8_LDA(At, 1, 1); PG8_STAGE(PG8_SB(1, 0), b3, voffB); PG8_STAGE(PG8_SB(1, 1), b3 + hstepB, voffB); PG8_STAGE(PG8_SA(1, 0), a3, voffA);
;             PG8_WAIT_V(8); PG8_WAIT_L(0); PG8_BAR; PG8_MMA(1, 0, At, B0); PG8_MMA(1, 1, At, B1); PG8_BAR; PG8_SCHED;
;         }
;         if (wr == 0) PG8_BAR;
	v_mfma_f32_16x16x32_bf16 v[82:85], v[166:169], v[196:199], v[82:85]
	ds_read_b128 v[170:173], v187 offset:49152
	v_mfma_f32_16x16x32_bf16 v[74:77], v[158:161], v[204:207], v[74:77]
	ds_read_b128 v[174:177], v187 offset:50176
	ds_read_b128 v[178:181], v187 offset:51200
	v_mfma_f32_16x16x32_bf16 v[66:69], v[166:169], v[204:207], v[66:69]
	s_setprio 0
	s_add_i32 s6, s6, s55
	v_lshl_add_u64 v[182:183], v[182:183], 0, s[34:35]
	s_mov_b32 m0, s6
	ds_read_b128 v[188:191], v187 offset:52224
	ds_read_b128 v[192:195], v187 offset:53248
	ds_read_b128 v[196:199], v187 offset:54272
	ds_read_b128 v[200:203], v187 offset:55296
	ds_read_b128 v[204:207], v187 offset:56320
	global_load_lds_dwordx4 v[182:183], off
	s_add_i32 m0, s6, 0x2000
	s_add_u32 s2, s2, 0x80080
	v_lshl_add_u64 v[182:183], v[208:209], 0, s[34:35]
	s_addc_u32 s3, s3, 0
	s_add_i32 s6, s12, s55
	global_load_lds_dwordx4 v[182:183], off
	s_mov_b32 m0, s6
	s_nop 0
	global_load_lds_dwordx4 v148, s[2:3]
	v_lshl_add_u64 v[182:183], s[2:3], 0, v[146:147]
	s_add_i32 m0, s6, 0x2000
	s_nop 0
	global_load_lds_dwordx4 v[182:183], off
	v_lshl_add_u64 v[182:183], v[210:211], 0, s[34:35]
	s_mov_b32 m0, s61
	s_nop 0
	global_load_lds_dwordx4 v[182:183], off
	v_lshl_add_u64 v[182:183], v[212:213], 0, s[34:35]
	s_mov_b32 m0, s62
	s_nop 0
	global_load_lds_dwordx4 v[182:183], off
	s_waitcnt vmcnt(8)
	s_waitcnt lgkmcnt(0)
	s_barrier
	s_setprio 1
	s_waitcnt lgkmcnt(0)
	v_mfma_f32_16x16x32_bf16 v[62:65], v[130:133], v[170:173], v[62:65]
	v_mfma_f32_16x16x32_bf16 v[54:57], v[138:141], v[170:173], v[54:57]
	v_mfma_f32_16x16x32_bf16 v[46:49], v[130:133], v[178:181], v[46:49]
	v_mfma_f32_16x16x32_bf16 v[38:41], v[138:141], v[178:181], v[38:41]
	v_mfma_f32_16x16x32_bf16 v[30:33], v[130:133], v[192:195], v[30:33]
	v_mfma_f32_16x16x32_bf16 v[22:25], v[138:141], v[192:195], v[22:25]
	v_mfma_f32_16x16x32_bf16 v[14:17], v[130:133], v[200:203], v[14:17]
	v_mfma_f32_16x16x32_bf16 v[6:9], v[138:141], v[200:203], v[6:9]
	v_mfma_f32_16x16x32_bf16 v[62:65], v[134:137], v[174:177], v[62:65]
	v_mfma_f32_16x16x32_bf16 v[54:57], v[142:145], v[174:177], v[54:57]
	v_mfma_f32_16x16x32_bf16 v[46:49], v[134:137], v[188:191], v[46:49]
	v_mfma_f32_16x16x32_bf16 v[38:41], v[142:145], v[188:191], v[38:41]
	v_mfma_f32_16x16x32_bf16 v[30:33], v[134:137], v[196:199], v[30:33]
	v_mfma_f32_16x16x32_bf16 v[22:25], v[142:145], v[196:199], v[22:25]
	v_mfma_f32_16x16x32_bf16 v[14:17], v[134:137], v[204:207], v[14:17]
	v_mfma_f32_16x16x32_bf16 v[6:9], v[142:145], v[204:207], v[6:9]
	s_setprio 0
	s_setprio 1
	v_mfma_f32_16x16x32_bf16 v[58:61], v[154:157], v[170:173], v[58:61]
	v_mfma_f32_16x16x32_bf16 v[50:53], v[162:165], v[170:173], v[50:53]
	v_mfma_f32_16x16x32_bf16 v[42:45], v[154:157], v[178:181], v[42:45]
	v_mfma_f32_16x16x32_bf16 v[34:37], v[162:165], v[178:181], v[34:37]
	v_mfma_f32_16x16x32_bf16 v[26:29], v[154:157], v[192:195], v[26:29]
	v_mfma_f32_16x16x32_bf16 v[18:21], v[162:165], v[192:195], v[18:21]
	v_mfma_f32_16x16x32_bf16 v[10:13], v[154:157], v[200:203], v[10:13]
	v_mfma_f32_16x16x32_bf16 v[2:5], v[162:165], v[200:203], v[2:5]
	v_mfma_f32_16x16x32_bf16 v[58:61], v[158:161], v[174:177], v[58:61]
	v_mfma_f32_16x16x32_bf16 v[50:53], v[166:169], v[174:177], v[50:53]
	v_mfma_f32_16x16x32_bf16 v[42:45], v[158:161], v[188:191], v[42:45]
	v_mfma_f32_16x16x32_bf16 v[34:37], v[166:169], v[188:191], v[34:37]
	v_mfma_f32_16x16x32_bf16 v[26:29], v[158:161], v[196:199], v[26:29]
	v_mfma_f32_16x16x32_bf16 v[18:21], v[166:169], v[196:199], v[18:21]
	s_setprio 2
	s_barrier
	v_mfma_f32_16x16x32_bf16 v[10:13], v[158:161], v[204:207], v[10:13]
	v_mfma_f32_16x16x32_bf16 v[2:5], v[166:169], v[204:207], v[2:5]
	s_setprio 0
	s_add_i32 s72, s72, 2
	s_add_u32 s28, s28, 0x100
	s_addc_u32 s29, s29, 0
	s_add_u32 s70, s70, 0x100
	s_addc_u32 s71, s71, 0
	s_cmp_gt_u32 s72, 29
	s_cbranch_scc0 .LBB0_51
	s_and_b64 vcc, exec, s[44:45]
	s_cbranch_vccz .LBB0_54
	s_barrier

; #define PG8_STAGE(bufoff, gbase, voff) do { _Pragma("unroll") for (int _i = 0; _i < 2; ++_i) \
;         __builtin_amdgcn_global_load_lds((const unsigned*)((const char*)(gbase) + (voff)[_i]), (LAS unsigned*)(lds + (bufoff) + ldsw + _i * 8192), 16, 0, 0); } while (0)
; #define PG8_LDA(dst, b, h) do { _Pragma("unroll") for (int m = 0; m < 4; ++m) _Pragma("unroll") for (int k = 0; k < 2; ++k) dst[m][k] = *(const LAS bf16x8*)(lds + PG8_SA(b, h) + aoff + m * 2048 + k * 1024); } while (0)
; #define PG8_LDB(dst, b, h) do { _Pragma("unroll") for (int n = 0; n < 2; ++n) _Pragma("unroll") for (int k = 0; k < 2; ++k) dst[n][k] = *(const LAS bf16x8*)(lds + PG8_SB(b, h) + boff + n * 2048 + k * 1024); } while (0)
; #define PG8_MMA(ai, bj, At, Bt) do { __builtin_amdgcn_s_setprio(1); _Pragma("unroll") for (int m = 0; m < 4; ++m) _Pragma("unroll") for (int n = 0; n < 2; ++n) _Pragma("unroll") for (int k = 0; k < 2; ++k) \
;         acc[ai][bj][m][n] = __builtin_amdgcn_mfma_f32_16x16x32_bf16(Bt[n][k], At[m][k], acc[ai][bj][m][n], 0, 0, 0); __builtin_amdgcn_s_setprio(0); } while (0)
; #define PG8_WAIT_V(n) asm volatile("s_waitcnt vmcnt(" #n ")" ::: "memory")
; #define PG8_WAIT_L(n) asm volatile("s_waitcnt lgkmcnt(" #n ")" ::: "memory")
; #define PG8_BAR __builtin_amdgcn_s_barrier()
; #define PG8_SCHED __builtin_amdgcn_sched_barrier(0)
; template <class Epi>
; __device__ __forceinline__ void gemm_phase(LAS unsigned char* lds, const Gemm g, const TileOrder& S, const Epi& E) {
;     ...
;             const bool last = (t == nt - 2);
;             const char* a1 = cA + (size_t)(t + 1) * kstepA;
;             const char* a2 = last ? nA : cA + (size_t)(t + 2) * kstepA; const char* b2 = last ? nB : cB + (size_t)(t + 2) * kstep;
;             const char* a3 = a2 + kstepA; const char* b3 = b2 + kstep;
;             PG8_LDB(B0, 0, 0); PG8_LDB(B1, 0, 1); PG8_SCHED; PG8_LDA(At, 0, 0); PG8_STAGE(PG8_SA(1, 1), a1 + hstepA, voffA);
;             PG8_WAIT_V(8); PG8_WAIT_L(0); PG8_BAR; PG8_MMA(0, 0, At, B0); PG8_MMA(0, 1, At, B1); PG8_BAR; PG8_SCHED;
;             PG8_LDA(At, 0, 1); PG8_STAGE(PG8_SB(0, 0), b2, voffB); PG8_STAGE(PG8_SB(0, 1), b2 + hstepB, voffB); PG8_STAGE(PG8_SA(0, 0), a2, voffA);
;             PG8_WAIT_V(8); PG8_WAIT_L(0); PG8_BAR; PG8_MMA(1, 0, At, B0); PG8_MMA(1, 1, At, B1); PG8_BAR; PG8_SCHED;
.LBB0_255:
	s_mov_b32 s6, 0x10000
	s_mov_b32 s14, 0x14000
	v_add_u32_e32 v134, s6, v238
	v_add_u32_e32 v158, s14, v238
	ds_read_b128 v[118:121], v134
	ds_read_b128 v[126:129], v134 offset:1024
	ds_read_b128 v[130:133], v134 offset:2048
	ds_read_b128 v[134:137], v134 offset:3072
	ds_read_b128 v[138:141], v158
	ds_read_b128 v[142:145], v158 offset:1024
	ds_read_b128 v[154:157], v158 offset:2048
	ds_read_b128 v[158:161], v158 offset:3072
	ds_read_b128 v[162:165], v239
	ds_read_b128 v[166:169], v239 offset:1024
	ds_read_b128 v[170:173], v239 offset:2048
	ds_read_b128 v[174:177], v239 offset:3072
	ds_read_b128 v[178:181], v239 offset:4096
	ds_read_b128 v[182:185], v239 offset:5120
	ds_read_b128 v[186:189], v239 offset:6144
	ds_read_b128 v[200:203], v239 offset:7168
	s_add_u32 s2, s28, 0x4000
	s_addc_u32 s3, s29, 0
	s_cmp_eq_u32 s68, 28
	s_cselect_b32 s48, s64, s2
	s_cselect_b32 s49, s43, s3
	s_cselect_b32 s30, s65, s66
	s_cselect_b32 s31, s39, s67
	s_add_u32 s2, s48, 0x8000
	s_addc_u32 s3, s49, 0
	s_add_i32 m0, s52, 0xc000
	s_nop 0
	global_load_lds_dwordx4 v196, s[28:29]
	s_add_i32 m0, s52, 0xe000
	s_nop 0
	global_load_lds_dwordx4 v198, s[28:29]
	s_waitcnt vmcnt(8)
	s_waitcnt lgkmcnt(0)
	s_barrier
	s_setprio 1
	s_waitcnt lgkmcnt(0)
	v_mfma_f32_16x16x32_bf16 v[150:153], v[118:121], v[162:165], v[150:153]
	v_mfma_f32_16x16x32_bf16 v[146:149], v[130:133], v[162:165], v[146:149]
	v_mfma_f32_16x16x32_bf16 v[110:113], v[118:121], v[170:173], v[110:113]
	v_mfma_f32_16x16x32_bf16 v[106:109], v[130:133], v[170:173], v[106:109]
	v_mfma_f32_16x16x32_bf16 v[94:97], v[118:121], v[178:181], v[94:97]
	v_mfma_f32_16x16x32_bf16 v[90:93], v[130:133], v[178:181], v[90:93]
	v_mfma_f32_16x16x32_bf16 v[78:81], v[118:121], v[186:189], v[78:81]
	v_mfma_f32_16x16x32_bf16 v[74:77], v[130:133], v[186:189], v[74:77]
	v_mfma_f32_16x16x32_bf16 v[150:153], v[126:129], v[166:169], v[150:153]
	v_mfma_f32_16x16x32_bf16 v[146:149], v[134:137], v[166:169], v[146:149]
	v_mfma_f32_16x16x32_bf16 v[110:113], v[126:129], v[174:177], v[110:113]
	v_mfma_f32_16x16x32_bf16 v[106:109], v[134:137], v[174:177], v[106:109]
	v_mfma_f32_16x16x32_bf16 v[94:97], v[126:129], v[182:185], v[94:97]
	v_mfma_f32_16x16x32_bf16 v[90:93], v[134:137], v[182:185], v[90:93]
	v_mfma_f32_16x16x32_bf16 v[78:81], v[126:129], v[200:203], v[78:81]
	v_mfma_f32_16x16x32_bf16 v[74:77], v[134:137], v[200:203], v[74:77]
	s_setprio 0
	s_setprio 1
	v_mfma_f32_16x16x32_bf16 v[122:125], v[138:141], v[162:165], v[122:125]
	v_mfma_f32_16x16x32_bf16 v[114:117], v[154:157], v[162:165], v[114:117]
	v_mfma_f32_16x16x32_bf16 v[102:105], v[138:141], v[170:173], v[102:105]
	v_mfma_f32_16x16x32_bf16 v[98:101], v[154:157], v[170:173], v[98:101]
	v_mfma_f32_16x16x32_bf16 v[86:89], v[138:141], v[178:181], v[86:89]
	v_mfma_f32_16x16x32_bf16 v[82:85], v[154:157], v[178:181], v[82:85]
	v_mfma_f32_16x16x32_bf16 v[70:73], v[138:141], v[186:189], v[70:73]
	v_mfma_f32_16x16x32_bf16 v[66:69], v[154:157], v[186:189], v[66:69]
	v_mfma_f32_16x16x32_bf16 v[122:125], v[142:145], v[166:169], v[122:125]
	v_mfma_f32_16x16x32_bf16 v[114:117], v[158:161], v[166:169], v[114:117]
	v_mfma_f32_16x16x32_bf16 v[102:105], v[142:145], v[174:177], v[102:105]
	v_mfma_f32_16x16x32_bf16 v[98:101], v[158:161], v[174:177], v[98:101]
	v_mfma_f32_16x16x32_bf16 v[86:89], v[142:145], v[182:185], v[86:89]
	s_setprio 2
	s_barrier
	v_mfma_f32_16x16x32_bf16 v[82:85], v[158:161], v[182:185], v[82:85]
	ds_read_b128 v[162:165], v239 offset:16384
	v_mfma_f32_16x16x32_bf16 v[70:73], v[142:145], v[200:203], v[70:73]
	ds_read_b128 v[166:169], v239 offset:17408
	ds_read_b128 v[170:173], v239 offset:18432
	v_mfma_f32_16x16x32_bf16 v[66:69], v[158:161], v[200:203], v[66:69]
	s_setprio 0
	s_add_i32 s6, s6, s51
	v_lshl_add_u64 v[204:205], s[30:31], 0, v[0:1]
	s_mov_b32 m0, s6
	ds_read_b128 v[174:177], v239 offset:19456
	ds_read_b128 v[178:181], v239 offset:20480
	ds_read_b128 v[182:185], v239 offset:21504
	ds_read_b128 v[186:189], v239 offset:22528
	ds_read_b128 v[200:203], v239 offset:23552
	global_load_lds_dwordx4 v[204:205], off
	s_add_i32 m0, s6, 0x2000
	s_add_u32 s12, s30, 0x80000
	v_lshl_add_u64 v[206:207], s[30:31], 0, v[190:191]
	s_addc_u32 s13, s31, 0
	s_add_i32 s6, s14, s51
	global_load_lds_dwordx4 v[206:207], off
	s_mov_b32 m0, s6
	s_nop 0
	global_load_lds_dwordx4 v0, s[12:13]
	s_add_i32 m0, s6, 0x2000
	s_nop 0
	global_load_lds_dwordx4 v190, s[12:13]
	s_mov_b32 m0, s52
	s_nop 0
	global_load_lds_dwordx4 v194, s[48:49]
	s_mov_b32 m0, s53
	s_nop 0
	global_load_lds_dwordx4 v192, s[48:49]
	s_waitcnt vmcnt(8)
	s_waitcnt lgkmcnt(0)
	s_barrier
	s_setprio 1
	s_waitcnt lgkmcnt(0)
	v_mfma_f32_16x16x32_bf16 v[62:65], v[118:121], v[162:165], v[62:65]
	v_mfma_f32_16x16x32_bf16 v[58:61], v[130:133], v[162:165], v[58:61]
	v_mfma_f32_16x16x32_bf16 v[46:49], v[118:121], v[170:173], v[46:49]
	v_mfma_f32_16x16x32_bf16 v[42:45], v[130:133], v[170:173], v[42:45]
	v_mfma_f32_16x16x32_bf16 v[30:33], v[118:121], v[178:181], v[30:33]
	v_mfma_f32_16x16x32_bf16 v[26:29], v[130:133], v[178:181], v[26:29]
	v_mfma_f32_16x16x32_bf16 v[14:17], v[118:121], v[186:189], v[14:17]
	v_mfma_f32_16x16x32_bf16 v[10:13], v[130:133], v[186:189], v[10:13]
	v_mfma_f32_16x16x32_bf16 v[62:65], v[126:129], v[166:169], v[62:65]
	v_mfma_f32_16x16x32_bf16 v[58:61], v[134:137], v[166:169], v[58:61]
	v_mfma_f32_16x16x32_bf16 v[46:49], v[126:129], v[174:177], v[46:49]
	v_mfma_f32_16x16x32_bf16 v[42:45], v[134:137], v[174:177], v[42:45]
	v_mfma_f32_16x16x32_bf16 v[30:33], v[126:129], v[182:185], v[30:33]
	v_mfma_f32_16x16x32_bf16 v[26:29], v[134:137], v[182:185], v[26:29]
	v_mfma_f32_16x16x32_bf16 v[14:17], v[126:129], v[200:203], v[14:17]
	v_mfma_f32_16x16x32_bf16 v[10:13], v[134:137], v[200:203], v[10:13]
	s_setprio 0
	s_setprio 1
	v_mfma_f32_16x16x32_bf16 v[54:57], v[138:141], v[162:165], v[54:57]
	v_mfma_f32_16x16x32_bf16 v[50:53], v[154:157], v[162:165], v[50:53]
	v_mfma_f32_16x16x32_bf16 v[38:41], v[138:141], v[170:173], v[38:41]
	v_mfma_f32_16x16x32_bf16 v[34:37], v[154:157], v[170:173], v[34:37]
	v_mfma_f32_16x16x32_bf16 v[22:25], v[138:141], v[178:181], v[22:25]
	v_mfma_f32_16x16x32_bf16 v[18:21], v[154:157], v[178:181], v[18:21]
	v_mfma_f32_16x16x32_bf16 v[6:9], v[138:141], v[186:189], v[6:9]
	v_mfma_f32_16x16x32_bf16 v[2:5], v[154:157], v[186:189], v[2:5]
	v_mfma_f32_16x16x32_bf16 v[54:57], v[142:145], v[166:169], v[54:57]
	v_mfma_f32_16x16x32_bf16 v[50:53], v[158:161], v[166:169], v[50:53]
	v_mfma_f32_16x16x32_bf16 v[38:41], v[142:145], v[174:177], v[38:41]
	v_mfma_f32_16x16x32_bf16 v[34:37], v[158:161], v[174:177], v[34:37]
	v_mfma_f32_16x16x32_bf16 v[22:25], v[142:145], v[182:185], v[22:25]
	s_setprio 2
	s_barrier
; #define PG8_STAGE(bufoff, gbase, voff) do { _Pragma("unroll") for (int _i = 0; _i < 2; ++_i) \
;         __builtin_amdgcn_global_load_lds((const unsigned*)((const char*)(gbase) + (voff)[_i]), (LAS unsigned*)(lds + (bufoff) + ldsw + _i * 8192), 16, 0, 0); } while (0)
; #define PG8_LDA(dst, b, h) do { _Pragma("unroll") for (int m = 0; m < 4; ++m) _Pragma("unroll") for (int k = 0; k < 2; ++k) dst[m][k] = *(const LAS bf16x8*)(lds + PG8_SA(b, h) + aoff + m * 2048 + k * 1024); } while (0)
; #define PG8_LDB(dst, b, h) do { _Pragma("unroll") for (int n = 0; n < 2; ++n) _Pragma("unroll") for (int k = 0; k < 2; ++k) dst[n][k] = *(const LAS bf16x8*)(lds + PG8_SB(b, h) + boff + n * 2048 + k * 1024); } while (0)
; #define PG8_MMA(ai, bj, At, Bt) do { __builtin_amdgcn_s_setprio(1); _Pragma("unroll") for (int m = 0; m < 4; ++m) _Pragma("unroll") for (int n = 0; n < 2; ++n) _Pragma("unroll") for (int k = 0; k < 2; ++k) \
;         acc[ai][bj][m][n] = __builtin_amdgcn_mfma_f32_16x16x32_bf16(Bt[n][k], At[m][k], acc[ai][bj][m][n], 0, 0, 0); __builtin_amdgcn_s_setprio(0); } while (0)
; #define PG8_WAIT_V(n) asm volatile("s_waitcnt vmcnt(" #n ")" ::: "memory")
; #define PG8_WAIT_L(n) asm volatile("s_waitcnt lgkmcnt(" #n ")" ::: "memory")
; #define PG8_BAR __builtin_amdgcn_s_barrier()
; #define PG8_SCHED __builtin_amdgcn_sched_barrier(0)
; template <class Epi>
; __device__ __forceinline__ void gemm_phase(LAS unsigned char* lds, const Gemm g, const TileOrder& S, const Epi& E) {
;     ...
;             PG8_WAIT_V(8); PG8_WAIT_L(0); PG8_BAR; PG8_MMA(1, 0, At, B0); PG8_MMA(1, 1, At, B1); PG8_BAR; PG8_SCHED;
;             PG8_LDB(B0, 1, 0); PG8_LDB(B1, 1, 1); PG8_SCHED; PG8_LDA(At, 1, 0); PG8_STAGE(PG8_SA(0, 1), a2 + hstepA, voffA);
;             PG8_WAIT_V(8); PG8_WAIT_L(0); PG8_BAR; PG8_MMA(0, 0, At, B0); PG8_MMA(0, 1, At, B1); PG8_BAR; PG8_SCHED;
	v_mfma_f32_16x16x32_bf16 v[18:21], v[158:161], v[182:185], v[18:21]
	s_mov_b32 s6, 0x18000
	s_mov_b32 s14, 0x1c000
	v_add_u32_e32 v134, s6, v238
	ds_read_b128 v[118:121], v134
	v_mfma_f32_16x16x32_bf16 v[6:9], v[142:145], v[200:203], v[6:9]
	ds_read_b128 v[126:129], v134 offset:1024
	ds_read_b128 v[130:133], v134 offset:2048
	v_mfma_f32_16x16x32_bf16 v[2:5], v[158:161], v[200:203], v[2:5]
	s_setprio 0
	v_add_u32_e32 v158, s14, v238
	ds_read_b128 v[134:137], v134 offset:3072
	ds_read_b128 v[138:141], v158
	ds_read_b128 v[142:145], v158 offset:1024
	ds_read_b128 v[154:157], v158 offset:2048
	ds_read_b128 v[158:161], v158 offset:3072
	s_add_u32 s12, s48, 0x4000
	s_addc_u32 s13, s49, 0
	s_mov_b32 m0, s54
	ds_read_b128 v[162:165], v239 offset:32768
	ds_read_b128 v[166:169], v239 offset:33792
	ds_read_b128 v[170:173], v239 offset:34816
	ds_read_b128 v[174:177], v239 offset:35840
	ds_read_b128 v[178:181], v239 offset:36864
	ds_read_b128 v[182:185], v239 offset:37888
	ds_read_b128 v[186:189], v239 offset:38912
	ds_read_b128 v[200:203], v239 offset:39936
	global_load_lds_dwordx4 v194, s[12:13]
	s_mov_b32 m0, s55
	s_nop 0
	global_load_lds_dwordx4 v192, s[12:13]
	s_waitcnt vmcnt(8)
	s_waitcnt lgkmcnt(0)
	s_barrier
	s_setprio 1
	s_waitcnt lgkmcnt(0)
	v_mfma_f32_16x16x32_bf16 v[150:153], v[118:121], v[162:165], v[150:153]
	v_mfma_f32_16x16x32_bf16 v[146:149], v[130:133], v[162:165], v[146:149]
	v_mfma_f32_16x16x32_bf16 v[110:113], v[118:121], v[170:173], v[110:113]
	v_mfma_f32_16x16x32_bf16 v[106:109], v[130:133], v[170:173], v[106:109]
	v_mfma_f32_16x16x32_bf16 v[94:97], v[118:121], v[178:181], v[94:97]
	v_mfma_f32_16x16x32_bf16 v[90:93], v[130:133], v[178:181], v[90:93]
	v_mfma_f32_16x16x32_bf16 v[78:81], v[118:121], v[186:189], v[78:81]
	v_mfma_f32_16x16x32_bf16 v[74:77], v[130:133], v[186:189], v[74:77]
	v_mfma_f32_16x16x32_bf16 v[150:153], v[126:129], v[166:169], v[150:153]
	v_mfma_f32_16x16x32_bf16 v[146:149], v[134:137], v[166:169], v[146:149]
	v_mfma_f32_16x16x32_bf16 v[110:113], v[126:129], v[174:177], v[110:113]
	v_mfma_f32_16x16x32_bf16 v[106:109], v[134:137], v[174:177], v[106:109]
	v_mfma_f32_16x16x32_bf16 v[94:97], v[126:129], v[182:185], v[94:97]
	v_mfma_f32_16x16x32_bf16 v[90:93], v[134:137], v[182:185], v[90:93]
	v_mfma_f32_16x16x32_bf16 v[78:81], v[126:129], v[200:203], v[78:81]
	v_mfma_f32_16x16x32_bf16 v[74:77], v[134:137], v[200:203], v[74:77]
	s_setprio 0
	s_setprio 1
	v_mfma_f32_16x16x32_bf16 v[122:125], v[138:141], v[162:165], v[122:125]
	v_mfma_f32_16x16x32_bf16 v[114:117], v[154:157], v[162:165], v[114:117]
	v_mfma_f32_16x16x32_bf16 v[102:105], v[138:141], v[170:173], v[102:105]
	v_mfma_f32_16x16x32_bf16 v[98:101], v[154:157], v[170:173], v[98:101]
	v_mfma_f32_16x16x32_bf16 v[86:89], v[138:141], v[178:181], v[86:89]
	v_mfma_f32_16x16x32_bf16 v[82:85], v[154:157], v[178:181], v[82:85]
	v_mfma_f32_16x16x32_bf16 v[70:73], v[138:141], v[186:189], v[70:73]
	v_mfma_f32_16x16x32_bf16 v[66:69], v[154:157], v[186:189], v[66:69]
	v_mfma_f32_16x16x32_bf16 v[122:125], v[142:145], v[166:169], v[122:125]
	v_mfma_f32_16x16x32_bf16 v[114:117], v[158:161], v[166:169], v[114:117]
	v_mfma_f32_16x16x32_bf16 v[102:105], v[142:145], v[174:177], v[102:105]
	v_mfma_f32_16x16x32_bf16 v[98:101], v[158:161], v[174:177], v[98:101]
	v_mfma_f32_16x16x32_bf16 v[86:89], v[142:145], v[182:185], v[86:89]
	s_setprio 2
	s_barrier
; #define PG8_STAGE(bufoff, gbase, voff) do { _Pragma("unroll") for (int _i = 0; _i < 2; ++_i) \
;         __builtin_amdgcn_global_load_lds((const unsigned*)((const char*)(gbase) + (voff)[_i]), (LAS unsigned*)(lds + (bufoff) + ldsw + _i * 8192), 16, 0, 0); } while (0)
; #define PG8_LDA(dst, b, h) do { _Pragma("unroll") for (int m = 0; m < 4; ++m) _Pragma("unroll") for (int k = 0; k < 2; ++k) dst[m][k] = *(const LAS bf16x8*)(lds + PG8_SA(b, h) + aoff + m * 2048 + k * 1024); } while (0)
; #define PG8_MMA(ai, bj, At, Bt) do { __builtin_amdgcn_s_setprio(1); _Pragma("unroll") for (int m = 0; m < 4; ++m) _Pragma("unroll") for (int n = 0; n < 2; ++n) _Pragma("unroll") for (int k = 0; k < 2; ++k) \
;         acc[ai][bj][m][n] = __builtin_amdgcn_mfma_f32_16x16x32_bf16(Bt[n][k], At[m][k], acc[ai][bj][m][n], 0, 0, 0); __builtin_amdgcn_s_setprio(0); } while (0)
; #define PG8_WAIT_V(n) asm volatile("s_waitcnt vmcnt(" #n ")" ::: "memory")
; #define PG8_WAIT_L(n) asm volatile("s_waitcnt lgkmcnt(" #n ")" ::: "memory")
; #define PG8_BAR __builtin_amdgcn_s_barrier()
; #define PG8_SCHED __builtin_amdgcn_sched_barrier(0)
; template <class Epi>
; __device__ __forceinline__ void gemm_phase(LAS unsigned char* lds, const Gemm g, const TileOrder& S, const Epi& E) {
;     ...
;             PG8_WAIT_V(8); PG8_WAIT_L(0); PG8_BAR; PG8_MMA(0, 0, At, B0); PG8_MMA(0, 1, At, B1); PG8_BAR; PG8_SCHED;
;             PG8_LDA(At, 1, 1); PG8_STAGE(PG8_SB(1, 0), b3, voffB); PG8_STAGE(PG8_SB(1, 1), b3 + hstepB, voffB); PG8_STAGE(PG8_SA(1, 0), a3, voffA);
;             PG8_WAIT_V(8); PG8_WAIT_L(0); PG8_BAR; PG8_MMA(1, 0, At, B0); PG8_MMA(1, 1, At, B1); PG8_BAR; PG8_SCHED;
;         }
;         if (wr == 0) PG8_BAR;
	v_mfma_f32_16x16x32_bf16 v[82:85], v[158:161], v[182:185], v[82:85]
	ds_read_b128 v[162:165], v239 offset:49152
	v_mfma_f32_16x16x32_bf16 v[70:73], v[142:145], v[200:203], v[70:73]
	ds_read_b128 v[166:169], v239 offset:50176
	ds_read_b128 v[170:173], v239 offset:51200
	v_mfma_f32_16x16x32_bf16 v[66:69], v[158:161], v[200:203], v[66:69]
	s_setprio 0
	s_add_i32 s6, s6, s51
	v_lshl_add_u64 v[204:205], v[204:205], 0, s[34:35]
	s_mov_b32 m0, s6
	ds_read_b128 v[174:177], v239 offset:52224
	ds_read_b128 v[178:181], v239 offset:53248
	ds_read_b128 v[182:185], v239 offset:54272
	ds_read_b128 v[186:189], v239 offset:55296
	ds_read_b128 v[200:203], v239 offset:56320
	global_load_lds_dwordx4 v[204:205], off
	s_add_i32 m0, s6, 0x2000
	s_add_u32 s12, s30, 0x80080
	v_lshl_add_u64 v[204:205], v[206:207], 0, s[34:35]
	s_addc_u32 s13, s31, 0
	s_add_i32 s6, s14, s51
	global_load_lds_dwordx4 v[204:205], off
	s_mov_b32 m0, s6
	s_nop 0
	global_load_lds_dwordx4 v0, s[12:13]
	s_add_i32 m0, s6, 0x2000
	s_nop 0
	global_load_lds_dwordx4 v190, s[12:13]
	s_mov_b32 m0, s60
	s_nop 0
	global_load_lds_dwordx4 v194, s[2:3]
	s_mov_b32 m0, s61
	s_nop 0
	global_load_lds_dwordx4 v192, s[2:3]
	s_waitcnt vmcnt(8)
	s_waitcnt lgkmcnt(0)
	s_barrier
	s_setprio 1
	s_waitcnt lgkmcnt(0)
	v_mfma_f32_16x16x32_bf16 v[62:65], v[118:121], v[162:165], v[62:65]
	v_mfma_f32_16x16x32_bf16 v[58:61], v[130:133], v[162:165], v[58:61]
	v_mfma_f32_16x16x32_bf16 v[46:49], v[118:121], v[170:173], v[46:49]
	v_mfma_f32_16x16x32_bf16 v[42:45], v[130:133], v[170:173], v[42:45]
	v_mfma_f32_16x16x32_bf16 v[30:33], v[118:121], v[178:181], v[30:33]
	v_mfma_f32_16x16x32_bf16 v[26:29], v[130:133], v[178:181], v[26:29]
	v_mfma_f32_16x16x32_bf16 v[14:17], v[118:121], v[186:189], v[14:17]
	v_mfma_f32_16x16x32_bf16 v[10:13], v[130:133], v[186:189], v[10:13]
	v_mfma_f32_16x16x32_bf16 v[62:65], v[126:129], v[166:169], v[62:65]
	v_mfma_f32_16x16x32_bf16 v[58:61], v[134:137], v[166:169], v[58:61]
	v_mfma_f32_16x16x32_bf16 v[46:49], v[126:129], v[174:177], v[46:49]
	v_mfma_f32_16x16x32_bf16 v[42:45], v[134:137], v[174:177], v[42:45]
	v_mfma_f32_16x16x32_bf16 v[30:33], v[126:129], v[182:185], v[30:33]
	v_mfma_f32_16x16x32_bf16 v[26:29], v[134:137], v[182:185], v[26:29]
	v_mfma_f32_16x16x32_bf16 v[14:17], v[126:129], v[200:203], v[14:17]
	v_mfma_f32_16x16x32_bf16 v[10:13], v[134:137], v[200:203], v[10:13]
	s_setprio 0
	s_setprio 1
	v_mfma_f32_16x16x32_bf16 v[54:57], v[138:141], v[162:165], v[54:57]
	v_mfma_f32_16x16x32_bf16 v[50:53], v[154:157], v[162:165], v[50:53]
	v_mfma_f32_16x16x32_bf16 v[38:41], v[138:141], v[170:173], v[38:41]
	v_mfma_f32_16x16x32_bf16 v[34:37], v[154:157], v[170:173], v[34:37]
	v_mfma_f32_16x16x32_bf16 v[22:25], v[138:141], v[178:181], v[22:25]
	v_mfma_f32_16x16x32_bf16 v[18:21], v[154:157], v[178:181], v[18:21]
	v_mfma_f32_16x16x32_bf16 v[6:9], v[138:141], v[186:189], v[6:9]
	v_mfma_f32_16x16x32_bf16 v[2:5], v[154:157], v[186:189], v[2:5]
	v_mfma_f32_16x16x32_bf16 v[54:57], v[142:145], v[166:169], v[54:57]
	v_mfma_f32_16x16x32_bf16 v[50:53], v[158:161], v[166:169], v[50:53]
	v_mfma_f32_16x16x32_bf16 v[38:41], v[142:145], v[174:177], v[38:41]
	v_mfma_f32_16x16x32_bf16 v[34:37], v[158:161], v[174:177], v[34:37]
	v_mfma_f32_16x16x32_bf16 v[22:25], v[142:145], v[182:185], v[22:25]
	v_mfma_f32_16x16x32_bf16 v[18:21], v[158:161], v[182:185], v[18:21]
	s_setprio 2
	s_barrier
	v_mfma_f32_16x16x32_bf16 v[6:9], v[142:145], v[200:203], v[6:9]
	v_mfma_f32_16x16x32_bf16 v[2:5], v[158:161], v[200:203], v[2:5]
	s_setprio 0
	s_add_i32 s68, s68, 2
	s_add_u32 s66, s66, 0x100
	s_addc_u32 s67, s67, 0
	s_add_u32 s28, s28, 0x10000
	s_addc_u32 s29, s29, 0
	s_cmp_gt_u32 s68, 29
	s_cbranch_scc0 .LBB0_255
	s_and_b64 vcc, exec, s[36:37]
	s_cbranch_vccz .LBB0_258
	s_barrier

; #define PG8_STAGE(bufoff, gbase, voff) do { _Pragma("unroll") for (int _i = 0; _i < 2; ++_i) \
;         __builtin_amdgcn_global_load_lds((const unsigned*)((const char*)(gbase) + (voff)[_i]), (LAS unsigned*)(lds + (bufoff) + ldsw + _i * 8192), 16, 0, 0); } while (0)
; #define PG8_LDA(dst, b, h) do { _Pragma("unroll") for (int m = 0; m < 4; ++m) _Pragma("unroll") for (int k = 0; k < 2; ++k) dst[m][k] = *(const LAS bf16x8*)(lds + PG8_SA(b, h) + aoff + m * 2048 + k * 1024); } while (0)
; #define PG8_LDB(dst, b, h) do { _Pragma("unroll") for (int n = 0; n < 2; ++n) _Pragma("unroll") for (int k = 0; k < 2; ++k) dst[n][k] = *(const LAS bf16x8*)(lds + PG8_SB(b, h) + boff + n * 2048 + k * 1024); } while (0)
; #define PG8_MMA(ai, bj, At, Bt) do { __builtin_amdgcn_s_setprio(1); _Pragma("unroll") for (int m = 0; m < 4; ++m) _Pragma("unroll") for (int n = 0; n < 2; ++n) _Pragma("unroll") for (int k = 0; k < 2; ++k) \
;         acc[ai][bj][m][n] = __builtin_amdgcn_mfma_f32_16x16x32_bf16(Bt[n][k], At[m][k], acc[ai][bj][m][n], 0, 0, 0); __builtin_amdgcn_s_setprio(0); } while (0)
; #define PG8_WAIT_V(n) asm volatile("s_waitcnt vmcnt(" #n ")" ::: "memory")
; #define PG8_WAIT_L(n) asm volatile("s_waitcnt lgkmcnt(" #n ")" ::: "memory")
; #define PG8_BAR __builtin_amdgcn_s_barrier()
; #define PG8_SCHED __builtin_amdgcn_sched_barrier(0)
; template <class Epi>
; __device__ __forceinline__ void gemm_phase(LAS unsigned char* lds, const Gemm g, const TileOrder& S, const Epi& E) {
;     ...
;             const bool last = (t == nt - 2);
;             const char* a1 = cA + (size_t)(t + 1) * kstepA;
;             const char* a2 = last ? nA : cA + (size_t)(t + 2) * kstepA; const char* b2 = last ? nB : cB + (size_t)(t + 2) * kstep;
;             const char* a3 = a2 + kstepA; const char* b3 = b2 + kstep;
;             PG8_LDB(B0, 0, 0); PG8_LDB(B1, 0, 1); PG8_SCHED; PG8_LDA(At, 0, 0); PG8_STAGE(PG8_SA(1, 1), a1 + hstepA, voffA);
;             PG8_WAIT_V(8); PG8_WAIT_L(0); PG8_BAR; PG8_MMA(0, 0, At, B0); PG8_MMA(0, 1, At, B1); PG8_BAR; PG8_SCHED;
;             PG8_LDA(At, 0, 1); PG8_STAGE(PG8_SB(0, 0), b2, voffB); PG8_STAGE(PG8_SB(0, 1), b2 + hstepB, voffB); PG8_STAGE(PG8_SA(0, 0), a2, voffA);
.LBB0_457:
	s_mov_b32 s6, 0x10000
	s_mov_b32 s12, 0x14000
	v_add_u32_e32 v156, s6, v142
	v_add_u32_e32 v172, s12, v142
	ds_read_b128 v[144:147], v156
	ds_read_b128 v[148:151], v156 offset:1024
	ds_read_b128 v[152:155], v156 offset:2048
	ds_read_b128 v[156:159], v156 offset:3072
	ds_read_b128 v[160:163], v172
	ds_read_b128 v[164:167], v172 offset:1024
	ds_read_b128 v[168:171], v172 offset:2048
	ds_read_b128 v[172:175], v172 offset:3072
	ds_read_b128 v[176:179], v143
	ds_read_b128 v[180:183], v143 offset:1024
	ds_read_b128 v[184:187], v143 offset:2048
	ds_read_b128 v[188:191], v143 offset:3072
	ds_read_b128 v[192:195], v143 offset:4096
	ds_read_b128 v[196:199], v143 offset:5120
	ds_read_b128 v[200:203], v143 offset:6144
	ds_read_b128 v[204:207], v143 offset:7168
	s_add_u32 s2, s44, 0x100
	s_addc_u32 s3, s45, 0
	s_cmp_eq_u32 s60, 4
	s_cselect_b32 s47, s39, s3
	s_cselect_b32 s46, s38, s2
	s_cselect_b32 s5, s29, s59
	s_cselect_b32 s4, s57, s58
	s_add_i32 m0, s26, 0xc000
	s_nop 0
	global_load_lds_dwordx4 v136, s[44:45]
	s_add_i32 m0, s26, 0xe000
	s_nop 0
	global_load_lds_dwordx4 v138, s[44:45]
	s_waitcnt vmcnt(8)
	s_waitcnt lgkmcnt(0)
	s_barrier
	s_setprio 1
	s_waitcnt lgkmcnt(0)
	v_mfma_f32_16x16x32_bf16 v[126:129], v[144:147], v[176:179], v[126:129]
	v_mfma_f32_16x16x32_bf16 v[122:125], v[152:155], v[176:179], v[122:125]
	v_mfma_f32_16x16x32_bf16 v[118:121], v[144:147], v[184:187], v[118:121]
	v_mfma_f32_16x16x32_bf16 v[114:117], v[152:155], v[184:187], v[114:117]
	v_mfma_f32_16x16x32_bf16 v[106:109], v[144:147], v[192:195], v[106:109]
	v_mfma_f32_16x16x32_bf16 v[98:101], v[152:155], v[192:195], v[98:101]
	v_mfma_f32_16x16x32_bf16 v[90:93], v[144:147], v[200:203], v[90:93]
	v_mfma_f32_16x16x32_bf16 v[82:85], v[152:155], v[200:203], v[82:85]
	v_mfma_f32_16x16x32_bf16 v[126:129], v[148:151], v[180:183], v[126:129]
	v_mfma_f32_16x16x32_bf16 v[122:125], v[156:159], v[180:183], v[122:125]
	v_mfma_f32_16x16x32_bf16 v[118:121], v[148:151], v[188:191], v[118:121]
	v_mfma_f32_16x16x32_bf16 v[114:117], v[156:159], v[188:191], v[114:117]
	v_mfma_f32_16x16x32_bf16 v[106:109], v[148:151], v[196:199], v[106:109]
	v_mfma_f32_16x16x32_bf16 v[98:101], v[156:159], v[196:199], v[98:101]
	v_mfma_f32_16x16x32_bf16 v[90:93], v[148:151], v[204:207], v[90:93]
	v_mfma_f32_16x16x32_bf16 v[82:85], v[156:159], v[204:207], v[82:85]
	s_setprio 0
	s_setprio 1
	v_mfma_f32_16x16x32_bf16 v[110:113], v[160:163], v[176:179], v[110:113]
	v_mfma_f32_16x16x32_bf16 v[102:105], v[168:171], v[176:179], v[102:105]
	v_mfma_f32_16x16x32_bf16 v[94:97], v[160:163], v[184:187], v[94:97]
	v_mfma_f32_16x16x32_bf16 v[86:89], v[168:171], v[184:187], v[86:89]
	v_mfma_f32_16x16x32_bf16 v[78:81], v[160:163], v[192:195], v[78:81]
	v_mfma_f32_16x16x32_bf16 v[74:77], v[168:171], v[192:195], v[74:77]
	v_mfma_f32_16x16x32_bf16 v[70:73], v[160:163], v[200:203], v[70:73]
	v_mfma_f32_16x16x32_bf16 v[66:69], v[168:171], v[200:203], v[66:69]
	v_mfma_f32_16x16x32_bf16 v[110:113], v[164:167], v[180:183], v[110:113]
	v_mfma_f32_16x16x32_bf16 v[102:105], v[172:175], v[180:183], v[102:105]
	v_mfma_f32_16x16x32_bf16 v[94:97], v[164:167], v[188:191], v[94:97]
	v_mfma_f32_16x16x32_bf16 v[86:89], v[172:175], v[188:191], v[86:89]
	v_mfma_f32_16x16x32_bf16 v[78:81], v[164:167], v[196:199], v[78:81]
	s_setprio 2
	s_barrier
	v_mfma_f32_16x16x32_bf16 v[74:77], v[172:175], v[196:199], v[74:77]
	ds_read_b128 v[176:179], v143 offset:16384
	v_mfma_f32_16x16x32_bf16 v[70:73], v[164:167], v[204:207], v[70:73]
	ds_read_b128 v[180:183], v143 offset:17408
	ds_read_b128 v[184:187], v143 offset:18432
	v_mfma_f32_16x16x32_bf16 v[66:69], v[172:175], v[204:207], v[66:69]
	s_setprio 0
	s_add_i32 s6, s6, s25
	v_lshl_add_u64 v[208:209], s[4:5], 0, v[0:1]
	s_mov_b32 m0, s6
	ds_read_b128 v[188:191], v143 offset:19456
	ds_read_b128 v[192:195], v143 offset:20480
	ds_read_b128 v[196:199], v143 offset:21504
	ds_read_b128 v[200:203], v143 offset:22528
	ds_read_b128 v[204:207], v143 offset:23552
	global_load_lds_dwordx4 v[208:209], off
	s_add_i32 m0, s6, 0x2000
	s_add_u32 s14, s4, 0x20000
	v_lshl_add_u64 v[210:211], s[4:5], 0, v[130:131]
	s_addc_u32 s15, s5, 0
	s_add_i32 s6, s12, s25
	global_load_lds_dwordx4 v[210:211], off
	s_mov_b32 m0, s6
	v_lshl_add_u64 v[214:215], s[46:47], 0, v[132:133]
	global_load_lds_dwordx4 v0, s[14:15]
	s_add_i32 m0, s6, 0x2000
	s_nop 0
	global_load_lds_dwordx4 v130, s[14:15]
	v_lshl_add_u64 v[212:213], s[46:47], 0, v[134:135]
	s_mov_b32 m0, s26
	s_nop 0
	global_load_lds_dwordx4 v[212:213], off
	s_mov_b32 m0, s48
	s_nop 0
	global_load_lds_dwordx4 v[214:215], off
	s_waitcnt vmcnt(8)
	s_waitcnt lgkmcnt(0)
	s_barrier
; #define PG8_STAGE(bufoff, gbase, voff) do { _Pragma("unroll") for (int _i = 0; _i < 2; ++_i) \
;         __builtin_amdgcn_global_load_lds((const unsigned*)((const char*)(gbase) + (voff)[_i]), (LAS unsigned*)(lds + (bufoff) + ldsw + _i * 8192), 16, 0, 0); } while (0)
; #define PG8_LDA(dst, b, h) do { _Pragma("unroll") for (int m = 0; m < 4; ++m) _Pragma("unroll") for (int k = 0; k < 2; ++k) dst[m][k] = *(const LAS bf16x8*)(lds + PG8_SA(b, h) + aoff + m * 2048 + k * 1024); } while (0)
; #define PG8_LDB(dst, b, h) do { _Pragma("unroll") for (int n = 0; n < 2; ++n) _Pragma("unroll") for (int k = 0; k < 2; ++k) dst[n][k] = *(const LAS bf16x8*)(lds + PG8_SB(b, h) + boff + n * 2048 + k * 1024); } while (0)
; #define PG8_MMA(ai, bj, At, Bt) do { __builtin_amdgcn_s_setprio(1); _Pragma("unroll") for (int m = 0; m < 4; ++m) _Pragma("unroll") for (int n = 0; n < 2; ++n) _Pragma("unroll") for (int k = 0; k < 2; ++k) \
;         acc[ai][bj][m][n] = __builtin_amdgcn_mfma_f32_16x16x32_bf16(Bt[n][k], At[m][k], acc[ai][bj][m][n], 0, 0, 0); __builtin_amdgcn_s_setprio(0); } while (0)
; #define PG8_WAIT_V(n) asm volatile("s_waitcnt vmcnt(" #n ")" ::: "memory")
; #define PG8_WAIT_L(n) asm volatile("s_waitcnt lgkmcnt(" #n ")" ::: "memory")
; #define PG8_BAR __builtin_amdgcn_s_barrier()
; #define PG8_SCHED __builtin_amdgcn_sched_barrier(0)
; template <class Epi>
; __device__ __forceinline__ void gemm_phase(LAS unsigned char* lds, const Gemm g, const TileOrder& S, const Epi& E) {
;     ...
;             PG8_WAIT_V(8); PG8_WAIT_L(0); PG8_BAR; PG8_MMA(1, 0, At, B0); PG8_MMA(1, 1, At, B1); PG8_BAR; PG8_SCHED;
;             PG8_LDB(B0, 1, 0); PG8_LDB(B1, 1, 1); PG8_SCHED; PG8_LDA(At, 1, 0); PG8_STAGE(PG8_SA(0, 1), a2 + hstepA, voffA);
;             PG8_WAIT_V(8); PG8_WAIT_L(0); PG8_BAR; PG8_MMA(0, 0, At, B0); PG8_MMA(0, 1, At, B1); PG8_BAR; PG8_SCHED;
	s_setprio 1
	s_waitcnt lgkmcnt(0)
	v_mfma_f32_16x16x32_bf16 v[62:65], v[144:147], v[176:179], v[62:65]
	v_mfma_f32_16x16x32_bf16 v[58:61], v[152:155], v[176:179], v[58:61]
	v_mfma_f32_16x16x32_bf16 v[54:57], v[144:147], v[184:187], v[54:57]
	v_mfma_f32_16x16x32_bf16 v[50:53], v[152:155], v[184:187], v[50:53]
	v_mfma_f32_16x16x32_bf16 v[38:41], v[144:147], v[192:195], v[38:41]
	v_mfma_f32_16x16x32_bf16 v[34:37], v[152:155], v[192:195], v[34:37]
	v_mfma_f32_16x16x32_bf16 v[22:25], v[144:147], v[200:203], v[22:25]
	v_mfma_f32_16x16x32_bf16 v[18:21], v[152:155], v[200:203], v[18:21]
	v_mfma_f32_16x16x32_bf16 v[62:65], v[148:151], v[180:183], v[62:65]
	v_mfma_f32_16x16x32_bf16 v[58:61], v[156:159], v[180:183], v[58:61]
	v_mfma_f32_16x16x32_bf16 v[54:57], v[148:151], v[188:191], v[54:57]
	v_mfma_f32_16x16x32_bf16 v[50:53], v[156:159], v[188:191], v[50:53]
	v_mfma_f32_16x16x32_bf16 v[38:41], v[148:151], v[196:199], v[38:41]
	v_mfma_f32_16x16x32_bf16 v[34:37], v[156:159], v[196:199], v[34:37]
	v_mfma_f32_16x16x32_bf16 v[22:25], v[148:151], v[204:207], v[22:25]
	v_mfma_f32_16x16x32_bf16 v[18:21], v[156:159], v[204:207], v[18:21]
	s_setprio 0
	s_setprio 1
	v_mfma_f32_16x16x32_bf16 v[46:49], v[160:163], v[176:179], v[46:49]
	v_mfma_f32_16x16x32_bf16 v[42:45], v[168:171], v[176:179], v[42:45]
	v_mfma_f32_16x16x32_bf16 v[30:33], v[160:163], v[184:187], v[30:33]
	v_mfma_f32_16x16x32_bf16 v[26:29], v[168:171], v[184:187], v[26:29]
	v_mfma_f32_16x16x32_bf16 v[14:17], v[160:163], v[192:195], v[14:17]
	v_mfma_f32_16x16x32_bf16 v[10:13], v[168:171], v[192:195], v[10:13]
	v_mfma_f32_16x16x32_bf16 v[6:9], v[160:163], v[200:203], v[6:9]
	v_mfma_f32_16x16x32_bf16 v[2:5], v[168:171], v[200:203], v[2:5]
	v_mfma_f32_16x16x32_bf16 v[46:49], v[164:167], v[180:183], v[46:49]
	v_mfma_f32_16x16x32_bf16 v[42:45], v[172:175], v[180:183], v[42:45]
	v_mfma_f32_16x16x32_bf16 v[30:33], v[164:167], v[188:191], v[30:33]
	v_mfma_f32_16x16x32_bf16 v[26:29], v[172:175], v[188:191], v[26:29]
	v_mfma_f32_16x16x32_bf16 v[14:17], v[164:167], v[196:199], v[14:17]
	s_setprio 2
	s_barrier
	v_mfma_f32_16x16x32_bf16 v[10:13], v[172:175], v[196:199], v[10:13]
	s_mov_b32 s6, 0x18000
	s_mov_b32 s12, 0x1c000
	v_add_u32_e32 v156, s6, v142
	ds_read_b128 v[144:147], v156
	v_mfma_f32_16x16x32_bf16 v[6:9], v[164:167], v[204:207], v[6:9]
	ds_read_b128 v[148:151], v156 offset:1024
	ds_read_b128 v[152:155], v156 offset:2048
	v_mfma_f32_16x16x32_bf16 v[2:5], v[172:175], v[204:207], v[2:5]
	s_setprio 0
	v_add_u32_e32 v172, s12, v142
	ds_read_b128 v[156:159], v156 offset:3072
	ds_read_b128 v[160:163], v172
	ds_read_b128 v[164:167], v172 offset:1024
	ds_read_b128 v[168:171], v172 offset:2048
	ds_read_b128 v[172:175], v172 offset:3072
	s_add_u32 s14, s46, 0x30000
	s_addc_u32 s15, s47, 0
	s_mov_b32 m0, s49
	ds_read_b128 v[176:179], v143 offset:32768
	ds_read_b128 v[180:183], v143 offset:33792
	ds_read_b128 v[184:187], v143 offset:34816
	ds_read_b128 v[188:191], v143 offset:35840
	ds_read_b128 v[192:195], v143 offset:36864
	ds_read_b128 v[196:199], v143 offset:37888
	ds_read_b128 v[200:203], v143 offset:38912
	ds_read_b128 v[204:207], v143 offset:39936
	global_load_lds_dwordx4 v134, s[14:15]
	s_mov_b32 m0, s50
	s_nop 0
	global_load_lds_dwordx4 v132, s[14:15]
	s_waitcnt vmcnt(8)
	s_waitcnt lgkmcnt(0)
	s_barrier
	s_setprio 1
	s_waitcnt lgkmcnt(0)
	v_mfma_f32_16x16x32_bf16 v[126:129], v[144:147], v[176:179], v[126:129]
	v_mfma_f32_16x16x32_bf16 v[122:125], v[152:155], v[176:179], v[122:125]
	v_mfma_f32_16x16x32_bf16 v[118:121], v[144:147], v[184:187], v[118:121]
	v_mfma_f32_16x16x32_bf16 v[114:117], v[152:155], v[184:187], v[114:117]
	v_mfma_f32_16x16x32_bf16 v[106:109], v[144:147], v[192:195], v[106:109]
	v_mfma_f32_16x16x32_bf16 v[98:101], v[152:155], v[192:195], v[98:101]
	v_mfma_f32_16x16x32_bf16 v[90:93], v[144:147], v[200:203], v[90:93]
	v_mfma_f32_16x16x32_bf16 v[82:85], v[152:155], v[200:203], v[82:85]
	v_mfma_f32_16x16x32_bf16 v[126:129], v[148:151], v[180:183], v[126:129]
	v_mfma_f32_16x16x32_bf16 v[122:125], v[156:159], v[180:183], v[122:125]
	v_mfma_f32_16x16x32_bf16 v[118:121], v[148:151], v[188:191], v[118:121]
	v_mfma_f32_16x16x32_bf16 v[114:117], v[156:159], v[188:191], v[114:117]
	v_mfma_f32_16x16x32_bf16 v[106:109], v[148:151], v[196:199], v[106:109]
	v_mfma_f32_16x16x32_bf16 v[98:101], v[156:159], v[196:199], v[98:101]
	v_mfma_f32_16x16x32_bf16 v[90:93], v[148:151], v[204:207], v[90:93]
	v_mfma_f32_16x16x32_bf16 v[82:85], v[156:159], v[204:207], v[82:85]
	s_setprio 0
	s_setprio 1
	v_mfma_f32_16x16x32_bf16 v[110:113], v[160:163], v[176:179], v[110:113]
	v_mfma_f32_16x16x32_bf16 v[102:105], v[168:171], v[176:179], v[102:105]
	v_mfma_f32_16x16x32_bf16 v[94:97], v[160:163], v[184:187], v[94:97]
	v_mfma_f32_16x16x32_bf16 v[86:89], v[168:171], v[184:187], v[86:89]
	v_mfma_f32_16x16x32_bf16 v[78:81], v[160:163], v[192:195], v[78:81]
	v_mfma_f32_16x16x32_bf16 v[74:77], v[168:171], v[192:195], v[74:77]
	v_mfma_f32_16x16x32_bf16 v[70:73], v[160:163], v[200:203], v[70:73]
	v_mfma_f32_16x16x32_bf16 v[66:69], v[168:171], v[200:203], v[66:69]
	v_mfma_f32_16x16x32_bf16 v[110:113], v[164:167], v[180:183], v[110:113]
	v_mfma_f32_16x16x32_bf16 v[102:105], v[172:175], v[180:183], v[102:105]
	v_mfma_f32_16x16x32_bf16 v[94:97], v[164:167], v[188:191], v[94:97]
	v_mfma_f32_16x16x32_bf16 v[86:89], v[172:175], v[188:191], v[86:89]
	v_mfma_f32_16x16x32_bf16 v[78:81], v[164:167], v[196:199], v[78:81]
	s_setprio 2
	s_barrier
; #define PG8_STAGE(bufoff, gbase, voff) do { _Pragma("unroll") for (int _i = 0; _i < 2; ++_i) \
;         __builtin_amdgcn_global_load_lds((const unsigned*)((const char*)(gbase) + (voff)[_i]), (LAS unsigned*)(lds + (bufoff) + ldsw + _i * 8192), 16, 0, 0); } while (0)
; #define PG8_LDA(dst, b, h) do { _Pragma("unroll") for (int m = 0; m < 4; ++m) _Pragma("unroll") for (int k = 0; k < 2; ++k) dst[m][k] = *(const LAS bf16x8*)(lds + PG8_SA(b, h) + aoff + m * 2048 + k * 1024); } while (0)
; #define PG8_MMA(ai, bj, At, Bt) do { __builtin_amdgcn_s_setprio(1); _Pragma("unroll") for (int m = 0; m < 4; ++m) _Pragma("unroll") for (int n = 0; n < 2; ++n) _Pragma("unroll") for (int k = 0; k < 2; ++k) \
;         acc[ai][bj][m][n] = __builtin_amdgcn_mfma_f32_16x16x32_bf16(Bt[n][k], At[m][k], acc[ai][bj][m][n], 0, 0, 0); __builtin_amdgcn_s_setprio(0); } while (0)
; #define PG8_WAIT_V(n) asm volatile("s_waitcnt vmcnt(" #n ")" ::: "memory")
; #define PG8_WAIT_L(n) asm volatile("s_waitcnt lgkmcnt(" #n ")" ::: "memory")
; #define PG8_BAR __builtin_amdgcn_s_barrier()
; #define PG8_SCHED __builtin_amdgcn_sched_barrier(0)
; template <class Epi>
; __device__ __forceinline__ void gemm_phase(LAS unsigned char* lds, const Gemm g, const TileOrder& S, const Epi& E) {
;     ...
;             PG8_WAIT_V(8); PG8_WAIT_L(0); PG8_BAR; PG8_MMA(0, 0, At, B0); PG8_MMA(0, 1, At, B1); PG8_BAR; PG8_SCHED;
;             PG8_LDA(At, 1, 1); PG8_STAGE(PG8_SB(1, 0), b3, voffB); PG8_STAGE(PG8_SB(1, 1), b3 + hstepB, voffB); PG8_STAGE(PG8_SA(1, 0), a3, voffA);
;             PG8_WAIT_V(8); PG8_WAIT_L(0); PG8_BAR; PG8_MMA(1, 0, At, B0); PG8_MMA(1, 1, At, B1); PG8_BAR; PG8_SCHED;
;         }
;         if (wr == 0) PG8_BAR;
	v_mfma_f32_16x16x32_bf16 v[74:77], v[172:175], v[196:199], v[74:77]
	ds_read_b128 v[176:179], v143 offset:49152
	v_mfma_f32_16x16x32_bf16 v[70:73], v[164:167], v[204:207], v[70:73]
	ds_read_b128 v[180:183], v143 offset:50176
	ds_read_b128 v[184:187], v143 offset:51200
	v_mfma_f32_16x16x32_bf16 v[66:69], v[172:175], v[204:207], v[66:69]
	s_setprio 0
	s_add_i32 s6, s6, s25
	v_lshl_add_u64 v[208:209], v[208:209], 0, s[34:35]
	s_mov_b32 m0, s6
	ds_read_b128 v[188:191], v143 offset:52224
	ds_read_b128 v[192:195], v143 offset:53248
	ds_read_b128 v[196:199], v143 offset:54272
	ds_read_b128 v[200:203], v143 offset:55296
	ds_read_b128 v[204:207], v143 offset:56320
	global_load_lds_dwordx4 v[208:209], off
	s_add_i32 m0, s6, 0x2000
	s_add_u32 s4, s4, 0x20080
	v_lshl_add_u64 v[208:209], v[210:211], 0, s[34:35]
	s_addc_u32 s5, s5, 0
	s_add_i32 s6, s12, s25
	global_load_lds_dwordx4 v[208:209], off
	s_mov_b32 m0, s6
	s_nop 0
	global_load_lds_dwordx4 v0, s[4:5]
	v_lshl_add_u64 v[208:209], s[4:5], 0, v[130:131]
	s_add_i32 m0, s6, 0x2000
	s_nop 0
	global_load_lds_dwordx4 v[208:209], off
	v_lshl_add_u64 v[208:209], v[212:213], 0, s[34:35]
	s_mov_b32 m0, s51
	s_nop 0
	global_load_lds_dwordx4 v[208:209], off
	v_lshl_add_u64 v[208:209], v[214:215], 0, s[34:35]
	s_mov_b32 m0, s52
	s_nop 0
	global_load_lds_dwordx4 v[208:209], off
	s_waitcnt vmcnt(8)
	s_waitcnt lgkmcnt(0)
	s_barrier
	s_setprio 1
	s_waitcnt lgkmcnt(0)
	v_mfma_f32_16x16x32_bf16 v[62:65], v[144:147], v[176:179], v[62:65]
	v_mfma_f32_16x16x32_bf16 v[58:61], v[152:155], v[176:179], v[58:61]
	v_mfma_f32_16x16x32_bf16 v[54:57], v[144:147], v[184:187], v[54:57]
	v_mfma_f32_16x16x32_bf16 v[50:53], v[152:155], v[184:187], v[50:53]
	v_mfma_f32_16x16x32_bf16 v[38:41], v[144:147], v[192:195], v[38:41]
	v_mfma_f32_16x16x32_bf16 v[34:37], v[152:155], v[192:195], v[34:37]
	v_mfma_f32_16x16x32_bf16 v[22:25], v[144:147], v[200:203], v[22:25]
	v_mfma_f32_16x16x32_bf16 v[18:21], v[152:155], v[200:203], v[18:21]
	v_mfma_f32_16x16x32_bf16 v[62:65], v[148:151], v[180:183], v[62:65]
	v_mfma_f32_16x16x32_bf16 v[58:61], v[156:159], v[180:183], v[58:61]
	v_mfma_f32_16x16x32_bf16 v[54:57], v[148:151], v[188:191], v[54:57]
	v_mfma_f32_16x16x32_bf16 v[50:53], v[156:159], v[188:191], v[50:53]
	v_mfma_f32_16x16x32_bf16 v[38:41], v[148:151], v[196:199], v[38:41]
	v_mfma_f32_16x16x32_bf16 v[34:37], v[156:159], v[196:199], v[34:37]
	v_mfma_f32_16x16x32_bf16 v[22:25], v[148:151], v[204:207], v[22:25]
	v_mfma_f32_16x16x32_bf16 v[18:21], v[156:159], v[204:207], v[18:21]
	s_setprio 0
	s_setprio 1
	v_mfma_f32_16x16x32_bf16 v[46:49], v[160:163], v[176:179], v[46:49]
	v_mfma_f32_16x16x32_bf16 v[42:45], v[168:171], v[176:179], v[42:45]
	v_mfma_f32_16x16x32_bf16 v[30:33], v[160:163], v[184:187], v[30:33]
	v_mfma_f32_16x16x32_bf16 v[26:29], v[168:171], v[184:187], v[26:29]
	v_mfma_f32_16x16x32_bf16 v[14:17], v[160:163], v[192:195], v[14:17]
	v_mfma_f32_16x16x32_bf16 v[10:13], v[168:171], v[192:195], v[10:13]
	v_mfma_f32_16x16x32_bf16 v[6:9], v[160:163], v[200:203], v[6:9]
	v_mfma_f32_16x16x32_bf16 v[2:5], v[168:171], v[200:203], v[2:5]
	v_mfma_f32_16x16x32_bf16 v[46:49], v[164:167], v[180:183], v[46:49]
	v_mfma_f32_16x16x32_bf16 v[42:45], v[172:175], v[180:183], v[42:45]
	v_mfma_f32_16x16x32_bf16 v[30:33], v[164:167], v[188:191], v[30:33]
	v_mfma_f32_16x16x32_bf16 v[26:29], v[172:175], v[188:191], v[26:29]
	v_mfma_f32_16x16x32_bf16 v[14:17], v[164:167], v[196:199], v[14:17]
	v_mfma_f32_16x16x32_bf16 v[10:13], v[172:175], v[196:199], v[10:13]
	s_setprio 2
	s_barrier
	v_mfma_f32_16x16x32_bf16 v[6:9], v[164:167], v[204:207], v[6:9]
	v_mfma_f32_16x16x32_bf16 v[2:5], v[172:175], v[204:207], v[2:5]
	s_setprio 0
	s_add_i32 s60, s60, 2
	s_add_u32 s58, s58, 0x100
	s_addc_u32 s59, s59, 0
	s_cmp_gt_u32 s60, 5
	s_mov_b64 s[44:45], s[2:3]
	s_cbranch_scc0 .LBB0_457
	s_and_b64 vcc, exec, s[36:37]
	s_cbranch_vccz .LBB0_460
	s_barrier

; #define PG8_STAGE(bufoff, gbase, voff) do { _Pragma("unroll") for (int _i = 0; _i < 2; ++_i) \
;         __builtin_amdgcn_global_load_lds((const unsigned*)((const char*)(gbase) + (voff)[_i]), (LAS unsigned*)(lds + (bufoff) + ldsw + _i * 8192), 16, 0, 0); } while (0)
; #define PG8_LDA(dst, b, h) do { _Pragma("unroll") for (int m = 0; m < 4; ++m) _Pragma("unroll") for (int k = 0; k < 2; ++k) dst[m][k] = *(const LAS bf16x8*)(lds + PG8_SA(b, h) + aoff + m * 2048 + k * 1024); } while (0)
; #define PG8_LDB(dst, b, h) do { _Pragma("unroll") for (int n = 0; n < 2; ++n) _Pragma("unroll") for (int k = 0; k < 2; ++k) dst[n][k] = *(const LAS bf16x8*)(lds + PG8_SB(b, h) + boff + n * 2048 + k * 1024); } while (0)
; #define PG8_MMA(ai, bj, At, Bt) do { __builtin_amdgcn_s_setprio(1); _Pragma("unroll") for (int m = 0; m < 4; ++m) _Pragma("unroll") for (int n = 0; n < 2; ++n) _Pragma("unroll") for (int k = 0; k < 2; ++k) \
;         acc[ai][bj][m][n] = __builtin_amdgcn_mfma_f32_16x16x32_bf16(Bt[n][k], At[m][k], acc[ai][bj][m][n], 0, 0, 0); __builtin_amdgcn_s_setprio(0); } while (0)
; #define PG8_WAIT_V(n) asm volatile("s_waitcnt vmcnt(" #n ")" ::: "memory")
; #define PG8_WAIT_L(n) asm volatile("s_waitcnt lgkmcnt(" #n ")" ::: "memory")
; #define PG8_BAR __builtin_amdgcn_s_barrier()
; #define PG8_SCHED __builtin_amdgcn_sched_barrier(0)
; template <class Epi>
; __device__ __forceinline__ void gemm_phase(LAS unsigned char* lds, const Gemm g, const TileOrder& S, const Epi& E) {
;     ...
;             const bool last = (t == nt - 2);
;             const char* a1 = cA + (size_t)(t + 1) * kstepA;
;             const char* a2 = last ? nA : cA + (size_t)(t + 2) * kstepA; const char* b2 = last ? nB : cB + (size_t)(t + 2) * kstep;
;             const char* a3 = a2 + kstepA; const char* b3 = b2 + kstep;
;             PG8_LDB(B0, 0, 0); PG8_LDB(B1, 0, 1); PG8_SCHED; PG8_LDA(At, 0, 0); PG8_STAGE(PG8_SA(1, 1), a1 + hstepA, voffA);
;             PG8_WAIT_V(8); PG8_WAIT_L(0); PG8_BAR; PG8_MMA(0, 0, At, B0); PG8_MMA(0, 1, At, B1); PG8_BAR; PG8_SCHED;
;             PG8_LDA(At, 0, 1); PG8_STAGE(PG8_SB(0, 0), b2, voffB); PG8_STAGE(PG8_SB(0, 1), b2 + hstepB, voffB); PG8_STAGE(PG8_SA(0, 0), a2, voffA);
.LBB0_596:
	s_mov_b32 s6, 0x10000
	s_mov_b32 s12, 0x14000
	v_add_u32_e32 v58, s6, v224
	v_add_u32_e32 v102, s12, v224
	ds_read_b128 v[42:45], v58
	ds_read_b128 v[46:49], v58 offset:1024
	ds_read_b128 v[50:53], v58 offset:2048
	ds_read_b128 v[58:61], v58 offset:3072
	ds_read_b128 v[74:77], v102
	ds_read_b128 v[82:85], v102 offset:1024
	ds_read_b128 v[94:97], v102 offset:2048
	ds_read_b128 v[102:105], v102 offset:3072
	ds_read_b128 v[114:117], v225
	ds_read_b128 v[126:129], v225 offset:1024
	ds_read_b128 v[138:141], v225 offset:2048
	ds_read_b128 v[150:153], v225 offset:3072
	ds_read_b128 v[162:165], v225 offset:4096
	ds_read_b128 v[174:177], v225 offset:5120
	ds_read_b128 v[186:189], v225 offset:6144
	ds_read_b128 v[190:193], v225 offset:7168
	s_add_u32 s2, s28, 0x100
	s_addc_u32 s3, s29, 0
	s_cmp_eq_u32 s62, 8
	s_cselect_b32 s47, s1, s3
	s_cselect_b32 s46, s0, s2
	s_cselect_b32 s31, s45, s61
	s_cselect_b32 s30, s44, s60
	s_add_i32 m0, s26, 0xc000
	s_nop 0
	global_load_lds_dwordx4 v214, s[28:29]
	s_add_i32 m0, s26, 0xe000
	s_nop 0
	global_load_lds_dwordx4 v216, s[28:29]
	s_waitcnt vmcnt(8)
	s_waitcnt lgkmcnt(0)
	s_barrier
	s_setprio 1
	s_waitcnt lgkmcnt(0)
	v_mfma_f32_16x16x32_bf16 v[182:185], v[42:45], v[114:117], v[182:185]
	v_mfma_f32_16x16x32_bf16 v[178:181], v[50:53], v[114:117], v[178:181]
	v_mfma_f32_16x16x32_bf16 v[158:161], v[42:45], v[138:141], v[158:161]
	v_mfma_f32_16x16x32_bf16 v[154:157], v[50:53], v[138:141], v[154:157]
	v_mfma_f32_16x16x32_bf16 v[134:137], v[42:45], v[162:165], v[134:137]
	v_mfma_f32_16x16x32_bf16 v[130:133], v[50:53], v[162:165], v[130:133]
	v_mfma_f32_16x16x32_bf16 v[110:113], v[42:45], v[186:189], v[110:113]
	v_mfma_f32_16x16x32_bf16 v[106:109], v[50:53], v[186:189], v[106:109]
	v_mfma_f32_16x16x32_bf16 v[182:185], v[46:49], v[126:129], v[182:185]
	v_mfma_f32_16x16x32_bf16 v[178:181], v[58:61], v[126:129], v[178:181]
	v_mfma_f32_16x16x32_bf16 v[158:161], v[46:49], v[150:153], v[158:161]
	v_mfma_f32_16x16x32_bf16 v[154:157], v[58:61], v[150:153], v[154:157]
	v_mfma_f32_16x16x32_bf16 v[134:137], v[46:49], v[174:177], v[134:137]
	v_mfma_f32_16x16x32_bf16 v[130:133], v[58:61], v[174:177], v[130:133]
	v_mfma_f32_16x16x32_bf16 v[110:113], v[46:49], v[190:193], v[110:113]
	v_mfma_f32_16x16x32_bf16 v[106:109], v[58:61], v[190:193], v[106:109]
	s_setprio 0
	s_setprio 1
	v_mfma_f32_16x16x32_bf16 v[170:173], v[74:77], v[114:117], v[170:173]
	v_mfma_f32_16x16x32_bf16 v[114:117], v[94:97], v[114:117], v[166:169]
	v_mfma_f32_16x16x32_bf16 v[122:125], v[74:77], v[162:165], v[122:125]
	v_mfma_f32_16x16x32_bf16 v[118:121], v[94:97], v[162:165], v[118:121]
	v_mfma_f32_16x16x32_bf16 v[98:101], v[74:77], v[186:189], v[98:101]
	v_mfma_f32_16x16x32_bf16 v[90:93], v[94:97], v[186:189], v[90:93]
	v_mfma_f32_16x16x32_bf16 v[170:173], v[82:85], v[126:129], v[170:173]
	v_mfma_f32_16x16x32_bf16 v[114:117], v[102:105], v[126:129], v[114:117]
	v_mfma_f32_16x16x32_bf16 v[126:129], v[74:77], v[138:141], v[146:149]
	v_mfma_f32_16x16x32_bf16 v[138:141], v[94:97], v[138:141], v[142:145]
	v_mfma_f32_16x16x32_bf16 v[122:125], v[82:85], v[174:177], v[122:125]
	v_mfma_f32_16x16x32_bf16 v[118:121], v[102:105], v[174:177], v[118:121]
	v_mfma_f32_16x16x32_bf16 v[98:101], v[82:85], v[190:193], v[98:101]
	s_setprio 2
	s_barrier
	v_mfma_f32_16x16x32_bf16 v[90:93], v[102:105], v[190:193], v[90:93]
	ds_read_b128 v[142:145], v225 offset:16384
	v_mfma_f32_16x16x32_bf16 v[126:129], v[82:85], v[150:153], v[126:129]
	ds_read_b128 v[146:149], v225 offset:17408
	v_mfma_f32_16x16x32_bf16 v[138:141], v[102:105], v[150:153], v[138:141]
	s_setprio 0
	s_add_i32 s6, s6, s25
	v_lshl_add_u64 v[198:199], s[30:31], 0, v[0:1]
	s_mov_b32 m0, s6
	ds_read_b128 v[150:153], v225 offset:18432
	ds_read_b128 v[162:165], v225 offset:19456
	ds_read_b128 v[166:169], v225 offset:20480
	ds_read_b128 v[174:177], v225 offset:21504
	ds_read_b128 v[186:189], v225 offset:22528
	ds_read_b128 v[190:193], v225 offset:23552
	global_load_lds_dwordx4 v[198:199], off
	s_add_i32 m0, s6, 0x2000
	s_add_u32 s14, s30, 0x30000
	v_lshl_add_u64 v[200:201], s[30:31], 0, v[208:209]
	s_addc_u32 s15, s31, 0
	s_add_i32 s6, s12, s25
	global_load_lds_dwordx4 v[200:201], off
	s_mov_b32 m0, s6
	v_lshl_add_u64 v[202:203], s[46:47], 0, v[212:213]
	global_load_lds_dwordx4 v0, s[14:15]
	v_lshl_add_u64 v[194:195], s[14:15], 0, v[208:209]
	s_add_i32 m0, s6, 0x2000
	v_lshl_add_u64 v[204:205], s[46:47], 0, v[210:211]
	global_load_lds_dwordx4 v[194:195], off
	s_mov_b32 m0, s26
	s_nop 0
	global_load_lds_dwordx4 v[202:203], off
	s_mov_b32 m0, s48
	s_nop 0
	global_load_lds_dwordx4 v[204:205], off
	s_waitcnt vmcnt(8)
	s_waitcnt lgkmcnt(0)
	s_barrier
; #define PG8_STAGE(bufoff, gbase, voff) do { _Pragma("unroll") for (int _i = 0; _i < 2; ++_i) \
;         __builtin_amdgcn_global_load_lds((const unsigned*)((const char*)(gbase) + (voff)[_i]), (LAS unsigned*)(lds + (bufoff) + ldsw + _i * 8192), 16, 0, 0); } while (0)
; #define PG8_LDA(dst, b, h) do { _Pragma("unroll") for (int m = 0; m < 4; ++m) _Pragma("unroll") for (int k = 0; k < 2; ++k) dst[m][k] = *(const LAS bf16x8*)(lds + PG8_SA(b, h) + aoff + m * 2048 + k * 1024); } while (0)
; #define PG8_LDB(dst, b, h) do { _Pragma("unroll") for (int n = 0; n < 2; ++n) _Pragma("unroll") for (int k = 0; k < 2; ++k) dst[n][k] = *(const LAS bf16x8*)(lds + PG8_SB(b, h) + boff + n * 2048 + k * 1024); } while (0)
; #define PG8_MMA(ai, bj, At, Bt) do { __builtin_amdgcn_s_setprio(1); _Pragma("unroll") for (int m = 0; m < 4; ++m) _Pragma("unroll") for (int n = 0; n < 2; ++n) _Pragma("unroll") for (int k = 0; k < 2; ++k) \
;         acc[ai][bj][m][n] = __builtin_amdgcn_mfma_f32_16x16x32_bf16(Bt[n][k], At[m][k], acc[ai][bj][m][n], 0, 0, 0); __builtin_amdgcn_s_setprio(0); } while (0)
; #define PG8_WAIT_V(n) asm volatile("s_waitcnt vmcnt(" #n ")" ::: "memory")
; #define PG8_WAIT_L(n) asm volatile("s_waitcnt lgkmcnt(" #n ")" ::: "memory")
; #define PG8_BAR __builtin_amdgcn_s_barrier()
; #define PG8_SCHED __builtin_amdgcn_sched_barrier(0)
; template <class Epi>
; __device__ __forceinline__ void gemm_phase(LAS unsigned char* lds, const Gemm g, const TileOrder& S, const Epi& E) {
;     ...
;             PG8_WAIT_V(8); PG8_WAIT_L(0); PG8_BAR; PG8_MMA(1, 0, At, B0); PG8_MMA(1, 1, At, B1); PG8_BAR; PG8_SCHED;
;             PG8_LDB(B0, 1, 0); PG8_LDB(B1, 1, 1); PG8_SCHED; PG8_LDA(At, 1, 0); PG8_STAGE(PG8_SA(0, 1), a2 + hstepA, voffA);
;             PG8_WAIT_V(8); PG8_WAIT_L(0); PG8_BAR; PG8_MMA(0, 0, At, B0); PG8_MMA(0, 1, At, B1); PG8_BAR; PG8_SCHED;
	s_setprio 1
	s_waitcnt lgkmcnt(0)
	v_mfma_f32_16x16x32_bf16 v[86:89], v[42:45], v[142:145], v[86:89]
	v_mfma_f32_16x16x32_bf16 v[78:81], v[50:53], v[142:145], v[78:81]
	v_mfma_f32_16x16x32_bf16 v[62:65], v[42:45], v[150:153], v[62:65]
	v_mfma_f32_16x16x32_bf16 v[54:57], v[50:53], v[150:153], v[54:57]
	v_mfma_f32_16x16x32_bf16 v[30:33], v[42:45], v[166:169], v[30:33]
	v_mfma_f32_16x16x32_bf16 v[26:29], v[50:53], v[166:169], v[26:29]
	v_mfma_f32_16x16x32_bf16 v[14:17], v[42:45], v[186:189], v[14:17]
	v_mfma_f32_16x16x32_bf16 v[10:13], v[50:53], v[186:189], v[10:13]
	v_mfma_f32_16x16x32_bf16 v[86:89], v[46:49], v[146:149], v[86:89]
	v_mfma_f32_16x16x32_bf16 v[78:81], v[58:61], v[146:149], v[78:81]
	v_mfma_f32_16x16x32_bf16 v[62:65], v[46:49], v[162:165], v[62:65]
	v_mfma_f32_16x16x32_bf16 v[54:57], v[58:61], v[162:165], v[54:57]
	v_mfma_f32_16x16x32_bf16 v[30:33], v[46:49], v[174:177], v[30:33]
	v_mfma_f32_16x16x32_bf16 v[26:29], v[58:61], v[174:177], v[26:29]
	v_mfma_f32_16x16x32_bf16 v[14:17], v[46:49], v[190:193], v[14:17]
	v_mfma_f32_16x16x32_bf16 v[10:13], v[58:61], v[190:193], v[10:13]
	s_setprio 0
	s_setprio 1
	v_mfma_f32_16x16x32_bf16 v[38:41], v[74:77], v[150:153], v[38:41]
	v_mfma_f32_16x16x32_bf16 v[34:37], v[94:97], v[150:153], v[34:37]
	v_mfma_f32_16x16x32_bf16 v[22:25], v[74:77], v[166:169], v[22:25]
	v_mfma_f32_16x16x32_bf16 v[18:21], v[94:97], v[166:169], v[18:21]
	v_mfma_f32_16x16x32_bf16 v[6:9], v[74:77], v[186:189], v[6:9]
	v_mfma_f32_16x16x32_bf16 v[2:5], v[94:97], v[186:189], v[2:5]
	v_mfma_f32_16x16x32_bf16 v[42:45], v[74:77], v[142:145], v[70:73]
	v_mfma_f32_16x16x32_bf16 v[46:49], v[94:97], v[142:145], v[66:69]
	v_mfma_f32_16x16x32_bf16 v[38:41], v[82:85], v[162:165], v[38:41]
	v_mfma_f32_16x16x32_bf16 v[34:37], v[102:105], v[162:165], v[34:37]
	v_mfma_f32_16x16x32_bf16 v[22:25], v[82:85], v[174:177], v[22:25]
	v_mfma_f32_16x16x32_bf16 v[18:21], v[102:105], v[174:177], v[18:21]
	v_mfma_f32_16x16x32_bf16 v[6:9], v[82:85], v[190:193], v[6:9]
	s_setprio 2
	s_barrier
	v_mfma_f32_16x16x32_bf16 v[2:5], v[102:105], v[190:193], v[2:5]
	s_mov_b32 s6, 0x18000
	s_mov_b32 s12, 0x1c000
	v_add_u32_e32 v70, s6, v224
	ds_read_b128 v[50:53], v70
	v_mfma_f32_16x16x32_bf16 v[42:45], v[82:85], v[146:149], v[42:45]
	ds_read_b128 v[58:61], v70 offset:1024
	ds_read_b128 v[66:69], v70 offset:2048
	v_mfma_f32_16x16x32_bf16 v[46:49], v[102:105], v[146:149], v[46:49]
	s_setprio 0
	v_add_u32_e32 v102, s12, v224
	ds_read_b128 v[70:73], v70 offset:3072
	ds_read_b128 v[74:77], v102
	ds_read_b128 v[82:85], v102 offset:1024
	ds_read_b128 v[94:97], v102 offset:2048
	ds_read_b128 v[102:105], v102 offset:3072
	s_add_u32 s14, s46, 0x30000
	s_addc_u32 s15, s47, 0
	s_mov_b32 m0, s49
	ds_read_b128 v[142:145], v225 offset:32768
	ds_read_b128 v[146:149], v225 offset:33792
	ds_read_b128 v[150:153], v225 offset:34816
	ds_read_b128 v[162:165], v225 offset:35840
	ds_read_b128 v[174:177], v225 offset:36864
	ds_read_b128 v[186:189], v225 offset:37888
	ds_read_b128 v[190:193], v225 offset:38912
	ds_read_b128 v[194:197], v225 offset:39936
	global_load_lds_dwordx4 v212, s[14:15]
	s_mov_b32 m0, s50
	s_nop 0
	global_load_lds_dwordx4 v210, s[14:15]
	s_waitcnt vmcnt(8)
	s_waitcnt lgkmcnt(0)
	s_barrier
	s_setprio 1
	s_waitcnt lgkmcnt(0)
	v_mfma_f32_16x16x32_bf16 v[166:169], v[50:53], v[142:145], v[182:185]
	v_mfma_f32_16x16x32_bf16 v[182:185], v[58:61], v[146:149], v[166:169]
	v_mfma_f32_16x16x32_bf16 v[166:169], v[66:69], v[142:145], v[178:181]
	v_mfma_f32_16x16x32_bf16 v[158:161], v[50:53], v[150:153], v[158:161]
	v_mfma_f32_16x16x32_bf16 v[154:157], v[66:69], v[150:153], v[154:157]
	v_mfma_f32_16x16x32_bf16 v[134:137], v[50:53], v[174:177], v[134:137]
	v_mfma_f32_16x16x32_bf16 v[130:133], v[66:69], v[174:177], v[130:133]
	v_mfma_f32_16x16x32_bf16 v[110:113], v[50:53], v[190:193], v[110:113]
	v_mfma_f32_16x16x32_bf16 v[106:109], v[66:69], v[190:193], v[106:109]
	v_mfma_f32_16x16x32_bf16 v[178:181], v[70:73], v[146:149], v[166:169]
	v_mfma_f32_16x16x32_bf16 v[158:161], v[58:61], v[162:165], v[158:161]
	v_mfma_f32_16x16x32_bf16 v[154:157], v[70:73], v[162:165], v[154:157]
	v_mfma_f32_16x16x32_bf16 v[134:137], v[58:61], v[186:189], v[134:137]
	v_mfma_f32_16x16x32_bf16 v[130:133], v[70:73], v[186:189], v[130:133]
	v_mfma_f32_16x16x32_bf16 v[110:113], v[58:61], v[194:197], v[110:113]
	v_mfma_f32_16x16x32_bf16 v[106:109], v[70:73], v[194:197], v[106:109]
	s_setprio 0
	s_setprio 1
	v_mfma_f32_16x16x32_bf16 v[166:169], v[74:77], v[142:145], v[170:173]
	v_mfma_f32_16x16x32_bf16 v[114:117], v[94:97], v[142:145], v[114:117]
	v_mfma_f32_16x16x32_bf16 v[170:173], v[82:85], v[146:149], v[166:169]
	v_mfma_f32_16x16x32_bf16 v[166:169], v[102:105], v[146:149], v[114:117]
	v_mfma_f32_16x16x32_bf16 v[114:117], v[74:77], v[150:153], v[126:129]
	v_mfma_f32_16x16x32_bf16 v[146:149], v[82:85], v[162:165], v[114:117]
	v_mfma_f32_16x16x32_bf16 v[114:117], v[94:97], v[150:153], v[138:141]
	v_mfma_f32_16x16x32_bf16 v[142:145], v[102:105], v[162:165], v[114:117]
	v_mfma_f32_16x16x32_bf16 v[114:117], v[74:77], v[174:177], v[122:125]
	v_mfma_f32_16x16x32_bf16 v[122:125], v[82:85], v[186:189], v[114:117]
	v_mfma_f32_16x16x32_bf16 v[114:117], v[94:97], v[174:177], v[118:121]
	v_mfma_f32_16x16x32_bf16 v[98:101], v[74:77], v[190:193], v[98:101]
	v_mfma_f32_16x16x32_bf16 v[90:93], v[94:97], v[190:193], v[90:93]
	s_setprio 2
	s_barrier
; #define PG8_STAGE(bufoff, gbase, voff) do { _Pragma("unroll") for (int _i = 0; _i < 2; ++_i) \
;         __builtin_amdgcn_global_load_lds((const unsigned*)((const char*)(gbase) + (voff)[_i]), (LAS unsigned*)(lds + (bufoff) + ldsw + _i * 8192), 16, 0, 0); } while (0)
; #define PG8_LDA(dst, b, h) do { _Pragma("unroll") for (int m = 0; m < 4; ++m) _Pragma("unroll") for (int k = 0; k < 2; ++k) dst[m][k] = *(const LAS bf16x8*)(lds + PG8_SA(b, h) + aoff + m * 2048 + k * 1024); } while (0)
; #define PG8_MMA(ai, bj, At, Bt) do { __builtin_amdgcn_s_setprio(1); _Pragma("unroll") for (int m = 0; m < 4; ++m) _Pragma("unroll") for (int n = 0; n < 2; ++n) _Pragma("unroll") for (int k = 0; k < 2; ++k) \
;         acc[ai][bj][m][n] = __builtin_amdgcn_mfma_f32_16x16x32_bf16(Bt[n][k], At[m][k], acc[ai][bj][m][n], 0, 0, 0); __builtin_amdgcn_s_setprio(0); } while (0)
; #define PG8_WAIT_V(n) asm volatile("s_waitcnt vmcnt(" #n ")" ::: "memory")
; #define PG8_WAIT_L(n) asm volatile("s_waitcnt lgkmcnt(" #n ")" ::: "memory")
; #define PG8_BAR __builtin_amdgcn_s_barrier()
; #define PG8_SCHED __builtin_amdgcn_sched_barrier(0)
; template <class Epi>
; __device__ __forceinline__ void gemm_phase(LAS unsigned char* lds, const Gemm g, const TileOrder& S, const Epi& E) {
;     ...
;             PG8_WAIT_V(8); PG8_WAIT_L(0); PG8_BAR; PG8_MMA(0, 0, At, B0); PG8_MMA(0, 1, At, B1); PG8_BAR; PG8_SCHED;
;             PG8_LDA(At, 1, 1); PG8_STAGE(PG8_SB(1, 0), b3, voffB); PG8_STAGE(PG8_SB(1, 1), b3 + hstepB, voffB); PG8_STAGE(PG8_SA(1, 0), a3, voffA);
;             PG8_WAIT_V(8); PG8_WAIT_L(0); PG8_BAR; PG8_MMA(1, 0, At, B0); PG8_MMA(1, 1, At, B1); PG8_BAR; PG8_SCHED;
;         }
;         if (wr == 0) PG8_BAR;
	v_mfma_f32_16x16x32_bf16 v[118:121], v[102:105], v[186:189], v[114:117]
	ds_read_b128 v[114:117], v225 offset:49152
	v_mfma_f32_16x16x32_bf16 v[98:101], v[82:85], v[194:197], v[98:101]
	ds_read_b128 v[126:129], v225 offset:50176
	ds_read_b128 v[138:141], v225 offset:51200
	v_mfma_f32_16x16x32_bf16 v[90:93], v[102:105], v[194:197], v[90:93]
	s_setprio 0
	s_add_i32 s6, s6, s25
	v_lshl_add_u64 v[194:195], v[198:199], 0, s[34:35]
	s_mov_b32 m0, s6
	ds_read_b128 v[150:153], v225 offset:52224
	ds_read_b128 v[162:165], v225 offset:53248
	ds_read_b128 v[174:177], v225 offset:54272
	ds_read_b128 v[186:189], v225 offset:55296
	ds_read_b128 v[190:193], v225 offset:56320
	global_load_lds_dwordx4 v[194:195], off
	s_add_i32 m0, s6, 0x2000
	s_add_u32 s14, s30, 0x30080
	v_lshl_add_u64 v[194:195], v[200:201], 0, s[34:35]
	s_addc_u32 s15, s31, 0
	s_add_i32 s6, s12, s25
	global_load_lds_dwordx4 v[194:195], off
	s_mov_b32 m0, s6
	s_nop 0
	global_load_lds_dwordx4 v0, s[14:15]
	v_lshl_add_u64 v[194:195], s[14:15], 0, v[208:209]
	s_add_i32 m0, s6, 0x2000
	s_nop 0
	global_load_lds_dwordx4 v[194:195], off
	v_lshl_add_u64 v[194:195], v[202:203], 0, s[34:35]
	s_mov_b32 m0, s51
	s_nop 0
	global_load_lds_dwordx4 v[194:195], off
	v_lshl_add_u64 v[194:195], v[204:205], 0, s[34:35]
	s_mov_b32 m0, s52
	s_nop 0
	global_load_lds_dwordx4 v[194:195], off
	s_waitcnt vmcnt(8)
	s_waitcnt lgkmcnt(0)
	s_barrier
	s_setprio 1
	s_waitcnt lgkmcnt(0)
	v_mfma_f32_16x16x32_bf16 v[86:89], v[50:53], v[114:117], v[86:89]
	v_mfma_f32_16x16x32_bf16 v[78:81], v[66:69], v[114:117], v[78:81]
	v_mfma_f32_16x16x32_bf16 v[62:65], v[50:53], v[138:141], v[62:65]
	v_mfma_f32_16x16x32_bf16 v[54:57], v[66:69], v[138:141], v[54:57]
	v_mfma_f32_16x16x32_bf16 v[30:33], v[50:53], v[162:165], v[30:33]
	v_mfma_f32_16x16x32_bf16 v[26:29], v[66:69], v[162:165], v[26:29]
	v_mfma_f32_16x16x32_bf16 v[14:17], v[50:53], v[186:189], v[14:17]
	v_mfma_f32_16x16x32_bf16 v[10:13], v[66:69], v[186:189], v[10:13]
	v_mfma_f32_16x16x32_bf16 v[86:89], v[58:61], v[126:129], v[86:89]
	v_mfma_f32_16x16x32_bf16 v[78:81], v[70:73], v[126:129], v[78:81]
	v_mfma_f32_16x16x32_bf16 v[62:65], v[58:61], v[150:153], v[62:65]
	v_mfma_f32_16x16x32_bf16 v[54:57], v[70:73], v[150:153], v[54:57]
	v_mfma_f32_16x16x32_bf16 v[30:33], v[58:61], v[174:177], v[30:33]
	v_mfma_f32_16x16x32_bf16 v[26:29], v[70:73], v[174:177], v[26:29]
	v_mfma_f32_16x16x32_bf16 v[14:17], v[58:61], v[190:193], v[14:17]
	v_mfma_f32_16x16x32_bf16 v[10:13], v[70:73], v[190:193], v[10:13]
	s_setprio 0
	s_setprio 1
	v_mfma_f32_16x16x32_bf16 v[42:45], v[74:77], v[114:117], v[42:45]
	v_mfma_f32_16x16x32_bf16 v[70:73], v[82:85], v[126:129], v[42:45]
	v_mfma_f32_16x16x32_bf16 v[42:45], v[94:97], v[114:117], v[46:49]
	v_mfma_f32_16x16x32_bf16 v[38:41], v[74:77], v[138:141], v[38:41]
	v_mfma_f32_16x16x32_bf16 v[34:37], v[94:97], v[138:141], v[34:37]
	v_mfma_f32_16x16x32_bf16 v[22:25], v[74:77], v[162:165], v[22:25]
	v_mfma_f32_16x16x32_bf16 v[18:21], v[94:97], v[162:165], v[18:21]
	v_mfma_f32_16x16x32_bf16 v[6:9], v[74:77], v[186:189], v[6:9]
	v_mfma_f32_16x16x32_bf16 v[2:5], v[94:97], v[186:189], v[2:5]
	v_mfma_f32_16x16x32_bf16 v[66:69], v[102:105], v[126:129], v[42:45]
	v_mfma_f32_16x16x32_bf16 v[38:41], v[82:85], v[150:153], v[38:41]
	v_mfma_f32_16x16x32_bf16 v[34:37], v[102:105], v[150:153], v[34:37]
	v_mfma_f32_16x16x32_bf16 v[22:25], v[82:85], v[174:177], v[22:25]
	v_mfma_f32_16x16x32_bf16 v[18:21], v[102:105], v[174:177], v[18:21]
	s_setprio 2
	s_barrier
	v_mfma_f32_16x16x32_bf16 v[6:9], v[82:85], v[190:193], v[6:9]
	v_mfma_f32_16x16x32_bf16 v[2:5], v[102:105], v[190:193], v[2:5]
	s_setprio 0
	s_add_i32 s62, s62, 2
	s_add_u32 s60, s60, 0x100
	s_addc_u32 s61, s61, 0
	s_cmp_gt_u32 s62, 9
	s_mov_b64 s[28:29], s[2:3]
	s_cbranch_scc0 .LBB0_596
	s_and_b64 vcc, exec, s[42:43]
	s_cbranch_vccz .LBB0_599
	s_barrier

; #define PG8_STAGE(bufoff, gbase, voff) do { _Pragma("unroll") for (int _i = 0; _i < 2; ++_i) \
;         __builtin_amdgcn_global_load_lds((const unsigned*)((const char*)(gbase) + (voff)[_i]), (LAS unsigned*)(lds + (bufoff) + ldsw + _i * 8192), 16, 0, 0); } while (0)
; #define PG8_LDA(dst, b, h) do { _Pragma("unroll") for (int m = 0; m < 4; ++m) _Pragma("unroll") for (int k = 0; k < 2; ++k) dst[m][k] = *(const LAS bf16x8*)(lds + PG8_SA(b, h) + aoff + m * 2048 + k * 1024); } while (0)
; #define PG8_LDB(dst, b, h) do { _Pragma("unroll") for (int n = 0; n < 2; ++n) _Pragma("unroll") for (int k = 0; k < 2; ++k) dst[n][k] = *(const LAS bf16x8*)(lds + PG8_SB(b, h) + boff + n * 2048 + k * 1024); } while (0)
; #define PG8_MMA(ai, bj, At, Bt) do { __builtin_amdgcn_s_setprio(1); _Pragma("unroll") for (int m = 0; m < 4; ++m) _Pragma("unroll") for (int n = 0; n < 2; ++n) _Pragma("unroll") for (int k = 0; k < 2; ++k) \
;         acc[ai][bj][m][n] = __builtin_amdgcn_mfma_f32_16x16x32_bf16(Bt[n][k], At[m][k], acc[ai][bj][m][n], 0, 0, 0); __builtin_amdgcn_s_setprio(0); } while (0)
; #define PG8_WAIT_V(n) asm volatile("s_waitcnt vmcnt(" #n ")" ::: "memory")
; #define PG8_WAIT_L(n) asm volatile("s_waitcnt lgkmcnt(" #n ")" ::: "memory")
; #define PG8_BAR __builtin_amdgcn_s_barrier()
; #define PG8_SCHED __builtin_amdgcn_sched_barrier(0)
; template <class Epi>
; __device__ __forceinline__ void gemm_phase(LAS unsigned char* lds, const Gemm g, const TileOrder& S, const Epi& E) {
;     ...
;             const bool last = (t == nt - 2);
;             const char* a1 = cA + (size_t)(t + 1) * kstepA;
;             const char* a2 = last ? nA : cA + (size_t)(t + 2) * kstepA; const char* b2 = last ? nB : cB + (size_t)(t + 2) * kstep;
;             const char* a3 = a2 + kstepA; const char* b3 = b2 + kstep;
;             PG8_LDB(B0, 0, 0); PG8_LDB(B1, 0, 1); PG8_SCHED; PG8_LDA(At, 0, 0); PG8_STAGE(PG8_SA(1, 1), a1 + hstepA, voffA);
;             PG8_WAIT_V(8); PG8_WAIT_L(0); PG8_BAR; PG8_MMA(0, 0, At, B0); PG8_MMA(0, 1, At, B1); PG8_BAR; PG8_SCHED;
;             PG8_LDA(At, 0, 1); PG8_STAGE(PG8_SB(0, 0), b2, voffB); PG8_STAGE(PG8_SB(0, 1), b2 + hstepB, voffB); PG8_STAGE(PG8_SA(0, 0), a2, voffA);
.LBB0_668:
	s_mov_b32 s6, 0x10000
	s_mov_b32 s12, 0x14000
	v_add_u32_e32 v142, s6, v184
	v_add_u32_e32 v168, s12, v184
	ds_read_b128 v[130:133], v142
	ds_read_b128 v[134:137], v142 offset:1024
	ds_read_b128 v[138:141], v142 offset:2048
	ds_read_b128 v[142:145], v142 offset:3072
	ds_read_b128 v[146:149], v168
	ds_read_b128 v[150:153], v168 offset:1024
	ds_read_b128 v[164:167], v168 offset:2048
	ds_read_b128 v[168:171], v168 offset:3072
	ds_read_b128 v[172:175], v185
	ds_read_b128 v[176:179], v185 offset:1024
	ds_read_b128 v[186:189], v185 offset:2048
	ds_read_b128 v[190:193], v185 offset:3072
	ds_read_b128 v[194:197], v185 offset:4096
	ds_read_b128 v[198:201], v185 offset:5120
	ds_read_b128 v[202:205], v185 offset:6144
	ds_read_b128 v[206:209], v185 offset:7168
	s_add_u32 s2, s4, 0xfff80080
	s_addc_u32 s3, s5, -1
	s_cmp_eq_u32 s66, 28
	s_cselect_b32 s29, s45, s3
	s_cselect_b32 s28, s62, s2
	s_cselect_b32 s3, s43, s65
	s_cselect_b32 s2, s63, s64
	s_add_i32 m0, s50, 0xc000
	s_nop 0
	global_load_lds_dwordx4 v160, s[4:5]
	s_add_i32 m0, s50, 0xe000
	s_nop 0
	global_load_lds_dwordx4 v162, s[4:5]
	s_waitcnt vmcnt(8)
	s_waitcnt lgkmcnt(0)
	s_barrier
	s_setprio 1
	s_waitcnt lgkmcnt(0)
	v_mfma_f32_16x16x32_bf16 v[122:125], v[130:133], v[172:175], v[122:125]
	v_mfma_f32_16x16x32_bf16 v[118:121], v[138:141], v[172:175], v[118:121]
	v_mfma_f32_16x16x32_bf16 v[110:113], v[130:133], v[186:189], v[110:113]
	v_mfma_f32_16x16x32_bf16 v[102:105], v[138:141], v[186:189], v[102:105]
	v_mfma_f32_16x16x32_bf16 v[94:97], v[130:133], v[194:197], v[94:97]
	v_mfma_f32_16x16x32_bf16 v[86:89], v[138:141], v[194:197], v[86:89]
	v_mfma_f32_16x16x32_bf16 v[78:81], v[130:133], v[202:205], v[78:81]
	v_mfma_f32_16x16x32_bf16 v[70:73], v[138:141], v[202:205], v[70:73]
	v_mfma_f32_16x16x32_bf16 v[122:125], v[134:137], v[176:179], v[122:125]
	v_mfma_f32_16x16x32_bf16 v[118:121], v[142:145], v[176:179], v[118:121]
	v_mfma_f32_16x16x32_bf16 v[110:113], v[134:137], v[190:193], v[110:113]
	v_mfma_f32_16x16x32_bf16 v[102:105], v[142:145], v[190:193], v[102:105]
	v_mfma_f32_16x16x32_bf16 v[94:97], v[134:137], v[198:201], v[94:97]
	v_mfma_f32_16x16x32_bf16 v[86:89], v[142:145], v[198:201], v[86:89]
	v_mfma_f32_16x16x32_bf16 v[78:81], v[134:137], v[206:209], v[78:81]
	v_mfma_f32_16x16x32_bf16 v[70:73], v[142:145], v[206:209], v[70:73]
	s_setprio 0
	s_setprio 1
	v_mfma_f32_16x16x32_bf16 v[114:117], v[146:149], v[172:175], v[114:117]
	v_mfma_f32_16x16x32_bf16 v[126:129], v[164:167], v[172:175], v[126:129]
	v_mfma_f32_16x16x32_bf16 v[106:109], v[146:149], v[186:189], v[106:109]
	v_mfma_f32_16x16x32_bf16 v[98:101], v[164:167], v[186:189], v[98:101]
	v_mfma_f32_16x16x32_bf16 v[90:93], v[146:149], v[194:197], v[90:93]
	v_mfma_f32_16x16x32_bf16 v[82:85], v[164:167], v[194:197], v[82:85]
	v_mfma_f32_16x16x32_bf16 v[74:77], v[146:149], v[202:205], v[74:77]
	v_mfma_f32_16x16x32_bf16 v[66:69], v[164:167], v[202:205], v[66:69]
	v_mfma_f32_16x16x32_bf16 v[114:117], v[150:153], v[176:179], v[114:117]
	v_mfma_f32_16x16x32_bf16 v[126:129], v[168:171], v[176:179], v[126:129]
	v_mfma_f32_16x16x32_bf16 v[106:109], v[150:153], v[190:193], v[106:109]
	v_mfma_f32_16x16x32_bf16 v[98:101], v[168:171], v[190:193], v[98:101]
	v_mfma_f32_16x16x32_bf16 v[90:93], v[150:153], v[198:201], v[90:93]
	s_setprio 2
	s_barrier
	v_mfma_f32_16x16x32_bf16 v[82:85], v[168:171], v[198:201], v[82:85]
	ds_read_b128 v[172:175], v185 offset:16384
	v_mfma_f32_16x16x32_bf16 v[74:77], v[150:153], v[206:209], v[74:77]
	ds_read_b128 v[176:179], v185 offset:17408
	ds_read_b128 v[186:189], v185 offset:18432
	v_mfma_f32_16x16x32_bf16 v[66:69], v[168:171], v[206:209], v[66:69]
	s_setprio 0
	s_add_i32 s6, s6, s31
	v_lshl_add_u64 v[180:181], s[2:3], 0, v[0:1]
	s_mov_b32 m0, s6
	ds_read_b128 v[190:193], v185 offset:19456
	ds_read_b128 v[194:197], v185 offset:20480
	ds_read_b128 v[198:201], v185 offset:21504
	ds_read_b128 v[202:205], v185 offset:22528
	ds_read_b128 v[206:209], v185 offset:23552
	global_load_lds_dwordx4 v[180:181], off
	s_add_i32 m0, s6, 0x2000
	s_add_u32 s14, s2, 0x80000
	v_lshl_add_u64 v[210:211], s[2:3], 0, v[154:155]
	s_addc_u32 s15, s3, 0
	s_add_i32 s6, s12, s31
	global_load_lds_dwordx4 v[210:211], off
	s_mov_b32 m0, s6
	v_lshl_add_u64 v[214:215], s[28:29], 0, v[156:157]
	global_load_lds_dwordx4 v0, s[14:15]
	s_add_i32 m0, s6, 0x2000
	s_nop 0
	global_load_lds_dwordx4 v154, s[14:15]
	v_lshl_add_u64 v[212:213], s[28:29], 0, v[158:159]
	s_mov_b32 m0, s50
	s_nop 0
	global_load_lds_dwordx4 v[212:213], off
	s_mov_b32 m0, s51
	s_nop 0
	global_load_lds_dwordx4 v[214:215], off
	s_waitcnt vmcnt(8)
	s_waitcnt lgkmcnt(0)
	s_barrier
; #define PG8_STAGE(bufoff, gbase, voff) do { _Pragma("unroll") for (int _i = 0; _i < 2; ++_i) \
;         __builtin_amdgcn_global_load_lds((const unsigned*)((const char*)(gbase) + (voff)[_i]), (LAS unsigned*)(lds + (bufoff) + ldsw + _i * 8192), 16, 0, 0); } while (0)
; #define PG8_LDA(dst, b, h) do { _Pragma("unroll") for (int m = 0; m < 4; ++m) _Pragma("unroll") for (int k = 0; k < 2; ++k) dst[m][k] = *(const LAS bf16x8*)(lds + PG8_SA(b, h) + aoff + m * 2048 + k * 1024); } while (0)
; #define PG8_LDB(dst, b, h) do { _Pragma("unroll") for (int n = 0; n < 2; ++n) _Pragma("unroll") for (int k = 0; k < 2; ++k) dst[n][k] = *(const LAS bf16x8*)(lds + PG8_SB(b, h) + boff + n * 2048 + k * 1024); } while (0)
; #define PG8_MMA(ai, bj, At, Bt) do { __builtin_amdgcn_s_setprio(1); _Pragma("unroll") for (int m = 0; m < 4; ++m) _Pragma("unroll") for (int n = 0; n < 2; ++n) _Pragma("unroll") for (int k = 0; k < 2; ++k) \
;         acc[ai][bj][m][n] = __builtin_amdgcn_mfma_f32_16x16x32_bf16(Bt[n][k], At[m][k], acc[ai][bj][m][n], 0, 0, 0); __builtin_amdgcn_s_setprio(0); } while (0)
; #define PG8_WAIT_V(n) asm volatile("s_waitcnt vmcnt(" #n ")" ::: "memory")
; #define PG8_WAIT_L(n) asm volatile("s_waitcnt lgkmcnt(" #n ")" ::: "memory")
; #define PG8_BAR __builtin_amdgcn_s_barrier()
; #define PG8_SCHED __builtin_amdgcn_sched_barrier(0)
; template <class Epi>
; __device__ __forceinline__ void gemm_phase(LAS unsigned char* lds, const Gemm g, const TileOrder& S, const Epi& E) {
;     ...
;             PG8_WAIT_V(8); PG8_WAIT_L(0); PG8_BAR; PG8_MMA(1, 0, At, B0); PG8_MMA(1, 1, At, B1); PG8_BAR; PG8_SCHED;
;             PG8_LDB(B0, 1, 0); PG8_LDB(B1, 1, 1); PG8_SCHED; PG8_LDA(At, 1, 0); PG8_STAGE(PG8_SA(0, 1), a2 + hstepA, voffA);
;             PG8_WAIT_V(8); PG8_WAIT_L(0); PG8_BAR; PG8_MMA(0, 0, At, B0); PG8_MMA(0, 1, At, B1); PG8_BAR; PG8_SCHED;
	s_setprio 1
	s_waitcnt lgkmcnt(0)
	v_mfma_f32_16x16x32_bf16 v[62:65], v[130:133], v[172:175], v[62:65]
	v_mfma_f32_16x16x32_bf16 v[54:57], v[138:141], v[172:175], v[54:57]
	v_mfma_f32_16x16x32_bf16 v[46:49], v[130:133], v[186:189], v[46:49]
	v_mfma_f32_16x16x32_bf16 v[38:41], v[138:141], v[186:189], v[38:41]
	v_mfma_f32_16x16x32_bf16 v[30:33], v[130:133], v[194:197], v[30:33]
	v_mfma_f32_16x16x32_bf16 v[22:25], v[138:141], v[194:197], v[22:25]
	v_mfma_f32_16x16x32_bf16 v[14:17], v[130:133], v[202:205], v[14:17]
	v_mfma_f32_16x16x32_bf16 v[6:9], v[138:141], v[202:205], v[6:9]
	v_mfma_f32_16x16x32_bf16 v[62:65], v[134:137], v[176:179], v[62:65]
	v_mfma_f32_16x16x32_bf16 v[54:57], v[142:145], v[176:179], v[54:57]
	v_mfma_f32_16x16x32_bf16 v[46:49], v[134:137], v[190:193], v[46:49]
	v_mfma_f32_16x16x32_bf16 v[38:41], v[142:145], v[190:193], v[38:41]
	v_mfma_f32_16x16x32_bf16 v[30:33], v[134:137], v[198:201], v[30:33]
	v_mfma_f32_16x16x32_bf16 v[22:25], v[142:145], v[198:201], v[22:25]
	v_mfma_f32_16x16x32_bf16 v[14:17], v[134:137], v[206:209], v[14:17]
	v_mfma_f32_16x16x32_bf16 v[6:9], v[142:145], v[206:209], v[6:9]
	s_setprio 0
	s_setprio 1
	v_mfma_f32_16x16x32_bf16 v[58:61], v[146:149], v[172:175], v[58:61]
	v_mfma_f32_16x16x32_bf16 v[50:53], v[164:167], v[172:175], v[50:53]
	v_mfma_f32_16x16x32_bf16 v[42:45], v[146:149], v[186:189], v[42:45]
	v_mfma_f32_16x16x32_bf16 v[34:37], v[164:167], v[186:189], v[34:37]
	v_mfma_f32_16x16x32_bf16 v[26:29], v[146:149], v[194:197], v[26:29]
	v_mfma_f32_16x16x32_bf16 v[18:21], v[164:167], v[194:197], v[18:21]
	v_mfma_f32_16x16x32_bf16 v[10:13], v[146:149], v[202:205], v[10:13]
	v_mfma_f32_16x16x32_bf16 v[2:5], v[164:167], v[202:205], v[2:5]
	v_mfma_f32_16x16x32_bf16 v[58:61], v[150:153], v[176:179], v[58:61]
	v_mfma_f32_16x16x32_bf16 v[50:53], v[168:171], v[176:179], v[50:53]
	v_mfma_f32_16x16x32_bf16 v[42:45], v[150:153], v[190:193], v[42:45]
	v_mfma_f32_16x16x32_bf16 v[34:37], v[168:171], v[190:193], v[34:37]
	v_mfma_f32_16x16x32_bf16 v[26:29], v[150:153], v[198:201], v[26:29]
	s_setprio 2
	s_barrier
	v_mfma_f32_16x16x32_bf16 v[18:21], v[168:171], v[198:201], v[18:21]
	s_mov_b32 s6, 0x18000
	s_mov_b32 s12, 0x1c000
	v_add_u32_e32 v142, s6, v184
	ds_read_b128 v[130:133], v142
	v_mfma_f32_16x16x32_bf16 v[10:13], v[150:153], v[206:209], v[10:13]
	ds_read_b128 v[134:137], v142 offset:1024
	ds_read_b128 v[138:141], v142 offset:2048
	v_mfma_f32_16x16x32_bf16 v[2:5], v[168:171], v[206:209], v[2:5]
	s_setprio 0
	v_add_u32_e32 v168, s12, v184
	ds_read_b128 v[142:145], v142 offset:3072
	ds_read_b128 v[146:149], v168
	ds_read_b128 v[150:153], v168 offset:1024
	ds_read_b128 v[164:167], v168 offset:2048
	ds_read_b128 v[168:171], v168 offset:3072
	s_add_u32 s14, s28, 0x80000
	s_addc_u32 s15, s29, 0
	s_mov_b32 m0, s52
	ds_read_b128 v[172:175], v185 offset:32768
	ds_read_b128 v[176:179], v185 offset:33792
	ds_read_b128 v[186:189], v185 offset:34816
	ds_read_b128 v[190:193], v185 offset:35840
	ds_read_b128 v[194:197], v185 offset:36864
	ds_read_b128 v[198:201], v185 offset:37888
	ds_read_b128 v[202:205], v185 offset:38912
	ds_read_b128 v[206:209], v185 offset:39936
	global_load_lds_dwordx4 v158, s[14:15]
	s_mov_b32 m0, s53
	s_nop 0
	global_load_lds_dwordx4 v156, s[14:15]
	s_waitcnt vmcnt(8)
	s_waitcnt lgkmcnt(0)
	s_barrier
	s_setprio 1
	s_waitcnt lgkmcnt(0)
	v_mfma_f32_16x16x32_bf16 v[122:125], v[130:133], v[172:175], v[122:125]
	v_mfma_f32_16x16x32_bf16 v[118:121], v[138:141], v[172:175], v[118:121]
	v_mfma_f32_16x16x32_bf16 v[110:113], v[130:133], v[186:189], v[110:113]
	v_mfma_f32_16x16x32_bf16 v[102:105], v[138:141], v[186:189], v[102:105]
	v_mfma_f32_16x16x32_bf16 v[94:97], v[130:133], v[194:197], v[94:97]
	v_mfma_f32_16x16x32_bf16 v[86:89], v[138:141], v[194:197], v[86:89]
	v_mfma_f32_16x16x32_bf16 v[78:81], v[130:133], v[202:205], v[78:81]
	v_mfma_f32_16x16x32_bf16 v[70:73], v[138:141], v[202:205], v[70:73]
	v_mfma_f32_16x16x32_bf16 v[122:125], v[134:137], v[176:179], v[122:125]
	v_mfma_f32_16x16x32_bf16 v[118:121], v[142:145], v[176:179], v[118:121]
	v_mfma_f32_16x16x32_bf16 v[110:113], v[134:137], v[190:193], v[110:113]
	v_mfma_f32_16x16x32_bf16 v[102:105], v[142:145], v[190:193], v[102:105]
	v_mfma_f32_16x16x32_bf16 v[94:97], v[134:137], v[198:201], v[94:97]
	v_mfma_f32_16x16x32_bf16 v[86:89], v[142:145], v[198:201], v[86:89]
	v_mfma_f32_16x16x32_bf16 v[78:81], v[134:137], v[206:209], v[78:81]
	v_mfma_f32_16x16x32_bf16 v[70:73], v[142:145], v[206:209], v[70:73]
	s_setprio 0
	s_setprio 1
	v_mfma_f32_16x16x32_bf16 v[114:117], v[146:149], v[172:175], v[114:117]
	v_mfma_f32_16x16x32_bf16 v[126:129], v[164:167], v[172:175], v[126:129]
	v_mfma_f32_16x16x32_bf16 v[106:109], v[146:149], v[186:189], v[106:109]
	v_mfma_f32_16x16x32_bf16 v[98:101], v[164:167], v[186:189], v[98:101]
	v_mfma_f32_16x16x32_bf16 v[90:93], v[146:149], v[194:197], v[90:93]
	v_mfma_f32_16x16x32_bf16 v[82:85], v[164:167], v[194:197], v[82:85]
	v_mfma_f32_16x16x32_bf16 v[74:77], v[146:149], v[202:205], v[74:77]
	v_mfma_f32_16x16x32_bf16 v[66:69], v[164:167], v[202:205], v[66:69]
	v_mfma_f32_16x16x32_bf16 v[114:117], v[150:153], v[176:179], v[114:117]
	v_mfma_f32_16x16x32_bf16 v[126:129], v[168:171], v[176:179], v[126:129]
	v_mfma_f32_16x16x32_bf16 v[106:109], v[150:153], v[190:193], v[106:109]
	v_mfma_f32_16x16x32_bf16 v[98:101], v[168:171], v[190:193], v[98:101]
	v_mfma_f32_16x16x32_bf16 v[90:93], v[150:153], v[198:201], v[90:93]
	s_setprio 2
	s_barrier
; #define PG8_STAGE(bufoff, gbase, voff) do { _Pragma("unroll") for (int _i = 0; _i < 2; ++_i) \
;         __builtin_amdgcn_global_load_lds((const unsigned*)((const char*)(gbase) + (voff)[_i]), (LAS unsigned*)(lds + (bufoff) + ldsw + _i * 8192), 16, 0, 0); } while (0)
; #define PG8_LDA(dst, b, h) do { _Pragma("unroll") for (int m = 0; m < 4; ++m) _Pragma("unroll") for (int k = 0; k < 2; ++k) dst[m][k] = *(const LAS bf16x8*)(lds + PG8_SA(b, h) + aoff + m * 2048 + k * 1024); } while (0)
; #define PG8_MMA(ai, bj, At, Bt) do { __builtin_amdgcn_s_setprio(1); _Pragma("unroll") for (int m = 0; m < 4; ++m) _Pragma("unroll") for (int n = 0; n < 2; ++n) _Pragma("unroll") for (int k = 0; k < 2; ++k) \
;         acc[ai][bj][m][n] = __builtin_amdgcn_mfma_f32_16x16x32_bf16(Bt[n][k], At[m][k], acc[ai][bj][m][n], 0, 0, 0); __builtin_amdgcn_s_setprio(0); } while (0)
; #define PG8_WAIT_V(n) asm volatile("s_waitcnt vmcnt(" #n ")" ::: "memory")
; #define PG8_WAIT_L(n) asm volatile("s_waitcnt lgkmcnt(" #n ")" ::: "memory")
; #define PG8_BAR __builtin_amdgcn_s_barrier()
; #define PG8_SCHED __builtin_amdgcn_sched_barrier(0)
; template <class Epi>
; __device__ __forceinline__ void gemm_phase(LAS unsigned char* lds, const Gemm g, const TileOrder& S, const Epi& E) {
;     ...
;             PG8_WAIT_V(8); PG8_WAIT_L(0); PG8_BAR; PG8_MMA(0, 0, At, B0); PG8_MMA(0, 1, At, B1); PG8_BAR; PG8_SCHED;
;             PG8_LDA(At, 1, 1); PG8_STAGE(PG8_SB(1, 0), b3, voffB); PG8_STAGE(PG8_SB(1, 1), b3 + hstepB, voffB); PG8_STAGE(PG8_SA(1, 0), a3, voffA);
;             PG8_WAIT_V(8); PG8_WAIT_L(0); PG8_BAR; PG8_MMA(1, 0, At, B0); PG8_MMA(1, 1, At, B1); PG8_BAR; PG8_SCHED;
;         }
;         if (wr == 0) PG8_BAR;
	v_mfma_f32_16x16x32_bf16 v[82:85], v[168:171], v[198:201], v[82:85]
	ds_read_b128 v[172:175], v185 offset:49152
	v_mfma_f32_16x16x32_bf16 v[74:77], v[150:153], v[206:209], v[74:77]
	ds_read_b128 v[176:179], v185 offset:50176
	ds_read_b128 v[186:189], v185 offset:51200
	v_mfma_f32_16x16x32_bf16 v[66:69], v[168:171], v[206:209], v[66:69]
	s_setprio 0
	s_add_i32 s6, s6, s31
	v_lshl_add_u64 v[180:181], v[180:181], 0, s[34:35]
	s_mov_b32 m0, s6
	ds_read_b128 v[190:193], v185 offset:52224
	ds_read_b128 v[194:197], v185 offset:53248
	ds_read_b128 v[198:201], v185 offset:54272
	ds_read_b128 v[202:205], v185 offset:55296
	ds_read_b128 v[206:209], v185 offset:56320
	global_load_lds_dwordx4 v[180:181], off
	s_add_i32 m0, s6, 0x2000
	s_add_u32 s2, s2, 0x80080
	v_lshl_add_u64 v[180:181], v[210:211], 0, s[34:35]
	s_addc_u32 s3, s3, 0
	s_add_i32 s6, s12, s31
	global_load_lds_dwordx4 v[180:181], off
	s_mov_b32 m0, s6
	s_nop 0
	global_load_lds_dwordx4 v0, s[2:3]
	v_lshl_add_u64 v[180:181], s[2:3], 0, v[154:155]
	s_add_i32 m0, s6, 0x2000
	s_nop 0
	global_load_lds_dwordx4 v[180:181], off
	v_lshl_add_u64 v[180:181], v[212:213], 0, s[34:35]
	s_mov_b32 m0, s58
	s_nop 0
	global_load_lds_dwordx4 v[180:181], off
	v_lshl_add_u64 v[180:181], v[214:215], 0, s[34:35]
	s_mov_b32 m0, s59
	s_nop 0
	global_load_lds_dwordx4 v[180:181], off
	s_waitcnt vmcnt(8)
	s_waitcnt lgkmcnt(0)
	s_barrier
	s_setprio 1
	s_waitcnt lgkmcnt(0)
	v_mfma_f32_16x16x32_bf16 v[62:65], v[130:133], v[172:175], v[62:65]
	v_mfma_f32_16x16x32_bf16 v[54:57], v[138:141], v[172:175], v[54:57]
	v_mfma_f32_16x16x32_bf16 v[46:49], v[130:133], v[186:189], v[46:49]
	v_mfma_f32_16x16x32_bf16 v[38:41], v[138:141], v[186:189], v[38:41]
	v_mfma_f32_16x16x32_bf16 v[30:33], v[130:133], v[194:197], v[30:33]
	v_mfma_f32_16x16x32_bf16 v[22:25], v[138:141], v[194:197], v[22:25]
	v_mfma_f32_16x16x32_bf16 v[14:17], v[130:133], v[202:205], v[14:17]
	v_mfma_f32_16x16x32_bf16 v[6:9], v[138:141], v[202:205], v[6:9]
	v_mfma_f32_16x16x32_bf16 v[62:65], v[134:137], v[176:179], v[62:65]
	v_mfma_f32_16x16x32_bf16 v[54:57], v[142:145], v[176:179], v[54:57]
	v_mfma_f32_16x16x32_bf16 v[46:49], v[134:137], v[190:193], v[46:49]
	v_mfma_f32_16x16x32_bf16 v[38:41], v[142:145], v[190:193], v[38:41]
	v_mfma_f32_16x16x32_bf16 v[30:33], v[134:137], v[198:201], v[30:33]
	v_mfma_f32_16x16x32_bf16 v[22:25], v[142:145], v[198:201], v[22:25]
	v_mfma_f32_16x16x32_bf16 v[14:17], v[134:137], v[206:209], v[14:17]
	v_mfma_f32_16x16x32_bf16 v[6:9], v[142:145], v[206:209], v[6:9]
	s_setprio 0
	s_setprio 1
	v_mfma_f32_16x16x32_bf16 v[58:61], v[146:149], v[172:175], v[58:61]
	v_mfma_f32_16x16x32_bf16 v[50:53], v[164:167], v[172:175], v[50:53]
	v_mfma_f32_16x16x32_bf16 v[42:45], v[146:149], v[186:189], v[42:45]
	v_mfma_f32_16x16x32_bf16 v[34:37], v[164:167], v[186:189], v[34:37]
	v_mfma_f32_16x16x32_bf16 v[26:29], v[146:149], v[194:197], v[26:29]
	v_mfma_f32_16x16x32_bf16 v[18:21], v[164:167], v[194:197], v[18:21]
	v_mfma_f32_16x16x32_bf16 v[10:13], v[146:149], v[202:205], v[10:13]
	v_mfma_f32_16x16x32_bf16 v[2:5], v[164:167], v[202:205], v[2:5]
	v_mfma_f32_16x16x32_bf16 v[58:61], v[150:153], v[176:179], v[58:61]
	v_mfma_f32_16x16x32_bf16 v[50:53], v[168:171], v[176:179], v[50:53]
	v_mfma_f32_16x16x32_bf16 v[42:45], v[150:153], v[190:193], v[42:45]
	v_mfma_f32_16x16x32_bf16 v[34:37], v[168:171], v[190:193], v[34:37]
	v_mfma_f32_16x16x32_bf16 v[26:29], v[150:153], v[198:201], v[26:29]
	v_mfma_f32_16x16x32_bf16 v[18:21], v[168:171], v[198:201], v[18:21]
	s_setprio 2
	s_barrier
	v_mfma_f32_16x16x32_bf16 v[10:13], v[150:153], v[206:209], v[10:13]
	v_mfma_f32_16x16x32_bf16 v[2:5], v[168:171], v[206:209], v[2:5]
	s_setprio 0
	s_add_i32 s66, s66, 2
	s_add_u32 s4, s4, 0x100
	s_addc_u32 s5, s5, 0
	s_add_u32 s64, s64, 0x100
	s_addc_u32 s65, s65, 0
	s_cmp_gt_u32 s66, 29
	s_cbranch_scc0 .LBB0_668
	s_and_b64 vcc, exec, s[38:39]
	s_cbranch_vccz .LBB0_671
	s_barrier

; #define PG8_STAGE(bufoff, gbase, voff) do { _Pragma("unroll") for (int _i = 0; _i < 2; ++_i) \
;         __builtin_amdgcn_global_load_lds((const unsigned*)((const char*)(gbase) + (voff)[_i]), (LAS unsigned*)(lds + (bufoff) + ldsw + _i * 8192), 16, 0, 0); } while (0)
; #define PG8_LDA(dst, b, h) do { _Pragma("unroll") for (int m = 0; m < 4; ++m) _Pragma("unroll") for (int k = 0; k < 2; ++k) dst[m][k] = *(const LAS bf16x8*)(lds + PG8_SA(b, h) + aoff + m * 2048 + k * 1024); } while (0)
; #define PG8_LDB(dst, b, h) do { _Pragma("unroll") for (int n = 0; n < 2; ++n) _Pragma("unroll") for (int k = 0; k < 2; ++k) dst[n][k] = *(const LAS bf16x8*)(lds + PG8_SB(b, h) + boff + n * 2048 + k * 1024); } while (0)
; #define PG8_MMA(ai, bj, At, Bt) do { __builtin_amdgcn_s_setprio(1); _Pragma("unroll") for (int m = 0; m < 4; ++m) _Pragma("unroll") for (int n = 0; n < 2; ++n) _Pragma("unroll") for (int k = 0; k < 2; ++k) \
;         acc[ai][bj][m][n] = __builtin_amdgcn_mfma_f32_16x16x32_bf16(Bt[n][k], At[m][k], acc[ai][bj][m][n], 0, 0, 0); __builtin_amdgcn_s_setprio(0); } while (0)
; #define PG8_WAIT_V(n) asm volatile("s_waitcnt vmcnt(" #n ")" ::: "memory")
; #define PG8_WAIT_L(n) asm volatile("s_waitcnt lgkmcnt(" #n ")" ::: "memory")
; #define PG8_BAR __builtin_amdgcn_s_barrier()
; #define PG8_SCHED __builtin_amdgcn_sched_barrier(0)
; template <class Epi>
; __device__ __forceinline__ void gemm_phase(LAS unsigned char* lds, const Gemm g, const TileOrder& S, const Epi& E) {
;     ...
;         for (int t = 0; t < nt; t += 2) {
;             const bool last = (t == nt - 2);
;             const char* a1 = cA + (size_t)(t + 1) * kstepA;
;             const char* a2 = last ? nA : cA + (size_t)(t + 2) * kstepA; const char* b2 = last ? nB : cB + (size_t)(t + 2) * kstep;
;             const char* a3 = a2 + kstepA; const char* b3 = b2 + kstep;
;             PG8_LDB(B0, 0, 0); PG8_LDB(B1, 0, 1); PG8_SCHED; PG8_LDA(At, 0, 0); PG8_STAGE(PG8_SA(1, 1), a1 + hstepA, voffA);
;             PG8_WAIT_V(8); PG8_WAIT_L(0); PG8_BAR; PG8_MMA(0, 0, At, B0); PG8_MMA(0, 1, At, B1); PG8_BAR; PG8_SCHED;
;             PG8_LDA(At, 0, 1); PG8_STAGE(PG8_SB(0, 0), b2, voffB); PG8_STAGE(PG8_SB(0, 1), b2 + hstepB, voffB); PG8_STAGE(PG8_SA(0, 0), a2, voffA);
;             PG8_WAIT_V(8); PG8_WAIT_L(0); PG8_BAR; PG8_MMA(1, 0, At, B0); PG8_MMA(1, 1, At, B1); PG8_BAR; PG8_SCHED;
.LBB0_757:
	s_mov_b32 s6, 0x10000
	v_add_u32_e32 v0, s6, v154
	s_mov_b32 s14, 0x14000
	ds_read_b128 v[142:145], v0
	ds_read_b128 v[146:149], v0 offset:1024
	ds_read_b128 v[156:159], v0 offset:2048
	ds_read_b128 v[160:163], v0 offset:3072
	v_add_u32_e32 v0, s14, v154
	ds_read_b128 v[164:167], v0
	ds_read_b128 v[168:171], v0 offset:1024
	ds_read_b128 v[172:175], v0 offset:2048
	ds_read_b128 v[176:179], v0 offset:3072
	ds_read_b128 v[180:183], v155
	ds_read_b128 v[184:187], v155 offset:1024
	ds_read_b128 v[188:191], v155 offset:2048
	ds_read_b128 v[192:195], v155 offset:3072
	ds_read_b128 v[196:199], v155 offset:4096
	ds_read_b128 v[200:203], v155 offset:5120
	ds_read_b128 v[204:207], v155 offset:6144
	ds_read_b128 v[208:211], v155 offset:7168
	s_add_u32 s2, s28, 0xfff80080
	s_addc_u32 s3, s29, -1
	s_cmp_eq_u32 s72, 28
	s_cselect_b32 s31, s47, s3
	s_cselect_b32 s30, s51, s2
	s_cselect_b32 s3, s49, s71
	s_cselect_b32 s2, s69, s70
	s_add_i32 m0, s59, 0xc000
	s_nop 0
	global_load_lds_dwordx4 v138, s[28:29]
	s_add_i32 m0, s59, 0xe000
	s_nop 0
	global_load_lds_dwordx4 v140, s[28:29]
	s_waitcnt vmcnt(8)
	s_waitcnt lgkmcnt(0)
	s_barrier
	s_setprio 1
	s_waitcnt lgkmcnt(0)
	v_mfma_f32_16x16x32_bf16 v[126:129], v[142:145], v[180:183], v[126:129]
	v_mfma_f32_16x16x32_bf16 v[122:125], v[156:159], v[180:183], v[122:125]
	v_mfma_f32_16x16x32_bf16 v[110:113], v[142:145], v[188:191], v[110:113]
	v_mfma_f32_16x16x32_bf16 v[106:109], v[156:159], v[188:191], v[106:109]
	v_mfma_f32_16x16x32_bf16 v[94:97], v[142:145], v[196:199], v[94:97]
	v_mfma_f32_16x16x32_bf16 v[90:93], v[156:159], v[196:199], v[90:93]
	v_mfma_f32_16x16x32_bf16 v[78:81], v[142:145], v[204:207], v[78:81]
	v_mfma_f32_16x16x32_bf16 v[74:77], v[156:159], v[204:207], v[74:77]
	v_mfma_f32_16x16x32_bf16 v[126:129], v[146:149], v[184:187], v[126:129]
	v_mfma_f32_16x16x32_bf16 v[122:125], v[160:163], v[184:187], v[122:125]
	v_mfma_f32_16x16x32_bf16 v[110:113], v[146:149], v[192:195], v[110:113]
	v_mfma_f32_16x16x32_bf16 v[106:109], v[160:163], v[192:195], v[106:109]
	v_mfma_f32_16x16x32_bf16 v[94:97], v[146:149], v[200:203], v[94:97]
	v_mfma_f32_16x16x32_bf16 v[90:93], v[160:163], v[200:203], v[90:93]
	v_mfma_f32_16x16x32_bf16 v[78:81], v[146:149], v[208:211], v[78:81]
	v_mfma_f32_16x16x32_bf16 v[74:77], v[160:163], v[208:211], v[74:77]
	s_setprio 0
	s_setprio 1
	v_mfma_f32_16x16x32_bf16 v[118:121], v[164:167], v[180:183], v[118:121]
	v_mfma_f32_16x16x32_bf16 v[114:117], v[172:175], v[180:183], v[114:117]
	v_mfma_f32_16x16x32_bf16 v[102:105], v[164:167], v[188:191], v[102:105]
	v_mfma_f32_16x16x32_bf16 v[98:101], v[172:175], v[188:191], v[98:101]
	v_mfma_f32_16x16x32_bf16 v[86:89], v[164:167], v[196:199], v[86:89]
	v_mfma_f32_16x16x32_bf16 v[82:85], v[172:175], v[196:199], v[82:85]
	v_mfma_f32_16x16x32_bf16 v[70:73], v[164:167], v[204:207], v[70:73]
	v_mfma_f32_16x16x32_bf16 v[66:69], v[172:175], v[204:207], v[66:69]
	v_mfma_f32_16x16x32_bf16 v[118:121], v[168:171], v[184:187], v[118:121]
	v_mfma_f32_16x16x32_bf16 v[114:117], v[176:179], v[184:187], v[114:117]
	v_mfma_f32_16x16x32_bf16 v[102:105], v[168:171], v[192:195], v[102:105]
	v_mfma_f32_16x16x32_bf16 v[98:101], v[176:179], v[192:195], v[98:101]
	v_mfma_f32_16x16x32_bf16 v[86:89], v[168:171], v[200:203], v[86:89]
	s_setprio 2
	s_barrier
	v_mfma_f32_16x16x32_bf16 v[82:85], v[176:179], v[200:203], v[82:85]
	ds_read_b128 v[180:183], v155 offset:16384
	v_mfma_f32_16x16x32_bf16 v[70:73], v[168:171], v[208:211], v[70:73]
	ds_read_b128 v[184:187], v155 offset:17408
	ds_read_b128 v[188:191], v155 offset:18432
	v_mfma_f32_16x16x32_bf16 v[66:69], v[176:179], v[208:211], v[66:69]
	s_setprio 0
	s_add_i32 s6, s6, s58
	v_lshl_add_u64 v[150:151], s[2:3], 0, v[134:135]
	s_mov_b32 m0, s6
	ds_read_b128 v[192:195], v155 offset:19456
	ds_read_b128 v[196:199], v155 offset:20480
	ds_read_b128 v[200:203], v155 offset:21504
	ds_read_b128 v[204:207], v155 offset:22528
	ds_read_b128 v[208:211], v155 offset:23552
	global_load_lds_dwordx4 v[150:151], off
	s_add_i32 m0, s6, 0x2000
	s_add_u32 s12, s2, 0x80000
	v_lshl_add_u64 v[212:213], s[2:3], 0, v[130:131]
	s_addc_u32 s13, s3, 0
	s_add_i32 s6, s14, s58
	global_load_lds_dwordx4 v[212:213], off
	s_mov_b32 m0, s6
	v_lshl_add_u64 v[216:217], s[30:31], 0, v[132:133]
	global_load_lds_dwordx4 v134, s[12:13]
	s_add_i32 m0, s6, 0x2000
	s_nop 0
	global_load_lds_dwordx4 v130, s[12:13]
	v_lshl_add_u64 v[214:215], s[30:31], 0, v[136:137]
	s_mov_b32 m0, s59
	s_nop 0
	global_load_lds_dwordx4 v[214:215], off
	s_mov_b32 m0, s60
	s_nop 0
	global_load_lds_dwordx4 v[216:217], off
	s_waitcnt vmcnt(8)
	s_waitcnt lgkmcnt(0)
	s_barrier
; #define PG8_STAGE(bufoff, gbase, voff) do { _Pragma("unroll") for (int _i = 0; _i < 2; ++_i) \
;         __builtin_amdgcn_global_load_lds((const unsigned*)((const char*)(gbase) + (voff)[_i]), (LAS unsigned*)(lds + (bufoff) + ldsw + _i * 8192), 16, 0, 0); } while (0)
; #define PG8_LDA(dst, b, h) do { _Pragma("unroll") for (int m = 0; m < 4; ++m) _Pragma("unroll") for (int k = 0; k < 2; ++k) dst[m][k] = *(const LAS bf16x8*)(lds + PG8_SA(b, h) + aoff + m * 2048 + k * 1024); } while (0)
; #define PG8_LDB(dst, b, h) do { _Pragma("unroll") for (int n = 0; n < 2; ++n) _Pragma("unroll") for (int k = 0; k < 2; ++k) dst[n][k] = *(const LAS bf16x8*)(lds + PG8_SB(b, h) + boff + n * 2048 + k * 1024); } while (0)
; #define PG8_MMA(ai, bj, At, Bt) do { __builtin_amdgcn_s_setprio(1); _Pragma("unroll") for (int m = 0; m < 4; ++m) _Pragma("unroll") for (int n = 0; n < 2; ++n) _Pragma("unroll") for (int k = 0; k < 2; ++k) \
;         acc[ai][bj][m][n] = __builtin_amdgcn_mfma_f32_16x16x32_bf16(Bt[n][k], At[m][k], acc[ai][bj][m][n], 0, 0, 0); __builtin_amdgcn_s_setprio(0); } while (0)
; #define PG8_WAIT_V(n) asm volatile("s_waitcnt vmcnt(" #n ")" ::: "memory")
; #define PG8_WAIT_L(n) asm volatile("s_waitcnt lgkmcnt(" #n ")" ::: "memory")
; #define PG8_BAR __builtin_amdgcn_s_barrier()
; #define PG8_SCHED __builtin_amdgcn_sched_barrier(0)
; template <class Epi>
; __device__ __forceinline__ void gemm_phase(LAS unsigned char* lds, const Gemm g, const TileOrder& S, const Epi& E) {
;     ...
;             PG8_WAIT_V(8); PG8_WAIT_L(0); PG8_BAR; PG8_MMA(1, 0, At, B0); PG8_MMA(1, 1, At, B1); PG8_BAR; PG8_SCHED;
;             PG8_LDB(B0, 1, 0); PG8_LDB(B1, 1, 1); PG8_SCHED; PG8_LDA(At, 1, 0); PG8_STAGE(PG8_SA(0, 1), a2 + hstepA, voffA);
;             PG8_WAIT_V(8); PG8_WAIT_L(0); PG8_BAR; PG8_MMA(0, 0, At, B0); PG8_MMA(0, 1, At, B1); PG8_BAR; PG8_SCHED;
;             PG8_LDA(At, 1, 1); PG8_STAGE(PG8_SB(1, 0), b3, voffB); PG8_STAGE(PG8_SB(1, 1), b3 + hstepB, voffB); PG8_STAGE(PG8_SA(1, 0), a3, voffA);
;             PG8_WAIT_V(8); PG8_WAIT_L(0); PG8_BAR; PG8_MMA(1, 0, At, B0); PG8_MMA(1, 1, At, B1); PG8_BAR; PG8_SCHED;
	s_setprio 1
	s_waitcnt lgkmcnt(0)
	v_mfma_f32_16x16x32_bf16 v[62:65], v[142:145], v[180:183], v[62:65]
	v_mfma_f32_16x16x32_bf16 v[58:61], v[156:159], v[180:183], v[58:61]
	v_mfma_f32_16x16x32_bf16 v[46:49], v[142:145], v[188:191], v[46:49]
	v_mfma_f32_16x16x32_bf16 v[42:45], v[156:159], v[188:191], v[42:45]
	v_mfma_f32_16x16x32_bf16 v[30:33], v[142:145], v[196:199], v[30:33]
	v_mfma_f32_16x16x32_bf16 v[26:29], v[156:159], v[196:199], v[26:29]
	v_mfma_f32_16x16x32_bf16 v[14:17], v[142:145], v[204:207], v[14:17]
	v_mfma_f32_16x16x32_bf16 v[10:13], v[156:159], v[204:207], v[10:13]
	v_mfma_f32_16x16x32_bf16 v[62:65], v[146:149], v[184:187], v[62:65]
	v_mfma_f32_16x16x32_bf16 v[58:61], v[160:163], v[184:187], v[58:61]
	v_mfma_f32_16x16x32_bf16 v[46:49], v[146:149], v[192:195], v[46:49]
	v_mfma_f32_16x16x32_bf16 v[42:45], v[160:163], v[192:195], v[42:45]
	v_mfma_f32_16x16x32_bf16 v[30:33], v[146:149], v[200:203], v[30:33]
	v_mfma_f32_16x16x32_bf16 v[26:29], v[160:163], v[200:203], v[26:29]
	v_mfma_f32_16x16x32_bf16 v[14:17], v[146:149], v[208:211], v[14:17]
	v_mfma_f32_16x16x32_bf16 v[10:13], v[160:163], v[208:211], v[10:13]
	s_setprio 0
	s_setprio 1
	v_mfma_f32_16x16x32_bf16 v[54:57], v[164:167], v[180:183], v[54:57]
	v_mfma_f32_16x16x32_bf16 v[50:53], v[172:175], v[180:183], v[50:53]
	v_mfma_f32_16x16x32_bf16 v[38:41], v[164:167], v[188:191], v[38:41]
	v_mfma_f32_16x16x32_bf16 v[34:37], v[172:175], v[188:191], v[34:37]
	v_mfma_f32_16x16x32_bf16 v[22:25], v[164:167], v[196:199], v[22:25]
	v_mfma_f32_16x16x32_bf16 v[18:21], v[172:175], v[196:199], v[18:21]
	v_mfma_f32_16x16x32_bf16 v[6:9], v[164:167], v[204:207], v[6:9]
	v_mfma_f32_16x16x32_bf16 v[2:5], v[172:175], v[204:207], v[2:5]
	v_mfma_f32_16x16x32_bf16 v[54:57], v[168:171], v[184:187], v[54:57]
	v_mfma_f32_16x16x32_bf16 v[50:53], v[176:179], v[184:187], v[50:53]
	v_mfma_f32_16x16x32_bf16 v[38:41], v[168:171], v[192:195], v[38:41]
	v_mfma_f32_16x16x32_bf16 v[34:37], v[176:179], v[192:195], v[34:37]
	v_mfma_f32_16x16x32_bf16 v[22:25], v[168:171], v[200:203], v[22:25]
	s_setprio 2
	s_barrier
	v_mfma_f32_16x16x32_bf16 v[18:21], v[176:179], v[200:203], v[18:21]
	s_mov_b32 s6, 0x18000
	v_add_u32_e32 v0, s6, v154
	s_mov_b32 s14, 0x1c000
	ds_read_b128 v[142:145], v0
	v_mfma_f32_16x16x32_bf16 v[6:9], v[168:171], v[208:211], v[6:9]
	ds_read_b128 v[146:149], v0 offset:1024
	ds_read_b128 v[156:159], v0 offset:2048
	v_mfma_f32_16x16x32_bf16 v[2:5], v[176:179], v[208:211], v[2:5]
	s_setprio 0
	ds_read_b128 v[160:163], v0 offset:3072
	v_add_u32_e32 v0, s14, v154
	ds_read_b128 v[164:167], v0
	ds_read_b128 v[168:171], v0 offset:1024
	ds_read_b128 v[172:175], v0 offset:2048
	ds_read_b128 v[176:179], v0 offset:3072
	s_add_u32 s12, s30, 0x80000
	s_addc_u32 s13, s31, 0
	s_mov_b32 m0, s61
	ds_read_b128 v[180:183], v155 offset:32768
	ds_read_b128 v[184:187], v155 offset:33792
	ds_read_b128 v[188:191], v155 offset:34816
	ds_read_b128 v[192:195], v155 offset:35840
	ds_read_b128 v[196:199], v155 offset:36864
	ds_read_b128 v[200:203], v155 offset:37888
	ds_read_b128 v[204:207], v155 offset:38912
	ds_read_b128 v[208:211], v155 offset:39936
	global_load_lds_dwordx4 v136, s[12:13]
	s_mov_b32 m0, s62
	s_nop 0
	global_load_lds_dwordx4 v132, s[12:13]
	s_waitcnt vmcnt(8)
	s_waitcnt lgkmcnt(0)
	s_barrier
	s_setprio 1
	s_waitcnt lgkmcnt(0)
	v_mfma_f32_16x16x32_bf16 v[126:129], v[142:145], v[180:183], v[126:129]
	v_mfma_f32_16x16x32_bf16 v[122:125], v[156:159], v[180:183], v[122:125]
	v_mfma_f32_16x16x32_bf16 v[110:113], v[142:145], v[188:191], v[110:113]
	v_mfma_f32_16x16x32_bf16 v[106:109], v[156:159], v[188:191], v[106:109]
	v_mfma_f32_16x16x32_bf16 v[94:97], v[142:145], v[196:199], v[94:97]
	v_mfma_f32_16x16x32_bf16 v[90:93], v[156:159], v[196:199], v[90:93]
	v_mfma_f32_16x16x32_bf16 v[78:81], v[142:145], v[204:207], v[78:81]
	v_mfma_f32_16x16x32_bf16 v[74:77], v[156:159], v[204:207], v[74:77]
	v_mfma_f32_16x16x32_bf16 v[126:129], v[146:149], v[184:187], v[126:129]
	v_mfma_f32_16x16x32_bf16 v[122:125], v[160:163], v[184:187], v[122:125]
	v_mfma_f32_16x16x32_bf16 v[110:113], v[146:149], v[192:195], v[110:113]
	v_mfma_f32_16x16x32_bf16 v[106:109], v[160:163], v[192:195], v[106:109]
	v_mfma_f32_16x16x32_bf16 v[94:97], v[146:149], v[200:203], v[94:97]
	v_mfma_f32_16x16x32_bf16 v[90:93], v[160:163], v[200:203], v[90:93]
	v_mfma_f32_16x16x32_bf16 v[78:81], v[146:149], v[208:211], v[78:81]
	v_mfma_f32_16x16x32_bf16 v[74:77], v[160:163], v[208:211], v[74:77]
	s_setprio 0
	s_setprio 1
	v_mfma_f32_16x16x32_bf16 v[118:121], v[164:167], v[180:183], v[118:121]
	v_mfma_f32_16x16x32_bf16 v[114:117], v[172:175], v[180:183], v[114:117]
	v_mfma_f32_16x16x32_bf16 v[102:105], v[164:167], v[188:191], v[102:105]
	v_mfma_f32_16x16x32_bf16 v[98:101], v[172:175], v[188:191], v[98:101]
	v_mfma_f32_16x16x32_bf16 v[86:89], v[164:167], v[196:199], v[86:89]
	v_mfma_f32_16x16x32_bf16 v[82:85], v[172:175], v[196:199], v[82:85]
	v_mfma_f32_16x16x32_bf16 v[70:73], v[164:167], v[204:207], v[70:73]
	v_mfma_f32_16x16x32_bf16 v[66:69], v[172:175], v[204:207], v[66:69]
	v_mfma_f32_16x16x32_bf16 v[118:121], v[168:171], v[184:187], v[118:121]
	v_mfma_f32_16x16x32_bf16 v[114:117], v[176:179], v[184:187], v[114:117]
	v_mfma_f32_16x16x32_bf16 v[102:105], v[168:171], v[192:195], v[102:105]
	v_mfma_f32_16x16x32_bf16 v[98:101], v[176:179], v[192:195], v[98:101]
	v_mfma_f32_16x16x32_bf16 v[86:89], v[168:171], v[200:203], v[86:89]
	s_setprio 2
	s_barrier
; #define PG8_STAGE(bufoff, gbase, voff) do { _Pragma("unroll") for (int _i = 0; _i < 2; ++_i) \
;         __builtin_amdgcn_global_load_lds((const unsigned*)((const char*)(gbase) + (voff)[_i]), (LAS unsigned*)(lds + (bufoff) + ldsw + _i * 8192), 16, 0, 0); } while (0)
; #define PG8_LDA(dst, b, h) do { _Pragma("unroll") for (int m = 0; m < 4; ++m) _Pragma("unroll") for (int k = 0; k < 2; ++k) dst[m][k] = *(const LAS bf16x8*)(lds + PG8_SA(b, h) + aoff + m * 2048 + k * 1024); } while (0)
; #define PG8_LDB(dst, b, h) do { _Pragma("unroll") for (int n = 0; n < 2; ++n) _Pragma("unroll") for (int k = 0; k < 2; ++k) dst[n][k] = *(const LAS bf16x8*)(lds + PG8_SB(b, h) + boff + n * 2048 + k * 1024); } while (0)
; #define PG8_MMA(ai, bj, At, Bt) do { __builtin_amdgcn_s_setprio(1); _Pragma("unroll") for (int m = 0; m < 4; ++m) _Pragma("unroll") for (int n = 0; n < 2; ++n) _Pragma("unroll") for (int k = 0; k < 2; ++k) \
;         acc[ai][bj][m][n] = __builtin_amdgcn_mfma_f32_16x16x32_bf16(Bt[n][k], At[m][k], acc[ai][bj][m][n], 0, 0, 0); __builtin_amdgcn_s_setprio(0); } while (0)
; #define PG8_WAIT_V(n) asm volatile("s_waitcnt vmcnt(" #n ")" ::: "memory")
; #define PG8_WAIT_L(n) asm volatile("s_waitcnt lgkmcnt(" #n ")" ::: "memory")
; #define PG8_BAR __builtin_amdgcn_s_barrier()
; #define PG8_SCHED __builtin_amdgcn_sched_barrier(0)
; template <class Epi>
; __device__ __forceinline__ void gemm_phase(LAS unsigned char* lds, const Gemm g, const TileOrder& S, const Epi& E) {
;     ...
;             PG8_LDB(B0, 1, 0); PG8_LDB(B1, 1, 1); PG8_SCHED; PG8_LDA(At, 1, 0); PG8_STAGE(PG8_SA(0, 1), a2 + hstepA, voffA);
;             PG8_WAIT_V(8); PG8_WAIT_L(0); PG8_BAR; PG8_MMA(0, 0, At, B0); PG8_MMA(0, 1, At, B1); PG8_BAR; PG8_SCHED;
;             PG8_LDA(At, 1, 1); PG8_STAGE(PG8_SB(1, 0), b3, voffB); PG8_STAGE(PG8_SB(1, 1), b3 + hstepB, voffB); PG8_STAGE(PG8_SA(1, 0), a3, voffA);
;             PG8_WAIT_V(8); PG8_WAIT_L(0); PG8_BAR; PG8_MMA(1, 0, At, B0); PG8_MMA(1, 1, At, B1); PG8_BAR; PG8_SCHED;
;         }
;         if (wr == 0) PG8_BAR;
	v_mfma_f32_16x16x32_bf16 v[82:85], v[176:179], v[200:203], v[82:85]
	ds_read_b128 v[180:183], v155 offset:49152
	v_mfma_f32_16x16x32_bf16 v[70:73], v[168:171], v[208:211], v[70:73]
	ds_read_b128 v[184:187], v155 offset:50176
	ds_read_b128 v[188:191], v155 offset:51200
	v_mfma_f32_16x16x32_bf16 v[66:69], v[176:179], v[208:211], v[66:69]
	s_setprio 0
	s_add_i32 s6, s6, s58
	v_lshl_add_u64 v[150:151], v[150:151], 0, s[34:35]
	s_mov_b32 m0, s6
	ds_read_b128 v[192:195], v155 offset:52224
	ds_read_b128 v[196:199], v155 offset:53248
	ds_read_b128 v[200:203], v155 offset:54272
	ds_read_b128 v[204:207], v155 offset:55296
	ds_read_b128 v[208:211], v155 offset:56320
	global_load_lds_dwordx4 v[150:151], off
	s_add_i32 m0, s6, 0x2000
	s_add_u32 s2, s2, 0x80080
	v_lshl_add_u64 v[150:151], v[212:213], 0, s[34:35]
	s_addc_u32 s3, s3, 0
	s_add_i32 s6, s14, s58
	global_load_lds_dwordx4 v[150:151], off
	s_mov_b32 m0, s6
	s_nop 0
	global_load_lds_dwordx4 v134, s[2:3]
	v_lshl_add_u64 v[150:151], s[2:3], 0, v[130:131]
	s_add_i32 m0, s6, 0x2000
	s_nop 0
	global_load_lds_dwordx4 v[150:151], off
	v_lshl_add_u64 v[150:151], v[214:215], 0, s[34:35]
	s_mov_b32 m0, s63
	s_nop 0
	global_load_lds_dwordx4 v[150:151], off
	v_lshl_add_u64 v[150:151], v[216:217], 0, s[34:35]
	s_mov_b32 m0, s64
	s_nop 0
	global_load_lds_dwordx4 v[150:151], off
	s_waitcnt vmcnt(8)
	s_waitcnt lgkmcnt(0)
	s_barrier
	s_setprio 1
	s_waitcnt lgkmcnt(0)
	v_mfma_f32_16x16x32_bf16 v[62:65], v[142:145], v[180:183], v[62:65]
	v_mfma_f32_16x16x32_bf16 v[58:61], v[156:159], v[180:183], v[58:61]
	v_mfma_f32_16x16x32_bf16 v[46:49], v[142:145], v[188:191], v[46:49]
	v_mfma_f32_16x16x32_bf16 v[42:45], v[156:159], v[188:191], v[42:45]
	v_mfma_f32_16x16x32_bf16 v[30:33], v[142:145], v[196:199], v[30:33]
	v_mfma_f32_16x16x32_bf16 v[26:29], v[156:159], v[196:199], v[26:29]
	v_mfma_f32_16x16x32_bf16 v[14:17], v[142:145], v[204:207], v[14:17]
	v_mfma_f32_16x16x32_bf16 v[10:13], v[156:159], v[204:207], v[10:13]
	v_mfma_f32_16x16x32_bf16 v[62:65], v[146:149], v[184:187], v[62:65]
	v_mfma_f32_16x16x32_bf16 v[58:61], v[160:163], v[184:187], v[58:61]
	v_mfma_f32_16x16x32_bf16 v[46:49], v[146:149], v[192:195], v[46:49]
	v_mfma_f32_16x16x32_bf16 v[42:45], v[160:163], v[192:195], v[42:45]
	v_mfma_f32_16x16x32_bf16 v[30:33], v[146:149], v[200:203], v[30:33]
	v_mfma_f32_16x16x32_bf16 v[26:29], v[160:163], v[200:203], v[26:29]
	v_mfma_f32_16x16x32_bf16 v[14:17], v[146:149], v[208:211], v[14:17]
	v_mfma_f32_16x16x32_bf16 v[10:13], v[160:163], v[208:211], v[10:13]
	s_setprio 0
	s_setprio 1
	v_mfma_f32_16x16x32_bf16 v[54:57], v[164:167], v[180:183], v[54:57]
	v_mfma_f32_16x16x32_bf16 v[50:53], v[172:175], v[180:183], v[50:53]
	v_mfma_f32_16x16x32_bf16 v[38:41], v[164:167], v[188:191], v[38:41]
	v_mfma_f32_16x16x32_bf16 v[34:37], v[172:175], v[188:191], v[34:37]
	v_mfma_f32_16x16x32_bf16 v[22:25], v[164:167], v[196:199], v[22:25]
	v_mfma_f32_16x16x32_bf16 v[18:21], v[172:175], v[196:199], v[18:21]
	v_mfma_f32_16x16x32_bf16 v[6:9], v[164:167], v[204:207], v[6:9]
	v_mfma_f32_16x16x32_bf16 v[2:5], v[172:175], v[204:207], v[2:5]
	v_mfma_f32_16x16x32_bf16 v[54:57], v[168:171], v[184:187], v[54:57]
	v_mfma_f32_16x16x32_bf16 v[50:53], v[176:179], v[184:187], v[50:53]
	v_mfma_f32_16x16x32_bf16 v[38:41], v[168:171], v[192:195], v[38:41]
	v_mfma_f32_16x16x32_bf16 v[34:37], v[176:179], v[192:195], v[34:37]
	v_mfma_f32_16x16x32_bf16 v[22:25], v[168:171], v[200:203], v[22:25]
	v_mfma_f32_16x16x32_bf16 v[18:21], v[176:179], v[200:203], v[18:21]
	s_setprio 2
	s_barrier
	v_mfma_f32_16x16x32_bf16 v[6:9], v[168:171], v[208:211], v[6:9]
	v_mfma_f32_16x16x32_bf16 v[2:5], v[176:179], v[208:211], v[2:5]
	s_setprio 0
	s_add_i32 s72, s72, 2
	s_add_u32 s28, s28, 0x100
	s_addc_u32 s29, s29, 0
	s_add_u32 s70, s70, 0x100
	s_addc_u32 s71, s71, 0
	s_cmp_gt_u32 s72, 29
	s_cbranch_scc0 .LBB0_757
	s_and_b64 vcc, exec, s[42:43]
	s_cbranch_vccz .LBB0_760
	s_barrier

; #define PG8_STAGE(bufoff, gbase, voff) do { _Pragma("unroll") for (int _i = 0; _i < 2; ++_i) \
;         __builtin_amdgcn_global_load_lds((const unsigned*)((const char*)(gbase) + (voff)[_i]), (LAS unsigned*)(lds + (bufoff) + ldsw + _i * 8192), 16, 0, 0); } while (0)
; #define PG8_LDA(dst, b, h) do { _Pragma("unroll") for (int m = 0; m < 4; ++m) _Pragma("unroll") for (int k = 0; k < 2; ++k) dst[m][k] = *(const LAS bf16x8*)(lds + PG8_SA(b, h) + aoff + m * 2048 + k * 1024); } while (0)
; #define PG8_LDB(dst, b, h) do { _Pragma("unroll") for (int n = 0; n < 2; ++n) _Pragma("unroll") for (int k = 0; k < 2; ++k) dst[n][k] = *(const LAS bf16x8*)(lds + PG8_SB(b, h) + boff + n * 2048 + k * 1024); } while (0)
; #define PG8_MMA(ai, bj, At, Bt) do { __builtin_amdgcn_s_setprio(1); _Pragma("unroll") for (int m = 0; m < 4; ++m) _Pragma("unroll") for (int n = 0; n < 2; ++n) _Pragma("unroll") for (int k = 0; k < 2; ++k) \
;         acc[ai][bj][m][n] = __builtin_amdgcn_mfma_f32_16x16x32_bf16(Bt[n][k], At[m][k], acc[ai][bj][m][n], 0, 0, 0); __builtin_amdgcn_s_setprio(0); } while (0)
; #define PG8_WAIT_V(n) asm volatile("s_waitcnt vmcnt(" #n ")" ::: "memory")
; #define PG8_WAIT_L(n) asm volatile("s_waitcnt lgkmcnt(" #n ")" ::: "memory")
; #define PG8_BAR __builtin_amdgcn_s_barrier()
; #define PG8_SCHED __builtin_amdgcn_sched_barrier(0)
; template <class Epi>
; __device__ __forceinline__ void gemm_phase(LAS unsigned char* lds, const Gemm g, const TileOrder& S, const Epi& E) {
;     ...
;         for (int t = 0; t < nt; t += 2) {
;             const bool last = (t == nt - 2);
;             const char* a1 = cA + (size_t)(t + 1) * kstepA;
;             const char* a2 = last ? nA : cA + (size_t)(t + 2) * kstepA; const char* b2 = last ? nB : cB + (size_t)(t + 2) * kstep;
;             const char* a3 = a2 + kstepA; const char* b3 = b2 + kstep;
;             PG8_LDB(B0, 0, 0); PG8_LDB(B1, 0, 1); PG8_SCHED; PG8_LDA(At, 0, 0); PG8_STAGE(PG8_SA(1, 1), a1 + hstepA, voffA);
;             PG8_WAIT_V(8); PG8_WAIT_L(0); PG8_BAR; PG8_MMA(0, 0, At, B0); PG8_MMA(0, 1, At, B1); PG8_BAR; PG8_SCHED;
;             PG8_LDA(At, 0, 1); PG8_STAGE(PG8_SB(0, 0), b2, voffB); PG8_STAGE(PG8_SB(0, 1), b2 + hstepB, voffB); PG8_STAGE(PG8_SA(0, 0), a2, voffA);
;             PG8_WAIT_V(8); PG8_WAIT_L(0); PG8_BAR; PG8_MMA(1, 0, At, B0); PG8_MMA(1, 1, At, B1); PG8_BAR; PG8_SCHED;
.LBB0_835:
	s_mov_b32 s6, 0x10000
	s_mov_b32 s14, 0x14000
	v_add_u32_e32 v106, s6, v240
	v_add_u32_e32 v150, s14, v240
	ds_read_b128 v[74:77], v106
	ds_read_b128 v[86:89], v106 offset:1024
	ds_read_b128 v[98:101], v106 offset:2048
	ds_read_b128 v[106:109], v106 offset:3072
	ds_read_b128 v[122:125], v150
	ds_read_b128 v[126:129], v150 offset:1024
	ds_read_b128 v[142:145], v150 offset:2048
	ds_read_b128 v[150:153], v150 offset:3072
	ds_read_b128 v[154:157], v241
	ds_read_b128 v[166:169], v241 offset:1024
	ds_read_b128 v[170:173], v241 offset:2048
	ds_read_b128 v[174:177], v241 offset:3072
	ds_read_b128 v[178:181], v241 offset:4096
	ds_read_b128 v[182:185], v241 offset:5120
	ds_read_b128 v[186:189], v241 offset:6144
	ds_read_b128 v[200:203], v241 offset:7168
	s_add_u32 s2, s28, 0x4000
	s_addc_u32 s3, s29, 0
	s_cmpk_eq_i32 s72, 0x7c
	s_cselect_b32 s38, s43, s2
	s_cselect_b32 s39, s42, s3
	s_cselect_b32 s30, s51, s53
	s_cselect_b32 s31, s45, s71
	s_add_u32 s2, s38, 0x8000
	s_addc_u32 s3, s39, 0
	s_add_i32 m0, s60, 0xc000
	s_nop 0
	global_load_lds_dwordx4 v196, s[28:29]
	s_add_i32 m0, s60, 0xe000
	s_nop 0
	global_load_lds_dwordx4 v198, s[28:29]
	s_waitcnt vmcnt(8)
	s_waitcnt lgkmcnt(0)
	s_barrier
	s_setprio 1
	s_waitcnt lgkmcnt(0)
	v_mfma_f32_16x16x32_bf16 v[162:165], v[74:77], v[154:157], v[162:165]
	v_mfma_f32_16x16x32_bf16 v[158:161], v[98:101], v[154:157], v[158:161]
	v_mfma_f32_16x16x32_bf16 v[134:137], v[74:77], v[170:173], v[134:137]
	v_mfma_f32_16x16x32_bf16 v[130:133], v[98:101], v[170:173], v[130:133]
	v_mfma_f32_16x16x32_bf16 v[110:113], v[74:77], v[178:181], v[110:113]
	v_mfma_f32_16x16x32_bf16 v[102:105], v[98:101], v[178:181], v[102:105]
	v_mfma_f32_16x16x32_bf16 v[82:85], v[74:77], v[186:189], v[82:85]
	v_mfma_f32_16x16x32_bf16 v[78:81], v[98:101], v[186:189], v[78:81]
	v_mfma_f32_16x16x32_bf16 v[162:165], v[86:89], v[166:169], v[162:165]
	v_mfma_f32_16x16x32_bf16 v[158:161], v[106:109], v[166:169], v[158:161]
	v_mfma_f32_16x16x32_bf16 v[134:137], v[86:89], v[174:177], v[134:137]
	v_mfma_f32_16x16x32_bf16 v[130:133], v[106:109], v[174:177], v[130:133]
	v_mfma_f32_16x16x32_bf16 v[110:113], v[86:89], v[182:185], v[110:113]
	v_mfma_f32_16x16x32_bf16 v[102:105], v[106:109], v[182:185], v[102:105]
	v_mfma_f32_16x16x32_bf16 v[82:85], v[86:89], v[200:203], v[82:85]
	v_mfma_f32_16x16x32_bf16 v[78:81], v[106:109], v[200:203], v[78:81]
	s_setprio 0
	s_setprio 1
	v_mfma_f32_16x16x32_bf16 v[146:149], v[122:125], v[154:157], v[146:149]
	v_mfma_f32_16x16x32_bf16 v[138:141], v[142:145], v[154:157], v[138:141]
	v_mfma_f32_16x16x32_bf16 v[118:121], v[122:125], v[170:173], v[118:121]
	v_mfma_f32_16x16x32_bf16 v[114:117], v[142:145], v[170:173], v[114:117]
	v_mfma_f32_16x16x32_bf16 v[94:97], v[122:125], v[178:181], v[94:97]
	v_mfma_f32_16x16x32_bf16 v[90:93], v[142:145], v[178:181], v[90:93]
	v_mfma_f32_16x16x32_bf16 v[70:73], v[122:125], v[186:189], v[70:73]
	v_mfma_f32_16x16x32_bf16 v[66:69], v[142:145], v[186:189], v[66:69]
	v_mfma_f32_16x16x32_bf16 v[146:149], v[126:129], v[166:169], v[146:149]
	v_mfma_f32_16x16x32_bf16 v[138:141], v[150:153], v[166:169], v[138:141]
	v_mfma_f32_16x16x32_bf16 v[118:121], v[126:129], v[174:177], v[118:121]
	v_mfma_f32_16x16x32_bf16 v[114:117], v[150:153], v[174:177], v[114:117]
	v_mfma_f32_16x16x32_bf16 v[94:97], v[126:129], v[182:185], v[94:97]
	s_setprio 2
	s_barrier
	v_mfma_f32_16x16x32_bf16 v[90:93], v[150:153], v[182:185], v[90:93]
	ds_read_b128 v[154:157], v241 offset:16384
	v_mfma_f32_16x16x32_bf16 v[70:73], v[126:129], v[200:203], v[70:73]
	ds_read_b128 v[166:169], v241 offset:17408
	ds_read_b128 v[170:173], v241 offset:18432
	v_mfma_f32_16x16x32_bf16 v[66:69], v[150:153], v[200:203], v[66:69]
	s_setprio 0
	s_add_i32 s6, s6, s59
	v_lshl_add_u64 v[204:205], s[30:31], 0, v[0:1]
	s_mov_b32 m0, s6
	ds_read_b128 v[174:177], v241 offset:19456
	ds_read_b128 v[178:181], v241 offset:20480
	ds_read_b128 v[182:185], v241 offset:21504
	ds_read_b128 v[186:189], v241 offset:22528
	ds_read_b128 v[200:203], v241 offset:23552
	global_load_lds_dwordx4 v[204:205], off
	s_add_i32 m0, s6, 0x2000
	s_add_u32 s12, s30, 0x200000
	v_lshl_add_u64 v[206:207], s[30:31], 0, v[190:191]
	s_addc_u32 s13, s31, 0
	s_add_i32 s6, s14, s59
	global_load_lds_dwordx4 v[206:207], off
	s_mov_b32 m0, s6
	s_nop 0
	global_load_lds_dwordx4 v0, s[12:13]
	s_add_i32 m0, s6, 0x2000
	s_nop 0
	global_load_lds_dwordx4 v190, s[12:13]
	s_mov_b32 m0, s60
	s_nop 0
	global_load_lds_dwordx4 v194, s[38:39]
	s_mov_b32 m0, s61
	s_nop 0
	global_load_lds_dwordx4 v192, s[38:39]
	s_waitcnt vmcnt(8)
	s_waitcnt lgkmcnt(0)
	s_barrier
	s_setprio 1
	s_waitcnt lgkmcnt(0)
	v_mfma_f32_16x16x32_bf16 v[62:65], v[74:77], v[154:157], v[62:65]
	v_mfma_f32_16x16x32_bf16 v[58:61], v[98:101], v[154:157], v[58:61]
	v_mfma_f32_16x16x32_bf16 v[46:49], v[74:77], v[170:173], v[46:49]
	v_mfma_f32_16x16x32_bf16 v[42:45], v[98:101], v[170:173], v[42:45]
	v_mfma_f32_16x16x32_bf16 v[30:33], v[74:77], v[178:181], v[30:33]
	v_mfma_f32_16x16x32_bf16 v[26:29], v[98:101], v[178:181], v[26:29]
	v_mfma_f32_16x16x32_bf16 v[14:17], v[74:77], v[186:189], v[14:17]
	v_mfma_f32_16x16x32_bf16 v[10:13], v[98:101], v[186:189], v[10:13]
	v_mfma_f32_16x16x32_bf16 v[62:65], v[86:89], v[166:169], v[62:65]
	v_mfma_f32_16x16x32_bf16 v[58:61], v[106:109], v[166:169], v[58:61]
	v_mfma_f32_16x16x32_bf16 v[46:49], v[86:89], v[174:177], v[46:49]
	v_mfma_f32_16x16x32_bf16 v[42:45], v[106:109], v[174:177], v[42:45]
	v_mfma_f32_16x16x32_bf16 v[30:33], v[86:89], v[182:185], v[30:33]
	v_mfma_f32_16x16x32_bf16 v[26:29], v[106:109], v[182:185], v[26:29]
	v_mfma_f32_16x16x32_bf16 v[14:17], v[86:89], v[200:203], v[14:17]
	v_mfma_f32_16x16x32_bf16 v[10:13], v[106:109], v[200:203], v[10:13]
	s_setprio 0
	s_setprio 1
	v_mfma_f32_16x16x32_bf16 v[54:57], v[122:125], v[154:157], v[54:57]
	v_mfma_f32_16x16x32_bf16 v[50:53], v[142:145], v[154:157], v[50:53]
	v_mfma_f32_16x16x32_bf16 v[38:41], v[122:125], v[170:173], v[38:41]
	v_mfma_f32_16x16x32_bf16 v[34:37], v[142:145], v[170:173], v[34:37]
	v_mfma_f32_16x16x32_bf16 v[22:25], v[122:125], v[178:181], v[22:25]
	v_mfma_f32_16x16x32_bf16 v[18:21], v[142:145], v[178:181], v[18:21]
	v_mfma_f32_16x16x32_bf16 v[6:9], v[122:125], v[186:189], v[6:9]
	v_mfma_f32_16x16x32_bf16 v[2:5], v[142:145], v[186:189], v[2:5]
	v_mfma_f32_16x16x32_bf16 v[54:57], v[126:129], v[166:169], v[54:57]
	v_mfma_f32_16x16x32_bf16 v[50:53], v[150:153], v[166:169], v[50:53]
	v_mfma_f32_16x16x32_bf16 v[38:41], v[126:129], v[174:177], v[38:41]
	v_mfma_f32_16x16x32_bf16 v[34:37], v[150:153], v[174:177], v[34:37]
	v_mfma_f32_16x16x32_bf16 v[22:25], v[126:129], v[182:185], v[22:25]
	s_setprio 2
	s_barrier
; #define PG8_STAGE(bufoff, gbase, voff) do { _Pragma("unroll") for (int _i = 0; _i < 2; ++_i) \
;         __builtin_amdgcn_global_load_lds((const unsigned*)((const char*)(gbase) + (voff)[_i]), (LAS unsigned*)(lds + (bufoff) + ldsw + _i * 8192), 16, 0, 0); } while (0)
; #define PG8_LDA(dst, b, h) do { _Pragma("unroll") for (int m = 0; m < 4; ++m) _Pragma("unroll") for (int k = 0; k < 2; ++k) dst[m][k] = *(const LAS bf16x8*)(lds + PG8_SA(b, h) + aoff + m * 2048 + k * 1024); } while (0)
; #define PG8_LDB(dst, b, h) do { _Pragma("unroll") for (int n = 0; n < 2; ++n) _Pragma("unroll") for (int k = 0; k < 2; ++k) dst[n][k] = *(const LAS bf16x8*)(lds + PG8_SB(b, h) + boff + n * 2048 + k * 1024); } while (0)
; #define PG8_MMA(ai, bj, At, Bt) do { __builtin_amdgcn_s_setprio(1); _Pragma("unroll") for (int m = 0; m < 4; ++m) _Pragma("unroll") for (int n = 0; n < 2; ++n) _Pragma("unroll") for (int k = 0; k < 2; ++k) \
;         acc[ai][bj][m][n] = __builtin_amdgcn_mfma_f32_16x16x32_bf16(Bt[n][k], At[m][k], acc[ai][bj][m][n], 0, 0, 0); __builtin_amdgcn_s_setprio(0); } while (0)
; #define PG8_WAIT_V(n) asm volatile("s_waitcnt vmcnt(" #n ")" ::: "memory")
; #define PG8_WAIT_L(n) asm volatile("s_waitcnt lgkmcnt(" #n ")" ::: "memory")
; #define PG8_BAR __builtin_amdgcn_s_barrier()
; #define PG8_SCHED __builtin_amdgcn_sched_barrier(0)
; template <class Epi>
; __device__ __forceinline__ void gemm_phase(LAS unsigned char* lds, const Gemm g, const TileOrder& S, const Epi& E) {
;     ...
;             PG8_WAIT_V(8); PG8_WAIT_L(0); PG8_BAR; PG8_MMA(1, 0, At, B0); PG8_MMA(1, 1, At, B1); PG8_BAR; PG8_SCHED;
;             PG8_LDB(B0, 1, 0); PG8_LDB(B1, 1, 1); PG8_SCHED; PG8_LDA(At, 1, 0); PG8_STAGE(PG8_SA(0, 1), a2 + hstepA, voffA);
;             PG8_WAIT_V(8); PG8_WAIT_L(0); PG8_BAR; PG8_MMA(0, 0, At, B0); PG8_MMA(0, 1, At, B1); PG8_BAR; PG8_SCHED;
;             PG8_LDA(At, 1, 1); PG8_STAGE(PG8_SB(1, 0), b3, voffB); PG8_STAGE(PG8_SB(1, 1), b3 + hstepB, voffB); PG8_STAGE(PG8_SA(1, 0), a3, voffA);
;             PG8_WAIT_V(8); PG8_WAIT_L(0); PG8_BAR; PG8_MMA(1, 0, At, B0); PG8_MMA(1, 1, At, B1); PG8_BAR; PG8_SCHED;
	v_mfma_f32_16x16x32_bf16 v[18:21], v[150:153], v[182:185], v[18:21]
	s_mov_b32 s6, 0x18000
	s_mov_b32 s14, 0x1c000
	v_add_u32_e32 v106, s6, v240
	ds_read_b128 v[74:77], v106
	v_mfma_f32_16x16x32_bf16 v[6:9], v[126:129], v[200:203], v[6:9]
	ds_read_b128 v[86:89], v106 offset:1024
	ds_read_b128 v[98:101], v106 offset:2048
	v_mfma_f32_16x16x32_bf16 v[2:5], v[150:153], v[200:203], v[2:5]
	s_setprio 0
	v_add_u32_e32 v150, s14, v240
	ds_read_b128 v[106:109], v106 offset:3072
	ds_read_b128 v[122:125], v150
	ds_read_b128 v[126:129], v150 offset:1024
	ds_read_b128 v[142:145], v150 offset:2048
	ds_read_b128 v[150:153], v150 offset:3072
	s_add_u32 s12, s38, 0x4000
	s_addc_u32 s13, s39, 0
	s_mov_b32 m0, s62
	ds_read_b128 v[154:157], v241 offset:32768
	ds_read_b128 v[166:169], v241 offset:33792
	ds_read_b128 v[170:173], v241 offset:34816
	ds_read_b128 v[174:177], v241 offset:35840
	ds_read_b128 v[178:181], v241 offset:36864
	ds_read_b128 v[182:185], v241 offset:37888
	ds_read_b128 v[186:189], v241 offset:38912
	ds_read_b128 v[200:203], v241 offset:39936
	global_load_lds_dwordx4 v194, s[12:13]
	s_mov_b32 m0, s63
	s_nop 0
	global_load_lds_dwordx4 v192, s[12:13]
	s_waitcnt vmcnt(8)
	s_waitcnt lgkmcnt(0)
	s_barrier
	s_setprio 1
	s_waitcnt lgkmcnt(0)
	v_mfma_f32_16x16x32_bf16 v[162:165], v[74:77], v[154:157], v[162:165]
	v_mfma_f32_16x16x32_bf16 v[158:161], v[98:101], v[154:157], v[158:161]
	v_mfma_f32_16x16x32_bf16 v[134:137], v[74:77], v[170:173], v[134:137]
	v_mfma_f32_16x16x32_bf16 v[130:133], v[98:101], v[170:173], v[130:133]
	v_mfma_f32_16x16x32_bf16 v[110:113], v[74:77], v[178:181], v[110:113]
	v_mfma_f32_16x16x32_bf16 v[102:105], v[98:101], v[178:181], v[102:105]
	v_mfma_f32_16x16x32_bf16 v[82:85], v[74:77], v[186:189], v[82:85]
	v_mfma_f32_16x16x32_bf16 v[78:81], v[98:101], v[186:189], v[78:81]
	v_mfma_f32_16x16x32_bf16 v[162:165], v[86:89], v[166:169], v[162:165]
	v_mfma_f32_16x16x32_bf16 v[158:161], v[106:109], v[166:169], v[158:161]
	v_mfma_f32_16x16x32_bf16 v[134:137], v[86:89], v[174:177], v[134:137]
	v_mfma_f32_16x16x32_bf16 v[130:133], v[106:109], v[174:177], v[130:133]
	v_mfma_f32_16x16x32_bf16 v[110:113], v[86:89], v[182:185], v[110:113]
	v_mfma_f32_16x16x32_bf16 v[102:105], v[106:109], v[182:185], v[102:105]
	v_mfma_f32_16x16x32_bf16 v[82:85], v[86:89], v[200:203], v[82:85]
	v_mfma_f32_16x16x32_bf16 v[78:81], v[106:109], v[200:203], v[78:81]
	s_setprio 0
	s_setprio 1
	v_mfma_f32_16x16x32_bf16 v[146:149], v[122:125], v[154:157], v[146:149]
	v_mfma_f32_16x16x32_bf16 v[138:141], v[142:145], v[154:157], v[138:141]
	v_mfma_f32_16x16x32_bf16 v[118:121], v[122:125], v[170:173], v[118:121]
	v_mfma_f32_16x16x32_bf16 v[114:117], v[142:145], v[170:173], v[114:117]
	v_mfma_f32_16x16x32_bf16 v[94:97], v[122:125], v[178:181], v[94:97]
	v_mfma_f32_16x16x32_bf16 v[90:93], v[142:145], v[178:181], v[90:93]
	v_mfma_f32_16x16x32_bf16 v[70:73], v[122:125], v[186:189], v[70:73]
	v_mfma_f32_16x16x32_bf16 v[66:69], v[142:145], v[186:189], v[66:69]
	v_mfma_f32_16x16x32_bf16 v[146:149], v[126:129], v[166:169], v[146:149]
	v_mfma_f32_16x16x32_bf16 v[138:141], v[150:153], v[166:169], v[138:141]
	v_mfma_f32_16x16x32_bf16 v[118:121], v[126:129], v[174:177], v[118:121]
	v_mfma_f32_16x16x32_bf16 v[114:117], v[150:153], v[174:177], v[114:117]
	v_mfma_f32_16x16x32_bf16 v[94:97], v[126:129], v[182:185], v[94:97]
	s_setprio 2
	s_barrier
; #define PG8_STAGE(bufoff, gbase, voff) do { _Pragma("unroll") for (int _i = 0; _i < 2; ++_i) \
;         __builtin_amdgcn_global_load_lds((const unsigned*)((const char*)(gbase) + (voff)[_i]), (LAS unsigned*)(lds + (bufoff) + ldsw + _i * 8192), 16, 0, 0); } while (0)
; #define PG8_LDA(dst, b, h) do { _Pragma("unroll") for (int m = 0; m < 4; ++m) _Pragma("unroll") for (int k = 0; k < 2; ++k) dst[m][k] = *(const LAS bf16x8*)(lds + PG8_SA(b, h) + aoff + m * 2048 + k * 1024); } while (0)
; #define PG8_LDB(dst, b, h) do { _Pragma("unroll") for (int n = 0; n < 2; ++n) _Pragma("unroll") for (int k = 0; k < 2; ++k) dst[n][k] = *(const LAS bf16x8*)(lds + PG8_SB(b, h) + boff + n * 2048 + k * 1024); } while (0)
; #define PG8_MMA(ai, bj, At, Bt) do { __builtin_amdgcn_s_setprio(1); _Pragma("unroll") for (int m = 0; m < 4; ++m) _Pragma("unroll") for (int n = 0; n < 2; ++n) _Pragma("unroll") for (int k = 0; k < 2; ++k) \
;         acc[ai][bj][m][n] = __builtin_amdgcn_mfma_f32_16x16x32_bf16(Bt[n][k], At[m][k], acc[ai][bj][m][n], 0, 0, 0); __builtin_amdgcn_s_setprio(0); } while (0)
; #define PG8_WAIT_V(n) asm volatile("s_waitcnt vmcnt(" #n ")" ::: "memory")
; #define PG8_WAIT_L(n) asm volatile("s_waitcnt lgkmcnt(" #n ")" ::: "memory")
; #define PG8_BAR __builtin_amdgcn_s_barrier()
; #define PG8_SCHED __builtin_amdgcn_sched_barrier(0)
; template <class Epi>
; __device__ __forceinline__ void gemm_phase(LAS unsigned char* lds, const Gemm g, const TileOrder& S, const Epi& E) {
;     ...
;             PG8_LDB(B0, 1, 0); PG8_LDB(B1, 1, 1); PG8_SCHED; PG8_LDA(At, 1, 0); PG8_STAGE(PG8_SA(0, 1), a2 + hstepA, voffA);
;             PG8_WAIT_V(8); PG8_WAIT_L(0); PG8_BAR; PG8_MMA(0, 0, At, B0); PG8_MMA(0, 1, At, B1); PG8_BAR; PG8_SCHED;
;             PG8_LDA(At, 1, 1); PG8_STAGE(PG8_SB(1, 0), b3, voffB); PG8_STAGE(PG8_SB(1, 1), b3 + hstepB, voffB); PG8_STAGE(PG8_SA(1, 0), a3, voffA);
;             PG8_WAIT_V(8); PG8_WAIT_L(0); PG8_BAR; PG8_MMA(1, 0, At, B0); PG8_MMA(1, 1, At, B1); PG8_BAR; PG8_SCHED;
;         }
;         if (wr == 0) PG8_BAR;
	v_mfma_f32_16x16x32_bf16 v[90:93], v[150:153], v[182:185], v[90:93]
	ds_read_b128 v[154:157], v241 offset:49152
	v_mfma_f32_16x16x32_bf16 v[70:73], v[126:129], v[200:203], v[70:73]
	ds_read_b128 v[166:169], v241 offset:50176
	ds_read_b128 v[170:173], v241 offset:51200
	v_mfma_f32_16x16x32_bf16 v[66:69], v[150:153], v[200:203], v[66:69]
	s_setprio 0
	s_add_i32 s6, s6, s59
	v_lshl_add_u64 v[204:205], v[204:205], 0, s[34:35]
	s_mov_b32 m0, s6
	ds_read_b128 v[174:177], v241 offset:52224
	ds_read_b128 v[178:181], v241 offset:53248
	ds_read_b128 v[182:185], v241 offset:54272
	ds_read_b128 v[186:189], v241 offset:55296
	ds_read_b128 v[200:203], v241 offset:56320
	global_load_lds_dwordx4 v[204:205], off
	s_add_i32 m0, s6, 0x2000
	s_add_u32 s12, s30, 0x200080
	v_lshl_add_u64 v[204:205], v[206:207], 0, s[34:35]
	s_addc_u32 s13, s31, 0
	s_add_i32 s6, s14, s59
	global_load_lds_dwordx4 v[204:205], off
	s_mov_b32 m0, s6
	s_nop 0
	global_load_lds_dwordx4 v0, s[12:13]
	s_add_i32 m0, s6, 0x2000
	s_nop 0
	global_load_lds_dwordx4 v190, s[12:13]
	s_mov_b32 m0, s69
	s_nop 0
	global_load_lds_dwordx4 v194, s[2:3]
	s_mov_b32 m0, s70
	s_nop 0
	global_load_lds_dwordx4 v192, s[2:3]
	s_waitcnt vmcnt(8)
	s_waitcnt lgkmcnt(0)
	s_barrier
	s_setprio 1
	s_waitcnt lgkmcnt(0)
	v_mfma_f32_16x16x32_bf16 v[62:65], v[74:77], v[154:157], v[62:65]
	v_mfma_f32_16x16x32_bf16 v[58:61], v[98:101], v[154:157], v[58:61]
	v_mfma_f32_16x16x32_bf16 v[46:49], v[74:77], v[170:173], v[46:49]
	v_mfma_f32_16x16x32_bf16 v[42:45], v[98:101], v[170:173], v[42:45]
	v_mfma_f32_16x16x32_bf16 v[30:33], v[74:77], v[178:181], v[30:33]
	v_mfma_f32_16x16x32_bf16 v[26:29], v[98:101], v[178:181], v[26:29]
	v_mfma_f32_16x16x32_bf16 v[14:17], v[74:77], v[186:189], v[14:17]
	v_mfma_f32_16x16x32_bf16 v[10:13], v[98:101], v[186:189], v[10:13]
	v_mfma_f32_16x16x32_bf16 v[62:65], v[86:89], v[166:169], v[62:65]
	v_mfma_f32_16x16x32_bf16 v[58:61], v[106:109], v[166:169], v[58:61]
	v_mfma_f32_16x16x32_bf16 v[46:49], v[86:89], v[174:177], v[46:49]
	v_mfma_f32_16x16x32_bf16 v[42:45], v[106:109], v[174:177], v[42:45]
	v_mfma_f32_16x16x32_bf16 v[30:33], v[86:89], v[182:185], v[30:33]
	v_mfma_f32_16x16x32_bf16 v[26:29], v[106:109], v[182:185], v[26:29]
	v_mfma_f32_16x16x32_bf16 v[14:17], v[86:89], v[200:203], v[14:17]
	v_mfma_f32_16x16x32_bf16 v[10:13], v[106:109], v[200:203], v[10:13]
	s_setprio 0
	s_setprio 1
	v_mfma_f32_16x16x32_bf16 v[54:57], v[122:125], v[154:157], v[54:57]
	v_mfma_f32_16x16x32_bf16 v[50:53], v[142:145], v[154:157], v[50:53]
	v_mfma_f32_16x16x32_bf16 v[38:41], v[122:125], v[170:173], v[38:41]
	v_mfma_f32_16x16x32_bf16 v[34:37], v[142:145], v[170:173], v[34:37]
	v_mfma_f32_16x16x32_bf16 v[22:25], v[122:125], v[178:181], v[22:25]
	v_mfma_f32_16x16x32_bf16 v[18:21], v[142:145], v[178:181], v[18:21]
	v_mfma_f32_16x16x32_bf16 v[6:9], v[122:125], v[186:189], v[6:9]
	v_mfma_f32_16x16x32_bf16 v[2:5], v[142:145], v[186:189], v[2:5]
	v_mfma_f32_16x16x32_bf16 v[54:57], v[126:129], v[166:169], v[54:57]
	v_mfma_f32_16x16x32_bf16 v[50:53], v[150:153], v[166:169], v[50:53]
	v_mfma_f32_16x16x32_bf16 v[38:41], v[126:129], v[174:177], v[38:41]
	v_mfma_f32_16x16x32_bf16 v[34:37], v[150:153], v[174:177], v[34:37]
	v_mfma_f32_16x16x32_bf16 v[22:25], v[126:129], v[182:185], v[22:25]
	v_mfma_f32_16x16x32_bf16 v[18:21], v[150:153], v[182:185], v[18:21]
	s_setprio 2
	s_barrier
	v_mfma_f32_16x16x32_bf16 v[6:9], v[126:129], v[200:203], v[6:9]
	v_mfma_f32_16x16x32_bf16 v[2:5], v[150:153], v[200:203], v[2:5]
	s_setprio 0
	s_add_i32 s72, s72, 2
	s_add_u32 s53, s53, 0x100
	s_addc_u32 s71, s71, 0
	s_add_u32 s28, s28, 0x10000
	s_addc_u32 s29, s29, 0
	s_cmpk_gt_u32 s72, 0x7d
	s_cbranch_scc0 .LBB0_835
	s_and_b64 vcc, exec, s[46:47]
	s_cbranch_vccz .LBB0_838
	s_barrier
